# GEMM phases: re-align the two ping-pong wave halves around every tile epilogue (wr=0 extra barrier after K loop, wr=1 extra barrier after epilogue) so both halves' epilogues run concurrently instead o
# speedup vs baseline: 1.0077x; 1.0077x over previous
; template <class Epi>
; __device__ __forceinline__ void gemm_phase(LAS unsigned char* lds, const Gemm g, const StaticOrder& S, const Epi& E, const int wid_s) {
;     ...
;     for (;;) {
;         const bool has_next = S.next(ui + 1, nxt);
;         const char* nA = has_next ? (const char*)g.A + (size_t)nxt.pm * tstepA : cA; const char* nB = has_next ? (const char*)g.Bt + (size_t)nxt.pn * tstepB : cB;
.LBB0_142:
	s_or_b64 exec, exec, s[4:5]
	s_and_b64 vcc, exec, s[10:11]
	s_mov_b32 s66, s36
	s_mov_b32 s16, s38
	s_mov_b64 s[12:13], s[42:43]
	s_mov_b64 s[4:5], s[40:41]
	s_cmpk_gt_u32 s46, 0xff
	s_cbranch_scc0 .Lalign_oddin_b
	s_barrier
.Lalign_oddin_b:
	s_cbranch_vccnz .LBB0_357

; #define PG8_STAGE(bufoff, gbase, voff) do { _Pragma("unroll") for (int _i = 0; _i < 2; ++_i) \
;         __builtin_amdgcn_global_load_lds((const unsigned*)((const char*)(gbase) + (voff)[_i]), (LAS unsigned*)(lds + (bufoff) + ldsw + _i * 8192), 16, 0, 0); } while (0)
; #define PG8_LDA(dst, b, h) do { _Pragma("unroll") for (int m = 0; m < 4; ++m) _Pragma("unroll") for (int k = 0; k < 2; ++k) dst[m][k] = *(const LAS h16x8*)(lds + PG8_SA(b, h) + aoff + m * 2048 + k * 1024); } while (0)
; #define PG8_LDB(dst, b, h) do { _Pragma("unroll") for (int n = 0; n < 2; ++n) _Pragma("unroll") for (int k = 0; k < 2; ++k) dst[n][k] = *(const LAS h16x8*)(lds + PG8_SB(b, h) + boff + n * 2048 + k * 1024); } while (0)
; #define PG8_MMA(ai, bj, At, Bt) do { __builtin_amdgcn_s_setprio(1); _Pragma("unroll") for (int m = 0; m < 4; ++m) _Pragma("unroll") for (int n = 0; n < 2; ++n) _Pragma("unroll") for (int k = 0; k < 2; ++k) \
;         acc[ai][bj][m][n] = __builtin_amdgcn_mfma_f32_16x16x32_f16(Bt[n][k], At[m][k], acc[ai][bj][m][n], 0, 0, 0); __builtin_amdgcn_s_setprio(0); } while (0)
; #define PG8_WAIT_V(n) asm volatile("s_waitcnt vmcnt(" #n ")" ::: "memory")
; #define PG8_WAIT_L(n) asm volatile("s_waitcnt lgkmcnt(" #n ")" ::: "memory")
; #define PG8_BAR __builtin_amdgcn_s_barrier()
; #define PG8_SCHED __builtin_amdgcn_sched_barrier(0)
; template <class Epi>
; __device__ __forceinline__ void gemm_phase(LAS unsigned char* lds, const Gemm g, const StaticOrder& S, const Epi& E, const int wid_s) {
;     ...
;             PG8_LDB(B0, 0, 0); PG8_SCHED; PG8_LDA(At, 0, 0); PG8_STAGE(PG8_SA(1, 1), a1 + hstepA, voffA);
;             PG8_WAIT_L(8); PG8_BAR; PG8_WAIT_L(0); PG8_MMA(0, 0, At, B0); PG8_BAR; PG8_SCHED;
;             PG8_LDB(B1, 0, 1); PG8_STAGE(PG8_SB(0, 0), b2, voffB);
;             PG8_BAR; PG8_WAIT_L(0); PG8_MMA(0, 1, At, B1); PG8_BAR;
;             PG8_LDA(At, 0, 1); PG8_STAGE(PG8_SA(0, 0), a2, voffA);
;             PG8_BAR; PG8_WAIT_L(0); PG8_MMA(1, 0, At, B0); PG8_BAR; PG8_SCHED;
;             PG8_STAGE(PG8_SB(0, 1), b2 + hstepB, voffB);
;             PG8_WAIT_V(6); PG8_BAR; PG8_MMA(1, 1, At, B1); PG8_BAR;
.LBB0_146:
	s_add_u32 s12, s4, 0xfffc0080
	s_addc_u32 s13, s5, -1
	s_add_i32 s24, 0, 0x10000
	v_add_u32_e32 v152, s24, v161
	ds_read_b128 v[140:143], v152
	ds_read_b128 v[144:147], v152 offset:1024
	ds_read_b128 v[148:151], v152 offset:2048
	ds_read_b128 v[182:185], v152 offset:3072
	s_cmp_eq_u32 s23, 12
	s_cselect_b32 s15, s17, s13
	s_cselect_b32 s14, s18, s12
	s_cselect_b32 s13, s19, s22
	s_cselect_b32 s12, s20, s21
	v_lshl_add_u64 v[152:153], s[4:5], 0, v[136:137]
	s_add_i32 m0, s52, 0xc000
	ds_read_b128 v[186:189], v181
	ds_read_b128 v[190:193], v181 offset:1024
	ds_read_b128 v[194:197], v181 offset:2048
	ds_read_b128 v[198:201], v181 offset:3072
	ds_read_b128 v[202:205], v181 offset:4096
	ds_read_b128 v[206:209], v181 offset:5120
	ds_read_b128 v[210:213], v181 offset:6144
	ds_read_b128 v[228:231], v181 offset:7168
	global_load_lds_dwordx4 v[152:153], off
	v_lshl_add_u64 v[152:153], s[4:5], 0, v[138:139]
	s_add_i32 m0, s52, 0xe000
	s_nop 0
	global_load_lds_dwordx4 v[152:153], off
	s_waitcnt lgkmcnt(8)
	s_barrier
	s_waitcnt lgkmcnt(0)
	s_setprio 1
	s_waitcnt lgkmcnt(0)
	v_mfma_f32_16x16x32_f16 v[126:129], v[140:143], v[186:189], v[126:129]
	v_mfma_f32_16x16x32_f16 v[122:125], v[148:151], v[186:189], v[122:125]
	v_mfma_f32_16x16x32_f16 v[110:113], v[140:143], v[194:197], v[110:113]
	v_mfma_f32_16x16x32_f16 v[106:109], v[148:151], v[194:197], v[106:109]
	v_mfma_f32_16x16x32_f16 v[94:97], v[140:143], v[202:205], v[94:97]
	v_mfma_f32_16x16x32_f16 v[90:93], v[148:151], v[202:205], v[90:93]
	v_mfma_f32_16x16x32_f16 v[78:81], v[140:143], v[210:213], v[78:81]
	v_mfma_f32_16x16x32_f16 v[74:77], v[148:151], v[210:213], v[74:77]
	v_mfma_f32_16x16x32_f16 v[126:129], v[144:147], v[190:193], v[126:129]
	v_mfma_f32_16x16x32_f16 v[122:125], v[182:185], v[190:193], v[122:125]
	v_mfma_f32_16x16x32_f16 v[110:113], v[144:147], v[198:201], v[110:113]
	v_mfma_f32_16x16x32_f16 v[106:109], v[182:185], v[198:201], v[106:109]
	v_mfma_f32_16x16x32_f16 v[94:97], v[144:147], v[206:209], v[94:97]
	v_mfma_f32_16x16x32_f16 v[90:93], v[182:185], v[206:209], v[90:93]
	v_mfma_f32_16x16x32_f16 v[78:81], v[144:147], v[228:231], v[78:81]
	v_mfma_f32_16x16x32_f16 v[74:77], v[182:185], v[228:231], v[74:77]
	s_setprio 0
	s_barrier
	s_add_i32 s26, 0, 0x14000
	v_add_u32_e32 v152, s26, v161
	s_add_i32 s24, s24, s51
	ds_read_b128 v[232:235], v152
	ds_read_b128 v[236:239], v152 offset:1024
	ds_read_b128 v[240:243], v152 offset:2048
	ds_read_b128 v[244:247], v152 offset:3072
	v_lshl_add_u64 v[152:153], s[12:13], 0, v[0:1]
	s_mov_b32 m0, s24
	v_lshl_add_u64 v[214:215], s[12:13], 0, v[130:131]
	global_load_lds_dwordx4 v[152:153], off
	s_add_i32 m0, s24, 0x2000
	s_nop 0
	global_load_lds_dwordx4 v[214:215], off
	s_barrier
	s_waitcnt lgkmcnt(0)
	s_setprio 1
	s_waitcnt lgkmcnt(0)
	v_mfma_f32_16x16x32_f16 v[118:121], v[232:235], v[186:189], v[118:121]
	v_mfma_f32_16x16x32_f16 v[114:117], v[240:243], v[186:189], v[114:117]
	v_mfma_f32_16x16x32_f16 v[102:105], v[232:235], v[194:197], v[102:105]
	v_mfma_f32_16x16x32_f16 v[98:101], v[240:243], v[194:197], v[98:101]
	v_mfma_f32_16x16x32_f16 v[86:89], v[232:235], v[202:205], v[86:89]
	v_mfma_f32_16x16x32_f16 v[82:85], v[240:243], v[202:205], v[82:85]
	v_mfma_f32_16x16x32_f16 v[70:73], v[232:235], v[210:213], v[70:73]
	v_mfma_f32_16x16x32_f16 v[66:69], v[240:243], v[210:213], v[66:69]
	v_mfma_f32_16x16x32_f16 v[118:121], v[236:239], v[190:193], v[118:121]
	v_mfma_f32_16x16x32_f16 v[114:117], v[244:247], v[190:193], v[114:117]
	v_mfma_f32_16x16x32_f16 v[102:105], v[236:239], v[198:201], v[102:105]
	v_mfma_f32_16x16x32_f16 v[98:101], v[244:247], v[198:201], v[98:101]
	v_mfma_f32_16x16x32_f16 v[86:89], v[236:239], v[206:209], v[86:89]
	v_mfma_f32_16x16x32_f16 v[82:85], v[244:247], v[206:209], v[82:85]
	v_mfma_f32_16x16x32_f16 v[70:73], v[236:239], v[228:231], v[70:73]
	v_mfma_f32_16x16x32_f16 v[66:69], v[244:247], v[228:231], v[66:69]
	s_setprio 0
	s_mov_b32 m0, s52
	v_lshl_add_u64 v[248:249], s[14:15], 0, v[134:135]
	s_barrier
	ds_read_b128 v[186:189], v181 offset:16384
	ds_read_b128 v[190:193], v181 offset:17408
	ds_read_b128 v[194:197], v181 offset:18432
	ds_read_b128 v[198:201], v181 offset:19456
	ds_read_b128 v[202:205], v181 offset:20480
	ds_read_b128 v[206:209], v181 offset:21504
	ds_read_b128 v[210:213], v181 offset:22528
	ds_read_b128 v[228:231], v181 offset:23552
	global_load_lds_dwordx4 v[248:249], off
	v_lshl_add_u64 v[250:251], s[14:15], 0, v[132:133]
	s_mov_b32 m0, s53
	s_nop 0
	global_load_lds_dwordx4 v[250:251], off
	s_barrier
	s_waitcnt lgkmcnt(0)
	s_setprio 1
	s_waitcnt lgkmcnt(0)
	v_mfma_f32_16x16x32_f16 v[62:65], v[140:143], v[186:189], v[62:65]
	v_mfma_f32_16x16x32_f16 v[58:61], v[148:151], v[186:189], v[58:61]
	v_mfma_f32_16x16x32_f16 v[46:49], v[140:143], v[194:197], v[46:49]
	v_mfma_f32_16x16x32_f16 v[42:45], v[148:151], v[194:197], v[42:45]
	v_mfma_f32_16x16x32_f16 v[30:33], v[140:143], v[202:205], v[30:33]
	v_mfma_f32_16x16x32_f16 v[26:29], v[148:151], v[202:205], v[26:29]
	v_mfma_f32_16x16x32_f16 v[14:17], v[140:143], v[210:213], v[14:17]
	v_mfma_f32_16x16x32_f16 v[10:13], v[148:151], v[210:213], v[10:13]
	v_mfma_f32_16x16x32_f16 v[62:65], v[144:147], v[190:193], v[62:65]
	v_mfma_f32_16x16x32_f16 v[58:61], v[182:185], v[190:193], v[58:61]
	v_mfma_f32_16x16x32_f16 v[46:49], v[144:147], v[198:201], v[46:49]
	v_mfma_f32_16x16x32_f16 v[42:45], v[182:185], v[198:201], v[42:45]
	v_mfma_f32_16x16x32_f16 v[30:33], v[144:147], v[206:209], v[30:33]
	v_mfma_f32_16x16x32_f16 v[26:29], v[182:185], v[206:209], v[26:29]
	v_mfma_f32_16x16x32_f16 v[14:17], v[144:147], v[228:231], v[14:17]
	v_mfma_f32_16x16x32_f16 v[10:13], v[182:185], v[228:231], v[10:13]
	s_setprio 0
	s_barrier
; #define PG8_STAGE(bufoff, gbase, voff) do { _Pragma("unroll") for (int _i = 0; _i < 2; ++_i) \
;         __builtin_amdgcn_global_load_lds((const unsigned*)((const char*)(gbase) + (voff)[_i]), (LAS unsigned*)(lds + (bufoff) + ldsw + _i * 8192), 16, 0, 0); } while (0)
; #define PG8_LDA(dst, b, h) do { _Pragma("unroll") for (int m = 0; m < 4; ++m) _Pragma("unroll") for (int k = 0; k < 2; ++k) dst[m][k] = *(const LAS h16x8*)(lds + PG8_SA(b, h) + aoff + m * 2048 + k * 1024); } while (0)
; #define PG8_LDB(dst, b, h) do { _Pragma("unroll") for (int n = 0; n < 2; ++n) _Pragma("unroll") for (int k = 0; k < 2; ++k) dst[n][k] = *(const LAS h16x8*)(lds + PG8_SB(b, h) + boff + n * 2048 + k * 1024); } while (0)
; #define PG8_MMA(ai, bj, At, Bt) do { __builtin_amdgcn_s_setprio(1); _Pragma("unroll") for (int m = 0; m < 4; ++m) _Pragma("unroll") for (int n = 0; n < 2; ++n) _Pragma("unroll") for (int k = 0; k < 2; ++k) \
;         acc[ai][bj][m][n] = __builtin_amdgcn_mfma_f32_16x16x32_f16(Bt[n][k], At[m][k], acc[ai][bj][m][n], 0, 0, 0); __builtin_amdgcn_s_setprio(0); } while (0)
; #define PG8_WAIT_V(n) asm volatile("s_waitcnt vmcnt(" #n ")" ::: "memory")
; #define PG8_WAIT_L(n) asm volatile("s_waitcnt lgkmcnt(" #n ")" ::: "memory")
; #define PG8_BAR __builtin_amdgcn_s_barrier()
; #define PG8_SCHED __builtin_amdgcn_sched_barrier(0)
; template <class Epi>
; __device__ __forceinline__ void gemm_phase(LAS unsigned char* lds, const Gemm g, const StaticOrder& S, const Epi& E, const int wid_s) {
;     ...
;             PG8_WAIT_V(6); PG8_BAR; PG8_MMA(1, 1, At, B1); PG8_BAR;
;             PG8_LDB(B0, 1, 0); PG8_SCHED; PG8_LDA(At, 1, 0); PG8_STAGE(PG8_SA(0, 1), a2 + hstepA, voffA);
;             PG8_WAIT_L(8); PG8_BAR; PG8_WAIT_L(0); PG8_MMA(0, 0, At, B0); PG8_BAR; PG8_SCHED;
;             PG8_LDB(B1, 1, 1); PG8_STAGE(PG8_SB(1, 0), b3, voffB);
;             PG8_BAR; PG8_WAIT_L(0); PG8_MMA(0, 1, At, B1); PG8_BAR;
;             PG8_LDA(At, 1, 1); PG8_STAGE(PG8_SA(1, 0), a3, voffA);
;             PG8_BAR; PG8_WAIT_L(0); PG8_MMA(1, 0, At, B0); PG8_BAR; PG8_SCHED;
	s_add_u32 s24, s12, 0x40000
	s_addc_u32 s25, s13, 0
	s_add_i32 s26, s26, s51
	v_lshl_add_u64 v[140:141], s[24:25], 0, v[0:1]
	s_mov_b32 m0, s26
	s_nop 0
	global_load_lds_dwordx4 v[140:141], off
	v_lshl_add_u64 v[140:141], s[24:25], 0, v[130:131]
	s_add_i32 m0, s26, 0x2000
	s_nop 0
	global_load_lds_dwordx4 v[140:141], off
	s_waitcnt vmcnt(6)
	s_barrier
	s_setprio 1
	v_mfma_f32_16x16x32_f16 v[54:57], v[232:235], v[186:189], v[54:57]
	v_mfma_f32_16x16x32_f16 v[50:53], v[240:243], v[186:189], v[50:53]
	v_mfma_f32_16x16x32_f16 v[38:41], v[232:235], v[194:197], v[38:41]
	v_mfma_f32_16x16x32_f16 v[34:37], v[240:243], v[194:197], v[34:37]
	v_mfma_f32_16x16x32_f16 v[22:25], v[232:235], v[202:205], v[22:25]
	v_mfma_f32_16x16x32_f16 v[18:21], v[240:243], v[202:205], v[18:21]
	v_mfma_f32_16x16x32_f16 v[6:9], v[232:235], v[210:213], v[6:9]
	v_mfma_f32_16x16x32_f16 v[2:5], v[240:243], v[210:213], v[2:5]
	v_mfma_f32_16x16x32_f16 v[54:57], v[236:239], v[190:193], v[54:57]
	v_mfma_f32_16x16x32_f16 v[50:53], v[244:247], v[190:193], v[50:53]
	v_mfma_f32_16x16x32_f16 v[38:41], v[236:239], v[198:201], v[38:41]
	v_mfma_f32_16x16x32_f16 v[34:37], v[244:247], v[198:201], v[34:37]
	v_mfma_f32_16x16x32_f16 v[22:25], v[236:239], v[206:209], v[22:25]
	v_mfma_f32_16x16x32_f16 v[18:21], v[244:247], v[206:209], v[18:21]
	v_mfma_f32_16x16x32_f16 v[6:9], v[236:239], v[228:231], v[6:9]
	v_mfma_f32_16x16x32_f16 v[2:5], v[244:247], v[228:231], v[2:5]
	s_setprio 0
	s_add_i32 s24, 0, 0x18000
	v_add_u32_e32 v182, s24, v161
	s_barrier
	ds_read_b128 v[140:143], v182
	ds_read_b128 v[144:147], v182 offset:1024
	ds_read_b128 v[148:151], v182 offset:2048
	ds_read_b128 v[182:185], v182 offset:3072
	s_add_u32 s14, s14, 0x40000
	s_addc_u32 s15, s15, 0
	s_mov_b32 m0, s54
	v_lshl_add_u64 v[232:233], s[14:15], 0, v[134:135]
	ds_read_b128 v[186:189], v181 offset:32768
	ds_read_b128 v[190:193], v181 offset:33792
	ds_read_b128 v[194:197], v181 offset:34816
	ds_read_b128 v[198:201], v181 offset:35840
	ds_read_b128 v[202:205], v181 offset:36864
	ds_read_b128 v[206:209], v181 offset:37888
	ds_read_b128 v[210:213], v181 offset:38912
	ds_read_b128 v[228:231], v181 offset:39936
	global_load_lds_dwordx4 v[232:233], off
	v_lshl_add_u64 v[232:233], s[14:15], 0, v[132:133]
	s_mov_b32 m0, s55
	s_nop 0
	global_load_lds_dwordx4 v[232:233], off
	s_waitcnt lgkmcnt(8)
	s_barrier
	s_waitcnt lgkmcnt(0)
	s_setprio 1
	s_waitcnt lgkmcnt(0)
	v_mfma_f32_16x16x32_f16 v[126:129], v[140:143], v[186:189], v[126:129]
	v_mfma_f32_16x16x32_f16 v[122:125], v[148:151], v[186:189], v[122:125]
	v_mfma_f32_16x16x32_f16 v[110:113], v[140:143], v[194:197], v[110:113]
	v_mfma_f32_16x16x32_f16 v[106:109], v[148:151], v[194:197], v[106:109]
	v_mfma_f32_16x16x32_f16 v[94:97], v[140:143], v[202:205], v[94:97]
	v_mfma_f32_16x16x32_f16 v[90:93], v[148:151], v[202:205], v[90:93]
	v_mfma_f32_16x16x32_f16 v[78:81], v[140:143], v[210:213], v[78:81]
	v_mfma_f32_16x16x32_f16 v[74:77], v[148:151], v[210:213], v[74:77]
	v_mfma_f32_16x16x32_f16 v[126:129], v[144:147], v[190:193], v[126:129]
	v_mfma_f32_16x16x32_f16 v[122:125], v[182:185], v[190:193], v[122:125]
	v_mfma_f32_16x16x32_f16 v[110:113], v[144:147], v[198:201], v[110:113]
	v_mfma_f32_16x16x32_f16 v[106:109], v[182:185], v[198:201], v[106:109]
	v_mfma_f32_16x16x32_f16 v[94:97], v[144:147], v[206:209], v[94:97]
	v_mfma_f32_16x16x32_f16 v[90:93], v[182:185], v[206:209], v[90:93]
	v_mfma_f32_16x16x32_f16 v[78:81], v[144:147], v[228:231], v[78:81]
	v_mfma_f32_16x16x32_f16 v[74:77], v[182:185], v[228:231], v[74:77]
	s_setprio 0
	s_barrier
	s_add_i32 s14, 0, 0x1c000
	s_add_i32 s15, s24, s51
	v_add_u32_e32 v227, s14, v161
	v_lshl_add_u64 v[152:153], v[152:153], 0, s[74:75]
	s_mov_b32 m0, s15
	ds_read_b128 v[232:235], v227
	ds_read_b128 v[236:239], v227 offset:1024
	ds_read_b128 v[240:243], v227 offset:2048
	ds_read_b128 v[244:247], v227 offset:3072
	global_load_lds_dwordx4 v[152:153], off
	v_lshl_add_u64 v[152:153], v[214:215], 0, s[74:75]
	s_add_i32 m0, s15, 0x2000
	s_nop 0
	global_load_lds_dwordx4 v[152:153], off
	s_barrier
	s_waitcnt lgkmcnt(0)
	s_setprio 1
	s_waitcnt lgkmcnt(0)
	v_mfma_f32_16x16x32_f16 v[118:121], v[232:235], v[186:189], v[118:121]
	v_mfma_f32_16x16x32_f16 v[114:117], v[240:243], v[186:189], v[114:117]
	v_mfma_f32_16x16x32_f16 v[102:105], v[232:235], v[194:197], v[102:105]
	v_mfma_f32_16x16x32_f16 v[98:101], v[240:243], v[194:197], v[98:101]
	v_mfma_f32_16x16x32_f16 v[86:89], v[232:235], v[202:205], v[86:89]
	v_mfma_f32_16x16x32_f16 v[82:85], v[240:243], v[202:205], v[82:85]
	v_mfma_f32_16x16x32_f16 v[70:73], v[232:235], v[210:213], v[70:73]
	v_mfma_f32_16x16x32_f16 v[66:69], v[240:243], v[210:213], v[66:69]
	v_mfma_f32_16x16x32_f16 v[118:121], v[236:239], v[190:193], v[118:121]
	v_mfma_f32_16x16x32_f16 v[114:117], v[244:247], v[190:193], v[114:117]
	v_mfma_f32_16x16x32_f16 v[102:105], v[236:239], v[198:201], v[102:105]
	v_mfma_f32_16x16x32_f16 v[98:101], v[244:247], v[198:201], v[98:101]
	v_mfma_f32_16x16x32_f16 v[86:89], v[236:239], v[206:209], v[86:89]
	v_mfma_f32_16x16x32_f16 v[82:85], v[244:247], v[206:209], v[82:85]
	v_mfma_f32_16x16x32_f16 v[70:73], v[236:239], v[228:231], v[70:73]
	v_mfma_f32_16x16x32_f16 v[66:69], v[244:247], v[228:231], v[66:69]
	s_setprio 0
	s_mov_b32 m0, s62
	v_lshl_add_u64 v[152:153], v[248:249], 0, s[74:75]
	s_barrier
	ds_read_b128 v[186:189], v181 offset:49152
	ds_read_b128 v[190:193], v181 offset:50176
	ds_read_b128 v[194:197], v181 offset:51200
	ds_read_b128 v[198:201], v181 offset:52224
	ds_read_b128 v[202:205], v181 offset:53248
	ds_read_b128 v[206:209], v181 offset:54272
	ds_read_b128 v[210:213], v181 offset:55296
	ds_read_b128 v[228:231], v181 offset:56320
	global_load_lds_dwordx4 v[152:153], off
	v_lshl_add_u64 v[152:153], v[250:251], 0, s[74:75]
	s_mov_b32 m0, s63
	s_nop 0
	global_load_lds_dwordx4 v[152:153], off
	s_barrier
; #define PG8_STAGE(bufoff, gbase, voff) do { _Pragma("unroll") for (int _i = 0; _i < 2; ++_i) \
;         __builtin_amdgcn_global_load_lds((const unsigned*)((const char*)(gbase) + (voff)[_i]), (LAS unsigned*)(lds + (bufoff) + ldsw + _i * 8192), 16, 0, 0); } while (0)
; #define PG8_MMA(ai, bj, At, Bt) do { __builtin_amdgcn_s_setprio(1); _Pragma("unroll") for (int m = 0; m < 4; ++m) _Pragma("unroll") for (int n = 0; n < 2; ++n) _Pragma("unroll") for (int k = 0; k < 2; ++k) \
;         acc[ai][bj][m][n] = __builtin_amdgcn_mfma_f32_16x16x32_f16(Bt[n][k], At[m][k], acc[ai][bj][m][n], 0, 0, 0); __builtin_amdgcn_s_setprio(0); } while (0)
; #define PG8_WAIT_V(n) asm volatile("s_waitcnt vmcnt(" #n ")" ::: "memory")
; #define PG8_WAIT_L(n) asm volatile("s_waitcnt lgkmcnt(" #n ")" ::: "memory")
; #define PG8_BAR __builtin_amdgcn_s_barrier()
; #define PG8_SCHED __builtin_amdgcn_sched_barrier(0)
; template <class Epi>
; __device__ __forceinline__ void gemm_phase(LAS unsigned char* lds, const Gemm g, const StaticOrder& S, const Epi& E, const int wid_s) {
;     ...
;             PG8_BAR; PG8_WAIT_L(0); PG8_MMA(1, 0, At, B0); PG8_BAR; PG8_SCHED;
;             PG8_STAGE(PG8_SB(1, 1), b3 + hstepB, voffB);
;             PG8_WAIT_V(6); PG8_BAR; PG8_MMA(1, 1, At, B1); PG8_BAR;
;     __device__ __forceinline__ void operator()(const f32x4 (&acc_c)[2][2][4][2], const Unit& u, int wr, int wc, int fr, int fq) const {
;     ...
;         float rsv[2][4];
; #pragma unroll
;         for (int ai = 0; ai < 2; ++ai)
; #pragma unroll
;             for (int m = 0; m < 4; ++m) rsv[ai][m] = rowsq[row0 + ai * HALF + m * 16];
; #pragma unroll
;         for (int ai = 0; ai < 2; ++ai)
; #pragma unroll
;             for (int m = 0; m < 4; ++m) { const float rs = rsqrtf(rsv[ai][m] * (1.0f / 1024.0f) + EPS);
; #pragma unroll
;                 for (int bj = 0; bj < 2; ++bj)
; #pragma unroll
;                     for (int n = 0; n < 2; ++n) acc[ai][bj][m][n] *= rs; }
	s_waitcnt lgkmcnt(0)
	s_setprio 1
	s_waitcnt lgkmcnt(0)
	v_mfma_f32_16x16x32_f16 v[62:65], v[140:143], v[186:189], v[62:65]
	v_mfma_f32_16x16x32_f16 v[58:61], v[148:151], v[186:189], v[58:61]
	v_mfma_f32_16x16x32_f16 v[46:49], v[140:143], v[194:197], v[46:49]
	v_mfma_f32_16x16x32_f16 v[42:45], v[148:151], v[194:197], v[42:45]
	v_mfma_f32_16x16x32_f16 v[30:33], v[140:143], v[202:205], v[30:33]
	v_mfma_f32_16x16x32_f16 v[26:29], v[148:151], v[202:205], v[26:29]
	v_mfma_f32_16x16x32_f16 v[14:17], v[140:143], v[210:213], v[14:17]
	v_mfma_f32_16x16x32_f16 v[10:13], v[148:151], v[210:213], v[10:13]
	v_mfma_f32_16x16x32_f16 v[62:65], v[144:147], v[190:193], v[62:65]
	v_mfma_f32_16x16x32_f16 v[58:61], v[182:185], v[190:193], v[58:61]
	v_mfma_f32_16x16x32_f16 v[46:49], v[144:147], v[198:201], v[46:49]
	v_mfma_f32_16x16x32_f16 v[42:45], v[182:185], v[198:201], v[42:45]
	v_mfma_f32_16x16x32_f16 v[30:33], v[144:147], v[206:209], v[30:33]
	v_mfma_f32_16x16x32_f16 v[26:29], v[182:185], v[206:209], v[26:29]
	v_mfma_f32_16x16x32_f16 v[14:17], v[144:147], v[228:231], v[14:17]
	v_mfma_f32_16x16x32_f16 v[10:13], v[182:185], v[228:231], v[10:13]
	s_setprio 0
	s_barrier
	s_add_u32 s12, s12, 0x40080
	s_addc_u32 s13, s13, 0
	s_add_i32 s14, s14, s51
	v_lshl_add_u64 v[140:141], s[12:13], 0, v[0:1]
	s_mov_b32 m0, s14
	s_nop 0
	global_load_lds_dwordx4 v[140:141], off
	v_lshl_add_u64 v[140:141], s[12:13], 0, v[130:131]
	s_add_i32 m0, s14, 0x2000
	s_nop 0
	global_load_lds_dwordx4 v[140:141], off
	s_waitcnt vmcnt(6)
	s_barrier
	s_setprio 1
	v_mfma_f32_16x16x32_f16 v[54:57], v[232:235], v[186:189], v[54:57]
	v_mfma_f32_16x16x32_f16 v[50:53], v[240:243], v[186:189], v[50:53]
	v_mfma_f32_16x16x32_f16 v[38:41], v[232:235], v[194:197], v[38:41]
	v_mfma_f32_16x16x32_f16 v[34:37], v[240:243], v[194:197], v[34:37]
	v_mfma_f32_16x16x32_f16 v[22:25], v[232:235], v[202:205], v[22:25]
	v_mfma_f32_16x16x32_f16 v[18:21], v[240:243], v[202:205], v[18:21]
	v_mfma_f32_16x16x32_f16 v[6:9], v[232:235], v[210:213], v[6:9]
	v_mfma_f32_16x16x32_f16 v[2:5], v[240:243], v[210:213], v[2:5]
	v_mfma_f32_16x16x32_f16 v[54:57], v[236:239], v[190:193], v[54:57]
	v_mfma_f32_16x16x32_f16 v[50:53], v[244:247], v[190:193], v[50:53]
	v_mfma_f32_16x16x32_f16 v[38:41], v[236:239], v[198:201], v[38:41]
	v_mfma_f32_16x16x32_f16 v[34:37], v[244:247], v[198:201], v[34:37]
	v_mfma_f32_16x16x32_f16 v[22:25], v[236:239], v[206:209], v[22:25]
	v_mfma_f32_16x16x32_f16 v[18:21], v[244:247], v[206:209], v[18:21]
	v_mfma_f32_16x16x32_f16 v[6:9], v[236:239], v[228:231], v[6:9]
	v_mfma_f32_16x16x32_f16 v[2:5], v[244:247], v[228:231], v[2:5]
	s_setprio 0
	s_add_i32 s23, s23, 2
	s_add_u32 s4, s4, 0x100
	s_addc_u32 s5, s5, 0
	s_add_u32 s21, s21, 0x100
	s_addc_u32 s22, s22, 0
	s_cmp_gt_u32 s23, 13
	s_barrier
	s_cbranch_scc0 .LBB0_146
	s_cmpk_gt_u32 s46, 0xff
	s_cbranch_scc1 .Lalign_oddin_a
	s_barrier
.Lalign_oddin_a:
	v_lshl_add_u32 v140, s16, 8, v154
	v_ashrrev_i32_e32 v141, 31, v140
	v_lshl_add_u64 v[144:145], v[140:141], 2, s[30:31]
	global_load_dword v146, v[144:145], off
	global_load_dword v147, v[144:145], off offset:64
	global_load_dword v148, v[144:145], off offset:128
	global_load_dword v149, v[144:145], off offset:192
	global_load_dword v150, v[144:145], off offset:512
	global_load_dword v143, v[144:145], off offset:576
	global_load_dword v142, v[144:145], off offset:640
	global_load_dword v141, v[144:145], off offset:704
	s_and_b32 s4, s66, 0x7ffffffe
	s_cmp_lg_u32 s4, 6
	s_cselect_b64 s[4:5], -1, 0
	s_cmp_lg_u32 s66, 8
	s_cselect_b64 s[12:13], -1, 0
	s_and_b64 s[14:15], s[12:13], s[4:5]
	s_cmp_gt_i32 s66, 3
	s_cselect_b64 s[12:13], -1, 0
	s_cmp_lt_i32 s66, 4
	s_cselect_b64 s[44:45], -1, 0
	s_and_b64 s[14:15], s[12:13], s[14:15]
	s_waitcnt vmcnt(0)
	v_fmamk_f32 v144, v146, 0x3a800000, v216
	v_cmp_gt_f32_e32 vcc, s2, v144
	v_mul_f32_e32 v145, 0x4b800000, v144
	v_fmamk_f32 v143, v143, 0x3a800000, v216
	v_cndmask_b32_e32 v144, v144, v145, vcc
	v_rsq_f32_e32 v144, v144
	v_fmamk_f32 v142, v142, 0x3a800000, v216
	v_fmamk_f32 v141, v141, 0x3a800000, v216
	v_mul_f32_e32 v145, 0x45800000, v144
	v_cndmask_b32_e32 v144, v144, v145, vcc
	v_pk_mul_f32 v[128:129], v[128:129], v[144:145] op_sel_hi:[1,0]
	v_pk_mul_f32 v[126:127], v[126:127], v[144:145] op_sel_hi:[1,0]
	v_pk_mul_f32 v[124:125], v[124:125], v[144:145] op_sel_hi:[1,0]
	v_pk_mul_f32 v[122:123], v[122:123], v[144:145] op_sel_hi:[1,0]
	v_pk_mul_f32 v[120:121], v[120:121], v[144:145] op_sel_hi:[1,0]
	v_pk_mul_f32 v[118:119], v[118:119], v[144:145] op_sel_hi:[1,0]
	v_pk_mul_f32 v[116:117], v[116:117], v[144:145] op_sel_hi:[1,0]
	v_pk_mul_f32 v[114:115], v[114:115], v[144:145] op_sel_hi:[1,0]
	v_fmamk_f32 v144, v147, 0x3a800000, v216
	v_cmp_gt_f32_e32 vcc, s2, v144
	v_mul_f32_e32 v145, 0x4b800000, v144
	s_nop 0
	v_cndmask_b32_e32 v144, v144, v145, vcc
	v_rsq_f32_e32 v144, v144
	s_nop 0
	v_mul_f32_e32 v145, 0x45800000, v144
	v_cndmask_b32_e32 v144, v144, v145, vcc
	v_pk_mul_f32 v[112:113], v[112:113], v[144:145] op_sel_hi:[1,0]
	v_pk_mul_f32 v[110:111], v[110:111], v[144:145] op_sel_hi:[1,0]
	v_pk_mul_f32 v[108:109], v[108:109], v[144:145] op_sel_hi:[1,0]
	v_pk_mul_f32 v[106:107], v[106:107], v[144:145] op_sel_hi:[1,0]
	v_pk_mul_f32 v[104:105], v[104:105], v[144:145] op_sel_hi:[1,0]
	v_pk_mul_f32 v[102:103], v[102:103], v[144:145] op_sel_hi:[1,0]
	v_pk_mul_f32 v[100:101], v[100:101], v[144:145] op_sel_hi:[1,0]
	v_pk_mul_f32 v[98:99], v[98:99], v[144:145] op_sel_hi:[1,0]
	v_fmamk_f32 v144, v148, 0x3a800000, v216
;     __device__ __forceinline__ void operator()(const f32x4 (&acc_c)[2][2][4][2], const Unit& u, int wr, int wc, int fr, int fq) const {
;     ...
;             for (int m = 0; m < 4; ++m) { const float rs = rsqrtf(rsv[ai][m] * (1.0f / 1024.0f) + EPS);
; #pragma unroll
;                 for (int bj = 0; bj < 2; ++bj)
; #pragma unroll
;                     for (int n = 0; n < 2; ++n) acc[ai][bj][m][n] *= rs; }
;         if (kind0 != 0) {
;             const int kidx = pn < 2 ? 0 : (pn < 4 ? 1 : (pn < 8 ? 2 : 3));
;             const int gcol = (kind0 == 1 ? 32 * (wc & 1) : 32 * wc) + 8 * fq;
;             const f32x4 ga = *(const f32x4*)(gtab + kidx * 128 + gcol), gb = *(const f32x4*)(gtab + kidx * 128 + gcol + 4);
;             const float gscale = 1.0f;
; #pragma unroll
;             for (int ai = 0; ai < 2; ++ai)
; #pragma unroll
;                 for (int m = 0; m < 4; ++m)
; #pragma unroll
;                     for (int bj = 0; bj < 2; ++bj) { const f32x4 a = acc[ai][bj][m][0], b = acc[ai][bj][m][1];
;                         float ss = (a[0] * a[0] + a[1] * a[1]) + (a[2] * a[2] + a[3] * a[3]) + (b[0] * b[0] + b[1] * b[1]) + (b[2] * b[2] + b[3] * b[3]);
;                         ss += __shfl_xor(ss, 16); ss += __shfl_xor(ss, 32);
;                         if (fq == 0) xch[((ai * HALF + wr * 64 + m * 16 + fr) * 2 + bj) * 4 + wc] = ss; }
	v_cmp_gt_f32_e32 vcc, s2, v144
	v_mul_f32_e32 v145, 0x4b800000, v144
	s_nop 0
	v_cndmask_b32_e32 v144, v144, v145, vcc
	v_rsq_f32_e32 v144, v144
	s_nop 0
	v_mul_f32_e32 v145, 0x45800000, v144
	v_cndmask_b32_e32 v144, v144, v145, vcc
	v_pk_mul_f32 v[96:97], v[96:97], v[144:145] op_sel_hi:[1,0]
	v_pk_mul_f32 v[94:95], v[94:95], v[144:145] op_sel_hi:[1,0]
	v_pk_mul_f32 v[92:93], v[92:93], v[144:145] op_sel_hi:[1,0]
	v_pk_mul_f32 v[90:91], v[90:91], v[144:145] op_sel_hi:[1,0]
	v_pk_mul_f32 v[88:89], v[88:89], v[144:145] op_sel_hi:[1,0]
	v_pk_mul_f32 v[86:87], v[86:87], v[144:145] op_sel_hi:[1,0]
	v_pk_mul_f32 v[84:85], v[84:85], v[144:145] op_sel_hi:[1,0]
	v_pk_mul_f32 v[82:83], v[82:83], v[144:145] op_sel_hi:[1,0]
	v_fmamk_f32 v144, v149, 0x3a800000, v216
	v_cmp_gt_f32_e32 vcc, s2, v144
	v_mul_f32_e32 v145, 0x4b800000, v144
	s_nop 0
	v_cndmask_b32_e32 v144, v144, v145, vcc
	v_rsq_f32_e32 v144, v144
	s_nop 0
	v_mul_f32_e32 v145, 0x45800000, v144
	v_cndmask_b32_e32 v144, v144, v145, vcc
	v_pk_mul_f32 v[80:81], v[80:81], v[144:145] op_sel_hi:[1,0]
	v_pk_mul_f32 v[78:79], v[78:79], v[144:145] op_sel_hi:[1,0]
	v_pk_mul_f32 v[76:77], v[76:77], v[144:145] op_sel_hi:[1,0]
	v_pk_mul_f32 v[74:75], v[74:75], v[144:145] op_sel_hi:[1,0]
	v_pk_mul_f32 v[72:73], v[72:73], v[144:145] op_sel_hi:[1,0]
	v_pk_mul_f32 v[70:71], v[70:71], v[144:145] op_sel_hi:[1,0]
	v_pk_mul_f32 v[68:69], v[68:69], v[144:145] op_sel_hi:[1,0]
	v_pk_mul_f32 v[66:67], v[66:67], v[144:145] op_sel_hi:[1,0]
	v_fmamk_f32 v144, v150, 0x3a800000, v216
	v_cmp_gt_f32_e32 vcc, s2, v144
	v_mul_f32_e32 v145, 0x4b800000, v144
	s_nop 0
	v_cndmask_b32_e32 v144, v144, v145, vcc
	v_rsq_f32_e32 v144, v144
	s_nop 0
	v_mul_f32_e32 v145, 0x45800000, v144
	v_cndmask_b32_e32 v144, v144, v145, vcc
	v_pk_mul_f32 v[64:65], v[64:65], v[144:145] op_sel_hi:[1,0]
	v_pk_mul_f32 v[62:63], v[62:63], v[144:145] op_sel_hi:[1,0]
	v_pk_mul_f32 v[60:61], v[60:61], v[144:145] op_sel_hi:[1,0]
	v_pk_mul_f32 v[58:59], v[58:59], v[144:145] op_sel_hi:[1,0]
	v_pk_mul_f32 v[56:57], v[56:57], v[144:145] op_sel_hi:[1,0]
	v_pk_mul_f32 v[54:55], v[54:55], v[144:145] op_sel_hi:[1,0]
	v_pk_mul_f32 v[52:53], v[52:53], v[144:145] op_sel_hi:[1,0]
	v_pk_mul_f32 v[50:51], v[50:51], v[144:145] op_sel_hi:[1,0]
	v_cmp_gt_f32_e32 vcc, s2, v143
	v_mul_f32_e32 v144, 0x4b800000, v143
	s_nop 0
	v_cndmask_b32_e32 v143, v143, v144, vcc
	v_rsq_f32_e32 v143, v143
	s_nop 0
	v_mul_f32_e32 v144, 0x45800000, v143
	v_cndmask_b32_e32 v144, v143, v144, vcc
	v_cmp_gt_f32_e32 vcc, s2, v142
	v_mul_f32_e32 v143, 0x4b800000, v142
	v_pk_mul_f32 v[48:49], v[48:49], v[144:145] op_sel_hi:[1,0]
	v_cndmask_b32_e32 v142, v142, v143, vcc
	v_rsq_f32_e32 v142, v142
	v_pk_mul_f32 v[46:47], v[46:47], v[144:145] op_sel_hi:[1,0]
	v_pk_mul_f32 v[44:45], v[44:45], v[144:145] op_sel_hi:[1,0]
	v_pk_mul_f32 v[42:43], v[42:43], v[144:145] op_sel_hi:[1,0]
	v_mul_f32_e32 v143, 0x45800000, v142
	v_cndmask_b32_e32 v142, v142, v143, vcc
	v_pk_mul_f32 v[32:33], v[32:33], v[142:143] op_sel_hi:[1,0]
	v_pk_mul_f32 v[30:31], v[30:31], v[142:143] op_sel_hi:[1,0]
	v_pk_mul_f32 v[28:29], v[28:29], v[142:143] op_sel_hi:[1,0]
	v_pk_mul_f32 v[26:27], v[26:27], v[142:143] op_sel_hi:[1,0]
	v_pk_mul_f32 v[24:25], v[24:25], v[142:143] op_sel_hi:[1,0]
	v_pk_mul_f32 v[22:23], v[22:23], v[142:143] op_sel_hi:[1,0]
	v_pk_mul_f32 v[20:21], v[20:21], v[142:143] op_sel_hi:[1,0]
	v_pk_mul_f32 v[18:19], v[18:19], v[142:143] op_sel_hi:[1,0]
	v_cmp_gt_f32_e32 vcc, s2, v141
	v_mul_f32_e32 v142, 0x4b800000, v141
	v_pk_mul_f32 v[40:41], v[40:41], v[144:145] op_sel_hi:[1,0]
	v_cndmask_b32_e32 v141, v141, v142, vcc
	v_rsq_f32_e32 v141, v141
	v_pk_mul_f32 v[38:39], v[38:39], v[144:145] op_sel_hi:[1,0]
	v_pk_mul_f32 v[36:37], v[36:37], v[144:145] op_sel_hi:[1,0]
	v_pk_mul_f32 v[34:35], v[34:35], v[144:145] op_sel_hi:[1,0]
	v_mul_f32_e32 v142, 0x45800000, v141
	v_cndmask_b32_e32 v146, v141, v142, vcc
	v_pk_mul_f32 v[144:145], v[16:17], v[146:147] op_sel_hi:[1,0]
	v_pk_mul_f32 v[142:143], v[14:15], v[146:147] op_sel_hi:[1,0]
	v_pk_mul_f32 v[152:153], v[12:13], v[146:147] op_sel_hi:[1,0]
	v_pk_mul_f32 v[150:151], v[10:11], v[146:147] op_sel_hi:[1,0]
	v_pk_mul_f32 v[16:17], v[8:9], v[146:147] op_sel_hi:[1,0]
	v_pk_mul_f32 v[14:15], v[6:7], v[146:147] op_sel_hi:[1,0]
	v_pk_mul_f32 v[148:149], v[4:5], v[146:147] op_sel_hi:[1,0]
	v_pk_mul_f32 v[146:147], v[2:3], v[146:147] op_sel_hi:[1,0]
	s_and_b64 vcc, exec, s[14:15]
	s_cbranch_vccnz .LBB0_325
	s_cmp_lt_i32 s66, 2
	s_cselect_b32 s16, 0, 0x80
	s_cmp_lt_i32 s66, 8
	s_movk_i32 s6, 0x180
	s_cselect_b32 s17, 0x100, s6
	s_and_b64 s[14:15], s[12:13], exec
	s_cselect_b32 s14, s58, s64
	v_or_b32_e32 v2, s14, v155
	s_cselect_b32 s14, s17, s16
	s_lshl_b32 s14, s14, 2
	s_add_u32 s14, s56, s14
	s_addc_u32 s15, s57, 0
	v_lshlrev_b32_e32 v6, 2, v2
	global_load_dwordx4 v[2:5], v6, s[14:15] offset:16
	s_nop 0
	global_load_dwordx4 v[6:9], v6, s[14:15]
	v_mul_f32_e32 v10, v127, v127
	v_mul_f32_e32 v11, v129, v129
	v_fmac_f32_e32 v10, v126, v126
	v_fmac_f32_e32 v11, v128, v128
	v_add_f32_e32 v10, v10, v11
	v_mul_f32_e32 v11, v123, v123
	v_fmac_f32_e32 v11, v122, v122
	v_add_f32_e32 v10, v11, v10
	v_mul_f32_e32 v11, v125, v125
	v_fmac_f32_e32 v11, v124, v124
	v_add_f32_e32 v10, v11, v10
	ds_bpermute_b32 v11, v162, v10
	s_waitcnt lgkmcnt(0)
	v_add_f32_e32 v10, v10, v11
	ds_bpermute_b32 v11, v163, v10
	s_and_saveexec_b64 s[14:15], s[8:9]
	s_cbranch_execz .LBB0_150
	s_waitcnt lgkmcnt(0)
	v_add_f32_e32 v10, v10, v11
	ds_write_b32 v165, v10

; template <class Epi>
; __device__ __forceinline__ void gemm_phase(LAS unsigned char* lds, const Gemm g, const StaticOrder& S, const Epi& E, const int wid_s) {
;     ...
;     for (;;) {
;         const bool has_next = S.next(ui + 1, nxt);
;         const char* nA = has_next ? (const char*)g.A + (size_t)nxt.pm * tstepA : cA; const char* nB = has_next ? (const char*)g.Bt + (size_t)nxt.pn * tstepB : cB;
.LBB0_787:
	s_or_b64 exec, exec, s[4:5]
	s_and_b64 vcc, exec, s[10:11]
	s_mov_b32 s44, s16
	s_mov_b32 s45, s18
	s_mov_b64 s[24:25], s[22:23]
	s_mov_b64 s[4:5], s[20:21]
	s_cmpk_gt_u32 s29, 0xff
	s_cbranch_scc0 .Lalign_oddout_b
	s_barrier

; #define PG8_STAGE(bufoff, gbase, voff) do { _Pragma("unroll") for (int _i = 0; _i < 2; ++_i) \
;         __builtin_amdgcn_global_load_lds((const unsigned*)((const char*)(gbase) + (voff)[_i]), (LAS unsigned*)(lds + (bufoff) + ldsw + _i * 8192), 16, 0, 0); } while (0)
; #define PG8_LDA(dst, b, h) do { _Pragma("unroll") for (int m = 0; m < 4; ++m) _Pragma("unroll") for (int k = 0; k < 2; ++k) dst[m][k] = *(const LAS h16x8*)(lds + PG8_SA(b, h) + aoff + m * 2048 + k * 1024); } while (0)
; #define PG8_LDB(dst, b, h) do { _Pragma("unroll") for (int n = 0; n < 2; ++n) _Pragma("unroll") for (int k = 0; k < 2; ++k) dst[n][k] = *(const LAS h16x8*)(lds + PG8_SB(b, h) + boff + n * 2048 + k * 1024); } while (0)
; #define PG8_MMA(ai, bj, At, Bt) do { __builtin_amdgcn_s_setprio(1); _Pragma("unroll") for (int m = 0; m < 4; ++m) _Pragma("unroll") for (int n = 0; n < 2; ++n) _Pragma("unroll") for (int k = 0; k < 2; ++k) \
;         acc[ai][bj][m][n] = __builtin_amdgcn_mfma_f32_16x16x32_f16(Bt[n][k], At[m][k], acc[ai][bj][m][n], 0, 0, 0); __builtin_amdgcn_s_setprio(0); } while (0)
; #define PG8_WAIT_V(n) asm volatile("s_waitcnt vmcnt(" #n ")" ::: "memory")
; #define PG8_WAIT_L(n) asm volatile("s_waitcnt lgkmcnt(" #n ")" ::: "memory")
; #define PG8_BAR __builtin_amdgcn_s_barrier()
; #define PG8_SCHED __builtin_amdgcn_sched_barrier(0)
; template <class Epi>
; __device__ __forceinline__ void gemm_phase(LAS unsigned char* lds, const Gemm g, const StaticOrder& S, const Epi& E, const int wid_s) {
;     ...
;             PG8_LDB(B0, 0, 0); PG8_SCHED; PG8_LDA(At, 0, 0); PG8_STAGE(PG8_SA(1, 1), a1 + hstepA, voffA);
;             PG8_WAIT_L(8); PG8_BAR; PG8_WAIT_L(0); PG8_MMA(0, 0, At, B0); PG8_BAR; PG8_SCHED;
;             PG8_LDB(B1, 0, 1); PG8_STAGE(PG8_SB(0, 0), b2, voffB);
;             PG8_BAR; PG8_WAIT_L(0); PG8_MMA(0, 1, At, B1); PG8_BAR;
;             PG8_LDA(At, 0, 1); PG8_STAGE(PG8_SA(0, 0), a2, voffA);
;             PG8_BAR; PG8_WAIT_L(0); PG8_MMA(1, 0, At, B0); PG8_BAR; PG8_SCHED;
;             PG8_STAGE(PG8_SB(0, 1), b2 + hstepB, voffB);
;             PG8_WAIT_V(6); PG8_BAR; PG8_MMA(1, 1, At, B1); PG8_BAR;
.LBB0_795:
	s_add_u32 s6, s4, 0xfffc0080
	s_addc_u32 s7, s5, -1
	s_add_i32 s51, 0, 0x10000
	v_add_u32_e32 v148, s51, v155
	ds_read_b128 v[136:139], v148
	ds_read_b128 v[140:143], v148 offset:1024
	ds_read_b128 v[144:147], v148 offset:2048
	ds_read_b128 v[148:151], v148 offset:3072
	s_cmp_eq_u32 s50, 12
	s_cselect_b32 s27, s19, s7
	s_cselect_b32 s26, s46, s6
	s_cselect_b32 s25, s17, s49
	s_cselect_b32 s24, s47, s48
	v_lshl_add_u64 v[152:153], s[4:5], 0, v[132:133]
	s_add_i32 m0, s37, 0xc000
	ds_read_b128 v[166:169], v164
	ds_read_b128 v[170:173], v164 offset:1024
	ds_read_b128 v[174:177], v164 offset:2048
	ds_read_b128 v[178:181], v164 offset:3072
	ds_read_b128 v[182:185], v164 offset:4096
	ds_read_b128 v[186:189], v164 offset:5120
	ds_read_b128 v[190:193], v164 offset:6144
	ds_read_b128 v[194:197], v164 offset:7168
	global_load_lds_dwordx4 v[152:153], off
	v_lshl_add_u64 v[152:153], s[4:5], 0, v[134:135]
	s_add_i32 m0, s37, 0xe000
	s_nop 0
	global_load_lds_dwordx4 v[152:153], off
	s_waitcnt lgkmcnt(8)
	s_barrier
	s_waitcnt lgkmcnt(0)
	s_setprio 1
	s_waitcnt lgkmcnt(0)
	v_mfma_f32_16x16x32_f16 v[126:129], v[136:139], v[166:169], v[126:129]
	v_mfma_f32_16x16x32_f16 v[122:125], v[144:147], v[166:169], v[122:125]
	v_mfma_f32_16x16x32_f16 v[110:113], v[136:139], v[174:177], v[110:113]
	v_mfma_f32_16x16x32_f16 v[106:109], v[144:147], v[174:177], v[106:109]
	v_mfma_f32_16x16x32_f16 v[94:97], v[136:139], v[182:185], v[94:97]
	v_mfma_f32_16x16x32_f16 v[90:93], v[144:147], v[182:185], v[90:93]
	v_mfma_f32_16x16x32_f16 v[78:81], v[136:139], v[190:193], v[78:81]
	v_mfma_f32_16x16x32_f16 v[74:77], v[144:147], v[190:193], v[74:77]
	v_mfma_f32_16x16x32_f16 v[126:129], v[140:143], v[170:173], v[126:129]
	v_mfma_f32_16x16x32_f16 v[122:125], v[148:151], v[170:173], v[122:125]
	v_mfma_f32_16x16x32_f16 v[110:113], v[140:143], v[178:181], v[110:113]
	v_mfma_f32_16x16x32_f16 v[106:109], v[148:151], v[178:181], v[106:109]
	v_mfma_f32_16x16x32_f16 v[94:97], v[140:143], v[186:189], v[94:97]
	v_mfma_f32_16x16x32_f16 v[90:93], v[148:151], v[186:189], v[90:93]
	v_mfma_f32_16x16x32_f16 v[78:81], v[140:143], v[194:197], v[78:81]
	v_mfma_f32_16x16x32_f16 v[74:77], v[148:151], v[194:197], v[74:77]
	s_setprio 0
	s_barrier
	s_add_i32 s6, 0, 0x14000
	v_add_u32_e32 v152, s6, v155
	s_add_i32 s7, s51, s36
	ds_read_b128 v[198:201], v152
	ds_read_b128 v[202:205], v152 offset:1024
	ds_read_b128 v[206:209], v152 offset:2048
	ds_read_b128 v[210:213], v152 offset:3072
	v_lshl_add_u64 v[152:153], s[24:25], 0, v[0:1]
	s_mov_b32 m0, s7
	v_lshl_add_u64 v[214:215], s[24:25], 0, v[130:131]
	global_load_lds_dwordx4 v[152:153], off
	s_add_i32 m0, s7, 0x2000
	s_nop 0
	global_load_lds_dwordx4 v[214:215], off
	s_barrier
	s_waitcnt lgkmcnt(0)
	s_setprio 1
	s_waitcnt lgkmcnt(0)
	v_mfma_f32_16x16x32_f16 v[118:121], v[198:201], v[166:169], v[118:121]
	v_mfma_f32_16x16x32_f16 v[114:117], v[206:209], v[166:169], v[114:117]
	v_mfma_f32_16x16x32_f16 v[102:105], v[198:201], v[174:177], v[102:105]
	v_mfma_f32_16x16x32_f16 v[98:101], v[206:209], v[174:177], v[98:101]
	v_mfma_f32_16x16x32_f16 v[86:89], v[198:201], v[182:185], v[86:89]
	v_mfma_f32_16x16x32_f16 v[82:85], v[206:209], v[182:185], v[82:85]
	v_mfma_f32_16x16x32_f16 v[70:73], v[198:201], v[190:193], v[70:73]
	v_mfma_f32_16x16x32_f16 v[66:69], v[206:209], v[190:193], v[66:69]
	v_mfma_f32_16x16x32_f16 v[118:121], v[202:205], v[170:173], v[118:121]
	v_mfma_f32_16x16x32_f16 v[114:117], v[210:213], v[170:173], v[114:117]
	v_mfma_f32_16x16x32_f16 v[102:105], v[202:205], v[178:181], v[102:105]
	v_mfma_f32_16x16x32_f16 v[98:101], v[210:213], v[178:181], v[98:101]
	v_mfma_f32_16x16x32_f16 v[86:89], v[202:205], v[186:189], v[86:89]
	v_mfma_f32_16x16x32_f16 v[82:85], v[210:213], v[186:189], v[82:85]
	v_mfma_f32_16x16x32_f16 v[70:73], v[202:205], v[194:197], v[70:73]
	v_mfma_f32_16x16x32_f16 v[66:69], v[210:213], v[194:197], v[66:69]
	s_setprio 0
	s_mov_b32 m0, s37
	v_lshl_add_u64 v[228:229], s[26:27], 0, v[0:1]
	s_barrier
	ds_read_b128 v[166:169], v164 offset:16384
	ds_read_b128 v[170:173], v164 offset:17408
	ds_read_b128 v[174:177], v164 offset:18432
	ds_read_b128 v[178:181], v164 offset:19456
	ds_read_b128 v[182:185], v164 offset:20480
	ds_read_b128 v[186:189], v164 offset:21504
	ds_read_b128 v[190:193], v164 offset:22528
	ds_read_b128 v[194:197], v164 offset:23552
	global_load_lds_dwordx4 v[228:229], off
	v_lshl_add_u64 v[230:231], s[26:27], 0, v[130:131]
	s_mov_b32 m0, s38
	s_nop 0
	global_load_lds_dwordx4 v[230:231], off
	s_barrier
	s_waitcnt lgkmcnt(0)
	s_setprio 1
	s_waitcnt lgkmcnt(0)
	v_mfma_f32_16x16x32_f16 v[62:65], v[136:139], v[166:169], v[62:65]
	v_mfma_f32_16x16x32_f16 v[58:61], v[144:147], v[166:169], v[58:61]
	v_mfma_f32_16x16x32_f16 v[46:49], v[136:139], v[174:177], v[46:49]
	v_mfma_f32_16x16x32_f16 v[42:45], v[144:147], v[174:177], v[42:45]
	v_mfma_f32_16x16x32_f16 v[30:33], v[136:139], v[182:185], v[30:33]
	v_mfma_f32_16x16x32_f16 v[26:29], v[144:147], v[182:185], v[26:29]
	v_mfma_f32_16x16x32_f16 v[14:17], v[136:139], v[190:193], v[14:17]
	v_mfma_f32_16x16x32_f16 v[10:13], v[144:147], v[190:193], v[10:13]
	v_mfma_f32_16x16x32_f16 v[62:65], v[140:143], v[170:173], v[62:65]
	v_mfma_f32_16x16x32_f16 v[58:61], v[148:151], v[170:173], v[58:61]
	v_mfma_f32_16x16x32_f16 v[46:49], v[140:143], v[178:181], v[46:49]
	v_mfma_f32_16x16x32_f16 v[42:45], v[148:151], v[178:181], v[42:45]
	v_mfma_f32_16x16x32_f16 v[30:33], v[140:143], v[186:189], v[30:33]
	v_mfma_f32_16x16x32_f16 v[26:29], v[148:151], v[186:189], v[26:29]
	v_mfma_f32_16x16x32_f16 v[14:17], v[140:143], v[194:197], v[14:17]
	v_mfma_f32_16x16x32_f16 v[10:13], v[148:151], v[194:197], v[10:13]
	s_setprio 0
	s_barrier
; #define PG8_STAGE(bufoff, gbase, voff) do { _Pragma("unroll") for (int _i = 0; _i < 2; ++_i) \
;         __builtin_amdgcn_global_load_lds((const unsigned*)((const char*)(gbase) + (voff)[_i]), (LAS unsigned*)(lds + (bufoff) + ldsw + _i * 8192), 16, 0, 0); } while (0)
; #define PG8_LDA(dst, b, h) do { _Pragma("unroll") for (int m = 0; m < 4; ++m) _Pragma("unroll") for (int k = 0; k < 2; ++k) dst[m][k] = *(const LAS h16x8*)(lds + PG8_SA(b, h) + aoff + m * 2048 + k * 1024); } while (0)
; #define PG8_LDB(dst, b, h) do { _Pragma("unroll") for (int n = 0; n < 2; ++n) _Pragma("unroll") for (int k = 0; k < 2; ++k) dst[n][k] = *(const LAS h16x8*)(lds + PG8_SB(b, h) + boff + n * 2048 + k * 1024); } while (0)
; #define PG8_MMA(ai, bj, At, Bt) do { __builtin_amdgcn_s_setprio(1); _Pragma("unroll") for (int m = 0; m < 4; ++m) _Pragma("unroll") for (int n = 0; n < 2; ++n) _Pragma("unroll") for (int k = 0; k < 2; ++k) \
;         acc[ai][bj][m][n] = __builtin_amdgcn_mfma_f32_16x16x32_f16(Bt[n][k], At[m][k], acc[ai][bj][m][n], 0, 0, 0); __builtin_amdgcn_s_setprio(0); } while (0)
; #define PG8_WAIT_V(n) asm volatile("s_waitcnt vmcnt(" #n ")" ::: "memory")
; #define PG8_WAIT_L(n) asm volatile("s_waitcnt lgkmcnt(" #n ")" ::: "memory")
; #define PG8_BAR __builtin_amdgcn_s_barrier()
; #define PG8_SCHED __builtin_amdgcn_sched_barrier(0)
; template <class Epi>
; __device__ __forceinline__ void gemm_phase(LAS unsigned char* lds, const Gemm g, const StaticOrder& S, const Epi& E, const int wid_s) {
;     ...
;             PG8_WAIT_V(6); PG8_BAR; PG8_MMA(1, 1, At, B1); PG8_BAR;
;             PG8_LDB(B0, 1, 0); PG8_SCHED; PG8_LDA(At, 1, 0); PG8_STAGE(PG8_SA(0, 1), a2 + hstepA, voffA);
;             PG8_WAIT_L(8); PG8_BAR; PG8_WAIT_L(0); PG8_MMA(0, 0, At, B0); PG8_BAR; PG8_SCHED;
;             PG8_LDB(B1, 1, 1); PG8_STAGE(PG8_SB(1, 0), b3, voffB);
;             PG8_BAR; PG8_WAIT_L(0); PG8_MMA(0, 1, At, B1); PG8_BAR;
;             PG8_LDA(At, 1, 1); PG8_STAGE(PG8_SA(1, 0), a3, voffA);
;             PG8_BAR; PG8_WAIT_L(0); PG8_MMA(1, 0, At, B0); PG8_BAR; PG8_SCHED;
	s_add_u32 s52, s24, 0x40000
	s_addc_u32 s53, s25, 0
	s_add_i32 s6, s6, s36
	v_lshl_add_u64 v[136:137], s[52:53], 0, v[0:1]
	s_mov_b32 m0, s6
	s_nop 0
	global_load_lds_dwordx4 v[136:137], off
	v_lshl_add_u64 v[136:137], s[52:53], 0, v[130:131]
	s_add_i32 m0, s6, 0x2000
	s_nop 0
	global_load_lds_dwordx4 v[136:137], off
	s_waitcnt vmcnt(6)
	s_barrier
	s_setprio 1
	v_mfma_f32_16x16x32_f16 v[54:57], v[198:201], v[166:169], v[54:57]
	v_mfma_f32_16x16x32_f16 v[50:53], v[206:209], v[166:169], v[50:53]
	v_mfma_f32_16x16x32_f16 v[38:41], v[198:201], v[174:177], v[38:41]
	v_mfma_f32_16x16x32_f16 v[34:37], v[206:209], v[174:177], v[34:37]
	v_mfma_f32_16x16x32_f16 v[22:25], v[198:201], v[182:185], v[22:25]
	v_mfma_f32_16x16x32_f16 v[18:21], v[206:209], v[182:185], v[18:21]
	v_mfma_f32_16x16x32_f16 v[6:9], v[198:201], v[190:193], v[6:9]
	v_mfma_f32_16x16x32_f16 v[2:5], v[206:209], v[190:193], v[2:5]
	v_mfma_f32_16x16x32_f16 v[54:57], v[202:205], v[170:173], v[54:57]
	v_mfma_f32_16x16x32_f16 v[50:53], v[210:213], v[170:173], v[50:53]
	v_mfma_f32_16x16x32_f16 v[38:41], v[202:205], v[178:181], v[38:41]
	v_mfma_f32_16x16x32_f16 v[34:37], v[210:213], v[178:181], v[34:37]
	v_mfma_f32_16x16x32_f16 v[22:25], v[202:205], v[186:189], v[22:25]
	v_mfma_f32_16x16x32_f16 v[18:21], v[210:213], v[186:189], v[18:21]
	v_mfma_f32_16x16x32_f16 v[6:9], v[202:205], v[194:197], v[6:9]
	v_mfma_f32_16x16x32_f16 v[2:5], v[210:213], v[194:197], v[2:5]
	s_setprio 0
	s_add_i32 s6, 0, 0x18000
	v_add_u32_e32 v148, s6, v155
	s_barrier
	ds_read_b128 v[136:139], v148
	ds_read_b128 v[140:143], v148 offset:1024
	ds_read_b128 v[144:147], v148 offset:2048
	ds_read_b128 v[148:151], v148 offset:3072
	s_add_u32 s26, s26, 0x40000
	s_addc_u32 s27, s27, 0
	s_mov_b32 m0, s39
	v_lshl_add_u64 v[198:199], s[26:27], 0, v[0:1]
	ds_read_b128 v[166:169], v164 offset:32768
	ds_read_b128 v[170:173], v164 offset:33792
	ds_read_b128 v[174:177], v164 offset:34816
	ds_read_b128 v[178:181], v164 offset:35840
	ds_read_b128 v[182:185], v164 offset:36864
	ds_read_b128 v[186:189], v164 offset:37888
	ds_read_b128 v[190:193], v164 offset:38912
	ds_read_b128 v[194:197], v164 offset:39936
	global_load_lds_dwordx4 v[198:199], off
	v_lshl_add_u64 v[198:199], s[26:27], 0, v[130:131]
	s_mov_b32 m0, s40
	s_nop 0
	global_load_lds_dwordx4 v[198:199], off
	s_waitcnt lgkmcnt(8)
	s_barrier
	s_waitcnt lgkmcnt(0)
	s_setprio 1
	s_waitcnt lgkmcnt(0)
	v_mfma_f32_16x16x32_f16 v[126:129], v[136:139], v[166:169], v[126:129]
	v_mfma_f32_16x16x32_f16 v[122:125], v[144:147], v[166:169], v[122:125]
	v_mfma_f32_16x16x32_f16 v[110:113], v[136:139], v[174:177], v[110:113]
	v_mfma_f32_16x16x32_f16 v[106:109], v[144:147], v[174:177], v[106:109]
	v_mfma_f32_16x16x32_f16 v[94:97], v[136:139], v[182:185], v[94:97]
	v_mfma_f32_16x16x32_f16 v[90:93], v[144:147], v[182:185], v[90:93]
	v_mfma_f32_16x16x32_f16 v[78:81], v[136:139], v[190:193], v[78:81]
	v_mfma_f32_16x16x32_f16 v[74:77], v[144:147], v[190:193], v[74:77]
	v_mfma_f32_16x16x32_f16 v[126:129], v[140:143], v[170:173], v[126:129]
	v_mfma_f32_16x16x32_f16 v[122:125], v[148:151], v[170:173], v[122:125]
	v_mfma_f32_16x16x32_f16 v[110:113], v[140:143], v[178:181], v[110:113]
	v_mfma_f32_16x16x32_f16 v[106:109], v[148:151], v[178:181], v[106:109]
	v_mfma_f32_16x16x32_f16 v[94:97], v[140:143], v[186:189], v[94:97]
	v_mfma_f32_16x16x32_f16 v[90:93], v[148:151], v[186:189], v[90:93]
	v_mfma_f32_16x16x32_f16 v[78:81], v[140:143], v[194:197], v[78:81]
	v_mfma_f32_16x16x32_f16 v[74:77], v[148:151], v[194:197], v[74:77]
	s_setprio 0
	s_barrier
	s_add_i32 s7, 0, 0x1c000
	s_add_i32 s6, s6, s36
	v_add_u32_e32 v165, s7, v155
	v_lshl_add_u64 v[152:153], v[152:153], 0, s[74:75]
	s_mov_b32 m0, s6
	ds_read_b128 v[198:201], v165
	ds_read_b128 v[202:205], v165 offset:1024
	ds_read_b128 v[206:209], v165 offset:2048
	ds_read_b128 v[210:213], v165 offset:3072
	global_load_lds_dwordx4 v[152:153], off
	v_lshl_add_u64 v[152:153], v[214:215], 0, s[74:75]
	s_add_i32 m0, s6, 0x2000
	s_nop 0
	global_load_lds_dwordx4 v[152:153], off
	s_barrier
	s_waitcnt lgkmcnt(0)
	s_setprio 1
	s_waitcnt lgkmcnt(0)
	v_mfma_f32_16x16x32_f16 v[118:121], v[198:201], v[166:169], v[118:121]
	v_mfma_f32_16x16x32_f16 v[114:117], v[206:209], v[166:169], v[114:117]
	v_mfma_f32_16x16x32_f16 v[102:105], v[198:201], v[174:177], v[102:105]
	v_mfma_f32_16x16x32_f16 v[98:101], v[206:209], v[174:177], v[98:101]
	v_mfma_f32_16x16x32_f16 v[86:89], v[198:201], v[182:185], v[86:89]
	v_mfma_f32_16x16x32_f16 v[82:85], v[206:209], v[182:185], v[82:85]
	v_mfma_f32_16x16x32_f16 v[70:73], v[198:201], v[190:193], v[70:73]
	v_mfma_f32_16x16x32_f16 v[66:69], v[206:209], v[190:193], v[66:69]
	v_mfma_f32_16x16x32_f16 v[118:121], v[202:205], v[170:173], v[118:121]
	v_mfma_f32_16x16x32_f16 v[114:117], v[210:213], v[170:173], v[114:117]
	v_mfma_f32_16x16x32_f16 v[102:105], v[202:205], v[178:181], v[102:105]
	v_mfma_f32_16x16x32_f16 v[98:101], v[210:213], v[178:181], v[98:101]
	v_mfma_f32_16x16x32_f16 v[86:89], v[202:205], v[186:189], v[86:89]
	v_mfma_f32_16x16x32_f16 v[82:85], v[210:213], v[186:189], v[82:85]
	v_mfma_f32_16x16x32_f16 v[70:73], v[202:205], v[194:197], v[70:73]
	v_mfma_f32_16x16x32_f16 v[66:69], v[210:213], v[194:197], v[66:69]
	s_setprio 0
	s_mov_b32 m0, s41
	v_lshl_add_u64 v[152:153], v[228:229], 0, s[74:75]
	s_barrier
	ds_read_b128 v[166:169], v164 offset:49152
	ds_read_b128 v[170:173], v164 offset:50176
	ds_read_b128 v[174:177], v164 offset:51200
	ds_read_b128 v[178:181], v164 offset:52224
	ds_read_b128 v[182:185], v164 offset:53248
	ds_read_b128 v[186:189], v164 offset:54272
	ds_read_b128 v[190:193], v164 offset:55296
	ds_read_b128 v[194:197], v164 offset:56320
	global_load_lds_dwordx4 v[152:153], off
	v_lshl_add_u64 v[152:153], v[230:231], 0, s[74:75]
	s_mov_b32 m0, s42
	s_nop 0
	global_load_lds_dwordx4 v[152:153], off
	s_barrier
; #define PG8_WAIT_V(n) asm volatile("s_waitcnt vmcnt(" #n ")" ::: "memory")
; #define PG8_WAIT_L(n) asm volatile("s_waitcnt lgkmcnt(" #n ")" ::: "memory")
; #define PG8_BAR __builtin_amdgcn_s_barrier()
; template <class Epi>
; __device__ __forceinline__ void gemm_phase(LAS unsigned char* lds, const Gemm g, const StaticOrder& S, const Epi& E, const int wid_s) {
;     ...
;             PG8_BAR; PG8_WAIT_L(0); PG8_MMA(1, 0, At, B0); PG8_BAR; PG8_SCHED;
;             PG8_STAGE(PG8_SB(1, 1), b3 + hstepB, voffB);
;             PG8_WAIT_V(6); PG8_BAR; PG8_MMA(1, 1, At, B1); PG8_BAR;
;     __device__ __forceinline__ void operator()(const f32x4 (&acc)[2][2][4][2], const Unit& u, int wr, int wc, int fr, int fq) const {
;         const int row0 = u.pm * BM + wr * 64 + fr, col0 = u.pn * BM + wc * 32 + 4 * fq;
;         h16x4 hin[2][2], hnx[2][2];
; #pragma unroll
;         for (int bj = 0; bj < 2; ++bj)
; #pragma unroll
;             for (int n = 0; n < 2; ++n) hin[bj][n] = *(const h16x4*)(HB + (size_t)row0 * D + col0 + bj * HALF + n * 16);
; #pragma unroll
;         for (int g = 0; g < 8; ++g) {
;             const int ai = g >> 2, m = g & 3;
;             const int r = row0 + ai * HALF + m * 16; float ss = 0.f;
;             if (g < 7) { const int rn = row0 + ((g + 1) >> 2) * HALF + ((g + 1) & 3) * 16;
; #pragma unroll
;                 for (int bj = 0; bj < 2; ++bj)
; #pragma unroll
;                     for (int n = 0; n < 2; ++n) hnx[bj][n] = *(const h16x4*)(HB + (size_t)rn * D + col0 + bj * HALF + n * 16); }
; #pragma unroll
;             for (int bj = 0; bj < 2; ++bj)
; #pragma unroll
;                 for (int n = 0; n < 2; ++n) {
;                     const size_t o = (size_t)r * D + col0 + bj * HALF + n * 16;
;                     f32x4 hv; hv[0] = (float)hin[bj][n][0]; hv[1] = (float)hin[bj][n][1]; hv[2] = (float)hin[bj][n][2]; hv[3] = (float)hin[bj][n][3];
;                     hv += acc[ai][bj][m][n];
;                     ss += hv[0] * hv[0] + hv[1] * hv[1] + hv[2] * hv[2] + hv[3] * hv[3];
;                     if (OUT != nullptr) *(f32x4*)(OUT + o) = hv;
;                     else { h16x4 hh; hh[0] = (h16)hv[0]; hh[1] = (h16)hv[1]; hh[2] = (h16)hv[2]; hh[3] = (h16)hv[3]; *(h16x4*)(HB + o) = hh; }
;                 }
;             ss += __shfl_xor(ss, 16); ss += __shfl_xor(ss, 32);
;             if (fq == 0) atomicAdd(rsq_next + r, ss);
	s_waitcnt lgkmcnt(0)
	s_setprio 1
	s_waitcnt lgkmcnt(0)
	v_mfma_f32_16x16x32_f16 v[62:65], v[136:139], v[166:169], v[62:65]
	v_mfma_f32_16x16x32_f16 v[58:61], v[144:147], v[166:169], v[58:61]
	v_mfma_f32_16x16x32_f16 v[46:49], v[136:139], v[174:177], v[46:49]
	v_mfma_f32_16x16x32_f16 v[42:45], v[144:147], v[174:177], v[42:45]
	v_mfma_f32_16x16x32_f16 v[30:33], v[136:139], v[182:185], v[30:33]
	v_mfma_f32_16x16x32_f16 v[26:29], v[144:147], v[182:185], v[26:29]
	v_mfma_f32_16x16x32_f16 v[14:17], v[136:139], v[190:193], v[14:17]
	v_mfma_f32_16x16x32_f16 v[10:13], v[144:147], v[190:193], v[10:13]
	v_mfma_f32_16x16x32_f16 v[62:65], v[140:143], v[170:173], v[62:65]
	v_mfma_f32_16x16x32_f16 v[58:61], v[148:151], v[170:173], v[58:61]
	v_mfma_f32_16x16x32_f16 v[46:49], v[140:143], v[178:181], v[46:49]
	v_mfma_f32_16x16x32_f16 v[42:45], v[148:151], v[178:181], v[42:45]
	v_mfma_f32_16x16x32_f16 v[30:33], v[140:143], v[186:189], v[30:33]
	v_mfma_f32_16x16x32_f16 v[26:29], v[148:151], v[186:189], v[26:29]
	v_mfma_f32_16x16x32_f16 v[14:17], v[140:143], v[194:197], v[14:17]
	v_mfma_f32_16x16x32_f16 v[10:13], v[148:151], v[194:197], v[10:13]
	s_setprio 0
	s_barrier
	s_add_u32 s24, s24, 0x40080
	s_addc_u32 s25, s25, 0
	s_add_i32 s6, s7, s36
	v_lshl_add_u64 v[136:137], s[24:25], 0, v[0:1]
	s_mov_b32 m0, s6
	s_nop 0
	global_load_lds_dwordx4 v[136:137], off
	v_lshl_add_u64 v[136:137], s[24:25], 0, v[130:131]
	s_add_i32 m0, s6, 0x2000
	s_nop 0
	global_load_lds_dwordx4 v[136:137], off
	s_waitcnt vmcnt(6)
	s_barrier
	s_setprio 1
	v_mfma_f32_16x16x32_f16 v[54:57], v[198:201], v[166:169], v[54:57]
	v_mfma_f32_16x16x32_f16 v[50:53], v[206:209], v[166:169], v[50:53]
	v_mfma_f32_16x16x32_f16 v[38:41], v[198:201], v[174:177], v[38:41]
	v_mfma_f32_16x16x32_f16 v[34:37], v[206:209], v[174:177], v[34:37]
	v_mfma_f32_16x16x32_f16 v[22:25], v[198:201], v[182:185], v[22:25]
	v_mfma_f32_16x16x32_f16 v[18:21], v[206:209], v[182:185], v[18:21]
	v_mfma_f32_16x16x32_f16 v[6:9], v[198:201], v[190:193], v[6:9]
	v_mfma_f32_16x16x32_f16 v[2:5], v[206:209], v[190:193], v[2:5]
	v_mfma_f32_16x16x32_f16 v[54:57], v[202:205], v[170:173], v[54:57]
	v_mfma_f32_16x16x32_f16 v[50:53], v[210:213], v[170:173], v[50:53]
	v_mfma_f32_16x16x32_f16 v[38:41], v[202:205], v[178:181], v[38:41]
	v_mfma_f32_16x16x32_f16 v[34:37], v[210:213], v[178:181], v[34:37]
	v_mfma_f32_16x16x32_f16 v[22:25], v[202:205], v[186:189], v[22:25]
	v_mfma_f32_16x16x32_f16 v[18:21], v[210:213], v[186:189], v[18:21]
	v_mfma_f32_16x16x32_f16 v[6:9], v[202:205], v[194:197], v[6:9]
	v_mfma_f32_16x16x32_f16 v[2:5], v[210:213], v[194:197], v[2:5]
	s_setprio 0
	s_add_i32 s50, s50, 2
	s_add_u32 s4, s4, 0x100
	s_addc_u32 s5, s5, 0
	s_add_u32 s48, s48, 0x100
	s_addc_u32 s49, s49, 0
	s_cmp_gt_u32 s50, 13
	s_barrier
	s_cbranch_scc0 .LBB0_795
	s_cmpk_gt_u32 s29, 0xff
	s_cbranch_scc1 .Lalign_oddout_a
	s_barrier
.Lalign_oddout_a:
	v_lshl_add_u32 v138, s45, 8, v154
	v_lshl_or_b32 v136, s44, 8, v163
	v_ashrrev_i32_e32 v139, 31, v138
	v_lshlrev_b64 v[140:141], 11, v[138:139]
	v_ashrrev_i32_e32 v137, 31, v136
	v_lshl_add_u64 v[140:141], s[12:13], 0, v[140:141]
	v_lshlrev_b64 v[142:143], 1, v[136:137]
	v_lshl_add_u64 v[152:153], v[140:141], 0, v[142:143]
	global_load_dwordx2 v[166:167], v[152:153], off
	global_load_dwordx2 v[168:169], v[152:153], off offset:32
	global_load_dwordx2 v[170:171], v[152:153], off offset:256
	global_load_dwordx2 v[172:173], v[152:153], off offset:288
	v_or_b32_e32 v140, 16, v138
	v_ashrrev_i32_e32 v141, 31, v140
	v_lshlrev_b64 v[144:145], 11, v[140:141]
	v_lshl_add_u64 v[144:145], s[12:13], 0, v[144:145]
	v_lshl_add_u64 v[142:143], v[144:145], 0, v[142:143]
	global_load_dwordx2 v[150:151], v[142:143], off
	global_load_dwordx2 v[148:149], v[142:143], off offset:32
	global_load_dwordx2 v[146:147], v[142:143], off offset:256
	global_load_dwordx2 v[144:145], v[142:143], off offset:288
	s_waitcnt vmcnt(0)
	v_cvt_f32_f16_e32 v174, v166
	v_cvt_f32_f16_sdwa v175, v166 dst_sel:DWORD dst_unused:UNUSED_PAD src0_sel:WORD_1
	v_cvt_f32_f16_e32 v166, v167
	v_cvt_f32_f16_sdwa v167, v167 dst_sel:DWORD dst_unused:UNUSED_PAD src0_sel:WORD_1
	v_pk_add_f32 v[126:127], v[126:127], v[174:175]
	s_nop 0
	v_mul_f32_e32 v165, v127, v127
	v_pk_add_f32 v[128:129], v[128:129], v[166:167]
	v_fmac_f32_e32 v165, v126, v126
	v_fmac_f32_e32 v165, v128, v128
	v_fmac_f32_e32 v165, v129, v129
	v_cvt_pk_f16_f32 v129, v128, v129
	v_cvt_pk_f16_f32 v128, v126, v127
	v_cvt_f32_f16_e32 v126, v168
	v_cvt_f32_f16_sdwa v127, v168 dst_sel:DWORD dst_unused:UNUSED_PAD src0_sel:WORD_1
	global_store_dwordx2 v[152:153], v[128:129], off
	v_cvt_f32_f16_e32 v128, v169
	v_cvt_f32_f16_sdwa v129, v169 dst_sel:DWORD dst_unused:UNUSED_PAD src0_sel:WORD_1
	v_pk_add_f32 v[122:123], v[122:123], v[126:127]
	v_pk_add_f32 v[124:125], v[124:125], v[128:129]
	v_mul_f32_e32 v126, v123, v123
	v_fmac_f32_e32 v126, v122, v122
	v_fmac_f32_e32 v126, v124, v124
	v_fmac_f32_e32 v126, v125, v125
	v_cvt_pk_f16_f32 v125, v124, v125
	v_cvt_pk_f16_f32 v124, v122, v123
	v_cvt_f32_f16_e32 v122, v170
	v_cvt_f32_f16_sdwa v123, v170 dst_sel:DWORD dst_unused:UNUSED_PAD src0_sel:WORD_1
	global_store_dwordx2 v[152:153], v[124:125], off offset:32
	v_cvt_f32_f16_e32 v124, v171
	v_cvt_f32_f16_sdwa v125, v171 dst_sel:DWORD dst_unused:UNUSED_PAD src0_sel:WORD_1
	v_pk_add_f32 v[118:119], v[118:119], v[122:123]
	v_add_f32_e32 v126, v165, v126
	v_mul_f32_e32 v122, v119, v119
	v_pk_add_f32 v[120:121], v[120:121], v[124:125]
	v_fmac_f32_e32 v122, v118, v118
	v_fmac_f32_e32 v122, v120, v120
	v_fmac_f32_e32 v122, v121, v121
	v_cvt_pk_f16_f32 v121, v120, v121
	v_cvt_pk_f16_f32 v120, v118, v119
	v_cvt_f32_f16_e32 v118, v172
	v_cvt_f32_f16_sdwa v119, v172 dst_sel:DWORD dst_unused:UNUSED_PAD src0_sel:WORD_1
	global_store_dwordx2 v[152:153], v[120:121], off offset:256
	v_cvt_f32_f16_e32 v120, v173
	v_cvt_f32_f16_sdwa v121, v173 dst_sel:DWORD dst_unused:UNUSED_PAD src0_sel:WORD_1
	v_pk_add_f32 v[114:115], v[114:115], v[118:119]
	v_add_f32_e32 v122, v126, v122
	v_mul_f32_e32 v118, v115, v115
	v_pk_add_f32 v[116:117], v[116:117], v[120:121]
	v_fmac_f32_e32 v118, v114, v114
	v_fmac_f32_e32 v118, v116, v116
	v_fmac_f32_e32 v118, v117, v117
	v_add_f32_e32 v118, v122, v118
	v_cvt_pk_f16_f32 v117, v116, v117
	v_cvt_pk_f16_f32 v116, v114, v115
	ds_bpermute_b32 v114, v161, v118
	global_store_dwordx2 v[152:153], v[116:117], off offset:288
	s_waitcnt lgkmcnt(0)
	v_add_f32_e32 v114, v118, v114
	ds_bpermute_b32 v115, v162, v114
	s_and_saveexec_b64 s[4:5], s[8:9]
	s_cbranch_execz .LBB0_798
	v_lshl_add_u64 v[116:117], v[138:139], 2, s[14:15]
	s_waitcnt lgkmcnt(0)
	v_add_f32_e32 v114, v114, v115
	global_atomic_add_f32 v[116:117], v114, off

; template <class Epi>
; __device__ __forceinline__ void gemm_phase(LAS unsigned char* lds, const Gemm g, const StaticOrder& S, const Epi& E, const int wid_s) {
;     ...
;     for (;;) {
;         const bool has_next = S.next(ui + 1, nxt);
;         const char* nA = has_next ? (const char*)g.A + (size_t)nxt.pm * tstepA : cA; const char* nB = has_next ? (const char*)g.Bt + (size_t)nxt.pn * tstepB : cB;
.LBB0_857:
	s_and_b64 vcc, exec, s[8:9]
	s_mov_b32 s43, s20
	s_mov_b32 s44, s22
	s_mov_b64 s[10:11], s[26:27]
	s_mov_b64 s[4:5], s[24:25]
	s_cmpk_gt_u32 s28, 0xff
	s_cbranch_scc0 .Lalign_evin_b
	s_barrier

; #define PG8_STAGE(bufoff, gbase, voff) do { _Pragma("unroll") for (int _i = 0; _i < 2; ++_i) \
;         __builtin_amdgcn_global_load_lds((const unsigned*)((const char*)(gbase) + (voff)[_i]), (LAS unsigned*)(lds + (bufoff) + ldsw + _i * 8192), 16, 0, 0); } while (0)
; #define PG8_LDA(dst, b, h) do { _Pragma("unroll") for (int m = 0; m < 4; ++m) _Pragma("unroll") for (int k = 0; k < 2; ++k) dst[m][k] = *(const LAS h16x8*)(lds + PG8_SA(b, h) + aoff + m * 2048 + k * 1024); } while (0)
; #define PG8_LDB(dst, b, h) do { _Pragma("unroll") for (int n = 0; n < 2; ++n) _Pragma("unroll") for (int k = 0; k < 2; ++k) dst[n][k] = *(const LAS h16x8*)(lds + PG8_SB(b, h) + boff + n * 2048 + k * 1024); } while (0)
; #define PG8_MMA(ai, bj, At, Bt) do { __builtin_amdgcn_s_setprio(1); _Pragma("unroll") for (int m = 0; m < 4; ++m) _Pragma("unroll") for (int n = 0; n < 2; ++n) _Pragma("unroll") for (int k = 0; k < 2; ++k) \
;         acc[ai][bj][m][n] = __builtin_amdgcn_mfma_f32_16x16x32_f16(Bt[n][k], At[m][k], acc[ai][bj][m][n], 0, 0, 0); __builtin_amdgcn_s_setprio(0); } while (0)
; #define PG8_WAIT_V(n) asm volatile("s_waitcnt vmcnt(" #n ")" ::: "memory")
; #define PG8_WAIT_L(n) asm volatile("s_waitcnt lgkmcnt(" #n ")" ::: "memory")
; #define PG8_BAR __builtin_amdgcn_s_barrier()
; #define PG8_SCHED __builtin_amdgcn_sched_barrier(0)
; template <class Epi>
; __device__ __forceinline__ void gemm_phase(LAS unsigned char* lds, const Gemm g, const StaticOrder& S, const Epi& E, const int wid_s) {
;     ...
;             PG8_LDB(B0, 0, 0); PG8_SCHED; PG8_LDA(At, 0, 0); PG8_STAGE(PG8_SA(1, 1), a1 + hstepA, voffA);
;             PG8_WAIT_L(8); PG8_BAR; PG8_WAIT_L(0); PG8_MMA(0, 0, At, B0); PG8_BAR; PG8_SCHED;
;             PG8_LDB(B1, 0, 1); PG8_STAGE(PG8_SB(0, 0), b2, voffB);
;             PG8_BAR; PG8_WAIT_L(0); PG8_MMA(0, 1, At, B1); PG8_BAR;
;             PG8_LDA(At, 0, 1); PG8_STAGE(PG8_SA(0, 0), a2, voffA);
;             PG8_BAR; PG8_WAIT_L(0); PG8_MMA(1, 0, At, B0); PG8_BAR; PG8_SCHED;
;             PG8_STAGE(PG8_SB(0, 1), b2 + hstepB, voffB);
;             PG8_WAIT_V(6); PG8_BAR; PG8_MMA(1, 1, At, B1); PG8_BAR;
.LBB0_861:
	s_add_u32 s10, s4, 0xfffc0080
	s_addc_u32 s11, s5, -1
	s_add_i32 s50, 0, 0x10000
	v_add_u32_e32 v152, s50, v155
	ds_read_b128 v[130:133], v152
	ds_read_b128 v[134:137], v152 offset:1024
	ds_read_b128 v[148:151], v152 offset:2048
	ds_read_b128 v[164:167], v152 offset:3072
	s_cmp_eq_u32 s49, 12
	s_cselect_b32 s13, s23, s11
	s_cselect_b32 s12, s45, s10
	s_cselect_b32 s11, s21, s48
	s_cselect_b32 s10, s46, s47
	v_lshl_add_u64 v[152:153], s[4:5], 0, v[144:145]
	s_add_i32 m0, s36, 0xc000
	ds_read_b128 v[168:171], v162
	ds_read_b128 v[172:175], v162 offset:1024
	ds_read_b128 v[176:179], v162 offset:2048
	ds_read_b128 v[180:183], v162 offset:3072
	ds_read_b128 v[184:187], v162 offset:4096
	ds_read_b128 v[188:191], v162 offset:5120
	ds_read_b128 v[192:195], v162 offset:6144
	ds_read_b128 v[196:199], v162 offset:7168
	global_load_lds_dwordx4 v[152:153], off
	v_lshl_add_u64 v[152:153], s[4:5], 0, v[146:147]
	s_add_i32 m0, s36, 0xe000
	s_nop 0
	global_load_lds_dwordx4 v[152:153], off
	s_waitcnt lgkmcnt(8)
	s_barrier
	s_waitcnt lgkmcnt(0)
	s_setprio 1
	s_waitcnt lgkmcnt(0)
	v_mfma_f32_16x16x32_f16 v[126:129], v[130:133], v[168:171], v[126:129]
	v_mfma_f32_16x16x32_f16 v[122:125], v[148:151], v[168:171], v[122:125]
	v_mfma_f32_16x16x32_f16 v[110:113], v[130:133], v[176:179], v[110:113]
	v_mfma_f32_16x16x32_f16 v[106:109], v[148:151], v[176:179], v[106:109]
	v_mfma_f32_16x16x32_f16 v[94:97], v[130:133], v[184:187], v[94:97]
	v_mfma_f32_16x16x32_f16 v[90:93], v[148:151], v[184:187], v[90:93]
	v_mfma_f32_16x16x32_f16 v[78:81], v[130:133], v[192:195], v[78:81]
	v_mfma_f32_16x16x32_f16 v[74:77], v[148:151], v[192:195], v[74:77]
	v_mfma_f32_16x16x32_f16 v[126:129], v[134:137], v[172:175], v[126:129]
	v_mfma_f32_16x16x32_f16 v[122:125], v[164:167], v[172:175], v[122:125]
	v_mfma_f32_16x16x32_f16 v[110:113], v[134:137], v[180:183], v[110:113]
	v_mfma_f32_16x16x32_f16 v[106:109], v[164:167], v[180:183], v[106:109]
	v_mfma_f32_16x16x32_f16 v[94:97], v[134:137], v[188:191], v[94:97]
	v_mfma_f32_16x16x32_f16 v[90:93], v[164:167], v[188:191], v[90:93]
	v_mfma_f32_16x16x32_f16 v[78:81], v[134:137], v[196:199], v[78:81]
	v_mfma_f32_16x16x32_f16 v[74:77], v[164:167], v[196:199], v[74:77]
	s_setprio 0
	s_barrier
	s_add_i32 s52, 0, 0x14000
	v_add_u32_e32 v152, s52, v155
	s_add_i32 s50, s50, s35
	ds_read_b128 v[200:203], v152
	ds_read_b128 v[204:207], v152 offset:1024
	ds_read_b128 v[208:211], v152 offset:2048
	ds_read_b128 v[212:215], v152 offset:3072
	v_lshl_add_u64 v[152:153], s[10:11], 0, v[0:1]
	s_mov_b32 m0, s50
	v_lshl_add_u64 v[228:229], s[10:11], 0, v[138:139]
	global_load_lds_dwordx4 v[152:153], off
	s_add_i32 m0, s50, 0x2000
	s_nop 0
	global_load_lds_dwordx4 v[228:229], off
	s_barrier
	s_waitcnt lgkmcnt(0)
	s_setprio 1
	s_waitcnt lgkmcnt(0)
	v_mfma_f32_16x16x32_f16 v[118:121], v[200:203], v[168:171], v[118:121]
	v_mfma_f32_16x16x32_f16 v[114:117], v[208:211], v[168:171], v[114:117]
	v_mfma_f32_16x16x32_f16 v[102:105], v[200:203], v[176:179], v[102:105]
	v_mfma_f32_16x16x32_f16 v[98:101], v[208:211], v[176:179], v[98:101]
	v_mfma_f32_16x16x32_f16 v[86:89], v[200:203], v[184:187], v[86:89]
	v_mfma_f32_16x16x32_f16 v[82:85], v[208:211], v[184:187], v[82:85]
	v_mfma_f32_16x16x32_f16 v[70:73], v[200:203], v[192:195], v[70:73]
	v_mfma_f32_16x16x32_f16 v[66:69], v[208:211], v[192:195], v[66:69]
	v_mfma_f32_16x16x32_f16 v[118:121], v[204:207], v[172:175], v[118:121]
	v_mfma_f32_16x16x32_f16 v[114:117], v[212:215], v[172:175], v[114:117]
	v_mfma_f32_16x16x32_f16 v[102:105], v[204:207], v[180:183], v[102:105]
	v_mfma_f32_16x16x32_f16 v[98:101], v[212:215], v[180:183], v[98:101]
	v_mfma_f32_16x16x32_f16 v[86:89], v[204:207], v[188:191], v[86:89]
	v_mfma_f32_16x16x32_f16 v[82:85], v[212:215], v[188:191], v[82:85]
	v_mfma_f32_16x16x32_f16 v[70:73], v[204:207], v[196:199], v[70:73]
	v_mfma_f32_16x16x32_f16 v[66:69], v[212:215], v[196:199], v[66:69]
	s_setprio 0
	s_mov_b32 m0, s36
	v_lshl_add_u64 v[230:231], s[12:13], 0, v[142:143]
	s_barrier
	ds_read_b128 v[168:171], v162 offset:16384
	ds_read_b128 v[172:175], v162 offset:17408
	ds_read_b128 v[176:179], v162 offset:18432
	ds_read_b128 v[180:183], v162 offset:19456
	ds_read_b128 v[184:187], v162 offset:20480
	ds_read_b128 v[188:191], v162 offset:21504
	ds_read_b128 v[192:195], v162 offset:22528
	ds_read_b128 v[196:199], v162 offset:23552
	global_load_lds_dwordx4 v[230:231], off
	v_lshl_add_u64 v[232:233], s[12:13], 0, v[140:141]
	s_mov_b32 m0, s37
	s_nop 0
	global_load_lds_dwordx4 v[232:233], off
	s_barrier
	s_waitcnt lgkmcnt(0)
	s_setprio 1
	s_waitcnt lgkmcnt(0)
	v_mfma_f32_16x16x32_f16 v[62:65], v[130:133], v[168:171], v[62:65]
	v_mfma_f32_16x16x32_f16 v[58:61], v[148:151], v[168:171], v[58:61]
	v_mfma_f32_16x16x32_f16 v[46:49], v[130:133], v[176:179], v[46:49]
	v_mfma_f32_16x16x32_f16 v[42:45], v[148:151], v[176:179], v[42:45]
	v_mfma_f32_16x16x32_f16 v[30:33], v[130:133], v[184:187], v[30:33]
	v_mfma_f32_16x16x32_f16 v[26:29], v[148:151], v[184:187], v[26:29]
	v_mfma_f32_16x16x32_f16 v[14:17], v[130:133], v[192:195], v[14:17]
	v_mfma_f32_16x16x32_f16 v[10:13], v[148:151], v[192:195], v[10:13]
	v_mfma_f32_16x16x32_f16 v[62:65], v[134:137], v[172:175], v[62:65]
	v_mfma_f32_16x16x32_f16 v[58:61], v[164:167], v[172:175], v[58:61]
	v_mfma_f32_16x16x32_f16 v[46:49], v[134:137], v[180:183], v[46:49]
	v_mfma_f32_16x16x32_f16 v[42:45], v[164:167], v[180:183], v[42:45]
	v_mfma_f32_16x16x32_f16 v[30:33], v[134:137], v[188:191], v[30:33]
	v_mfma_f32_16x16x32_f16 v[26:29], v[164:167], v[188:191], v[26:29]
	v_mfma_f32_16x16x32_f16 v[14:17], v[134:137], v[196:199], v[14:17]
	v_mfma_f32_16x16x32_f16 v[10:13], v[164:167], v[196:199], v[10:13]
	s_setprio 0
	s_barrier
; #define PG8_STAGE(bufoff, gbase, voff) do { _Pragma("unroll") for (int _i = 0; _i < 2; ++_i) \
;         __builtin_amdgcn_global_load_lds((const unsigned*)((const char*)(gbase) + (voff)[_i]), (LAS unsigned*)(lds + (bufoff) + ldsw + _i * 8192), 16, 0, 0); } while (0)
; #define PG8_LDA(dst, b, h) do { _Pragma("unroll") for (int m = 0; m < 4; ++m) _Pragma("unroll") for (int k = 0; k < 2; ++k) dst[m][k] = *(const LAS h16x8*)(lds + PG8_SA(b, h) + aoff + m * 2048 + k * 1024); } while (0)
; #define PG8_LDB(dst, b, h) do { _Pragma("unroll") for (int n = 0; n < 2; ++n) _Pragma("unroll") for (int k = 0; k < 2; ++k) dst[n][k] = *(const LAS h16x8*)(lds + PG8_SB(b, h) + boff + n * 2048 + k * 1024); } while (0)
; #define PG8_MMA(ai, bj, At, Bt) do { __builtin_amdgcn_s_setprio(1); _Pragma("unroll") for (int m = 0; m < 4; ++m) _Pragma("unroll") for (int n = 0; n < 2; ++n) _Pragma("unroll") for (int k = 0; k < 2; ++k) \
;         acc[ai][bj][m][n] = __builtin_amdgcn_mfma_f32_16x16x32_f16(Bt[n][k], At[m][k], acc[ai][bj][m][n], 0, 0, 0); __builtin_amdgcn_s_setprio(0); } while (0)
; #define PG8_WAIT_V(n) asm volatile("s_waitcnt vmcnt(" #n ")" ::: "memory")
; #define PG8_WAIT_L(n) asm volatile("s_waitcnt lgkmcnt(" #n ")" ::: "memory")
; #define PG8_BAR __builtin_amdgcn_s_barrier()
; #define PG8_SCHED __builtin_amdgcn_sched_barrier(0)
; template <class Epi>
; __device__ __forceinline__ void gemm_phase(LAS unsigned char* lds, const Gemm g, const StaticOrder& S, const Epi& E, const int wid_s) {
;     ...
;             PG8_WAIT_V(6); PG8_BAR; PG8_MMA(1, 1, At, B1); PG8_BAR;
;             PG8_LDB(B0, 1, 0); PG8_SCHED; PG8_LDA(At, 1, 0); PG8_STAGE(PG8_SA(0, 1), a2 + hstepA, voffA);
;             PG8_WAIT_L(8); PG8_BAR; PG8_WAIT_L(0); PG8_MMA(0, 0, At, B0); PG8_BAR; PG8_SCHED;
;             PG8_LDB(B1, 1, 1); PG8_STAGE(PG8_SB(1, 0), b3, voffB);
;             PG8_BAR; PG8_WAIT_L(0); PG8_MMA(0, 1, At, B1); PG8_BAR;
;             PG8_LDA(At, 1, 1); PG8_STAGE(PG8_SA(1, 0), a3, voffA);
;             PG8_BAR; PG8_WAIT_L(0); PG8_MMA(1, 0, At, B0); PG8_BAR; PG8_SCHED;
	s_add_u32 s50, s10, 0x40000
	s_addc_u32 s51, s11, 0
	s_add_i32 s52, s52, s35
	v_lshl_add_u64 v[130:131], s[50:51], 0, v[0:1]
	s_mov_b32 m0, s52
	s_nop 0
	global_load_lds_dwordx4 v[130:131], off
	v_lshl_add_u64 v[130:131], s[50:51], 0, v[138:139]
	s_add_i32 m0, s52, 0x2000
	s_nop 0
	global_load_lds_dwordx4 v[130:131], off
	s_waitcnt vmcnt(6)
	s_barrier
	s_setprio 1
	v_mfma_f32_16x16x32_f16 v[54:57], v[200:203], v[168:171], v[54:57]
	v_mfma_f32_16x16x32_f16 v[50:53], v[208:211], v[168:171], v[50:53]
	v_mfma_f32_16x16x32_f16 v[38:41], v[200:203], v[176:179], v[38:41]
	v_mfma_f32_16x16x32_f16 v[34:37], v[208:211], v[176:179], v[34:37]
	v_mfma_f32_16x16x32_f16 v[22:25], v[200:203], v[184:187], v[22:25]
	v_mfma_f32_16x16x32_f16 v[18:21], v[208:211], v[184:187], v[18:21]
	v_mfma_f32_16x16x32_f16 v[6:9], v[200:203], v[192:195], v[6:9]
	v_mfma_f32_16x16x32_f16 v[2:5], v[208:211], v[192:195], v[2:5]
	v_mfma_f32_16x16x32_f16 v[54:57], v[204:207], v[172:175], v[54:57]
	v_mfma_f32_16x16x32_f16 v[50:53], v[212:215], v[172:175], v[50:53]
	v_mfma_f32_16x16x32_f16 v[38:41], v[204:207], v[180:183], v[38:41]
	v_mfma_f32_16x16x32_f16 v[34:37], v[212:215], v[180:183], v[34:37]
	v_mfma_f32_16x16x32_f16 v[22:25], v[204:207], v[188:191], v[22:25]
	v_mfma_f32_16x16x32_f16 v[18:21], v[212:215], v[188:191], v[18:21]
	v_mfma_f32_16x16x32_f16 v[6:9], v[204:207], v[196:199], v[6:9]
	v_mfma_f32_16x16x32_f16 v[2:5], v[212:215], v[196:199], v[2:5]
	s_setprio 0
	s_add_i32 s50, 0, 0x18000
	v_add_u32_e32 v163, s50, v155
	s_barrier
	ds_read_b128 v[130:133], v163
	ds_read_b128 v[134:137], v163 offset:1024
	ds_read_b128 v[148:151], v163 offset:2048
	ds_read_b128 v[164:167], v163 offset:3072
	s_add_u32 s12, s12, 0x40000
	s_addc_u32 s13, s13, 0
	s_mov_b32 m0, s38
	v_lshl_add_u64 v[200:201], s[12:13], 0, v[142:143]
	ds_read_b128 v[168:171], v162 offset:32768
	ds_read_b128 v[172:175], v162 offset:33792
	ds_read_b128 v[176:179], v162 offset:34816
	ds_read_b128 v[180:183], v162 offset:35840
	ds_read_b128 v[184:187], v162 offset:36864
	ds_read_b128 v[188:191], v162 offset:37888
	ds_read_b128 v[192:195], v162 offset:38912
	ds_read_b128 v[196:199], v162 offset:39936
	global_load_lds_dwordx4 v[200:201], off
	v_lshl_add_u64 v[200:201], s[12:13], 0, v[140:141]
	s_mov_b32 m0, s39
	s_nop 0
	global_load_lds_dwordx4 v[200:201], off
	s_waitcnt lgkmcnt(8)
	s_barrier
	s_waitcnt lgkmcnt(0)
	s_setprio 1
	s_waitcnt lgkmcnt(0)
	v_mfma_f32_16x16x32_f16 v[126:129], v[130:133], v[168:171], v[126:129]
	v_mfma_f32_16x16x32_f16 v[122:125], v[148:151], v[168:171], v[122:125]
	v_mfma_f32_16x16x32_f16 v[110:113], v[130:133], v[176:179], v[110:113]
	v_mfma_f32_16x16x32_f16 v[106:109], v[148:151], v[176:179], v[106:109]
	v_mfma_f32_16x16x32_f16 v[94:97], v[130:133], v[184:187], v[94:97]
	v_mfma_f32_16x16x32_f16 v[90:93], v[148:151], v[184:187], v[90:93]
	v_mfma_f32_16x16x32_f16 v[78:81], v[130:133], v[192:195], v[78:81]
	v_mfma_f32_16x16x32_f16 v[74:77], v[148:151], v[192:195], v[74:77]
	v_mfma_f32_16x16x32_f16 v[126:129], v[134:137], v[172:175], v[126:129]
	v_mfma_f32_16x16x32_f16 v[122:125], v[164:167], v[172:175], v[122:125]
	v_mfma_f32_16x16x32_f16 v[110:113], v[134:137], v[180:183], v[110:113]
	v_mfma_f32_16x16x32_f16 v[106:109], v[164:167], v[180:183], v[106:109]
	v_mfma_f32_16x16x32_f16 v[94:97], v[134:137], v[188:191], v[94:97]
	v_mfma_f32_16x16x32_f16 v[90:93], v[164:167], v[188:191], v[90:93]
	v_mfma_f32_16x16x32_f16 v[78:81], v[134:137], v[196:199], v[78:81]
	v_mfma_f32_16x16x32_f16 v[74:77], v[164:167], v[196:199], v[74:77]
	s_setprio 0
	s_barrier
	s_add_i32 s12, 0, 0x1c000
	s_add_i32 s13, s50, s35
	v_add_u32_e32 v163, s12, v155
	v_lshl_add_u64 v[152:153], v[152:153], 0, s[74:75]
	s_mov_b32 m0, s13
	ds_read_b128 v[200:203], v163
	ds_read_b128 v[204:207], v163 offset:1024
	ds_read_b128 v[208:211], v163 offset:2048
	ds_read_b128 v[212:215], v163 offset:3072
	global_load_lds_dwordx4 v[152:153], off
	v_lshl_add_u64 v[152:153], v[228:229], 0, s[74:75]
	s_add_i32 m0, s13, 0x2000
	s_nop 0
	global_load_lds_dwordx4 v[152:153], off
	s_barrier
	s_waitcnt lgkmcnt(0)
	s_setprio 1
	s_waitcnt lgkmcnt(0)
	v_mfma_f32_16x16x32_f16 v[118:121], v[200:203], v[168:171], v[118:121]
	v_mfma_f32_16x16x32_f16 v[114:117], v[208:211], v[168:171], v[114:117]
	v_mfma_f32_16x16x32_f16 v[102:105], v[200:203], v[176:179], v[102:105]
	v_mfma_f32_16x16x32_f16 v[98:101], v[208:211], v[176:179], v[98:101]
	v_mfma_f32_16x16x32_f16 v[86:89], v[200:203], v[184:187], v[86:89]
	v_mfma_f32_16x16x32_f16 v[82:85], v[208:211], v[184:187], v[82:85]
	v_mfma_f32_16x16x32_f16 v[70:73], v[200:203], v[192:195], v[70:73]
	v_mfma_f32_16x16x32_f16 v[66:69], v[208:211], v[192:195], v[66:69]
	v_mfma_f32_16x16x32_f16 v[118:121], v[204:207], v[172:175], v[118:121]
	v_mfma_f32_16x16x32_f16 v[114:117], v[212:215], v[172:175], v[114:117]
	v_mfma_f32_16x16x32_f16 v[102:105], v[204:207], v[180:183], v[102:105]
	v_mfma_f32_16x16x32_f16 v[98:101], v[212:215], v[180:183], v[98:101]
	v_mfma_f32_16x16x32_f16 v[86:89], v[204:207], v[188:191], v[86:89]
	v_mfma_f32_16x16x32_f16 v[82:85], v[212:215], v[188:191], v[82:85]
	v_mfma_f32_16x16x32_f16 v[70:73], v[204:207], v[196:199], v[70:73]
	v_mfma_f32_16x16x32_f16 v[66:69], v[212:215], v[196:199], v[66:69]
	s_setprio 0
	s_mov_b32 m0, s40
	v_lshl_add_u64 v[152:153], v[230:231], 0, s[74:75]
	s_barrier
	ds_read_b128 v[168:171], v162 offset:49152
	ds_read_b128 v[172:175], v162 offset:50176
	ds_read_b128 v[176:179], v162 offset:51200
	ds_read_b128 v[180:183], v162 offset:52224
	ds_read_b128 v[184:187], v162 offset:53248
	ds_read_b128 v[188:191], v162 offset:54272
	ds_read_b128 v[192:195], v162 offset:55296
	ds_read_b128 v[196:199], v162 offset:56320
	global_load_lds_dwordx4 v[152:153], off
	v_lshl_add_u64 v[152:153], v[232:233], 0, s[74:75]
	s_mov_b32 m0, s41
	s_nop 0
	global_load_lds_dwordx4 v[152:153], off
	s_barrier
; __device__ __forceinline__ float gelu_tanh(float x) { const float z = 1.5957691216f * (x + 0.044715f * x * x * x); return x * __builtin_amdgcn_rcpf(1.f + __expf(-z)); }
; #define PG8_STAGE(bufoff, gbase, voff) do { _Pragma("unroll") for (int _i = 0; _i < 2; ++_i) \
;         __builtin_amdgcn_global_load_lds((const unsigned*)((const char*)(gbase) + (voff)[_i]), (LAS unsigned*)(lds + (bufoff) + ldsw + _i * 8192), 16, 0, 0); } while (0)
; #define PG8_WAIT_V(n) asm volatile("s_waitcnt vmcnt(" #n ")" ::: "memory")
; #define PG8_WAIT_L(n) asm volatile("s_waitcnt lgkmcnt(" #n ")" ::: "memory")
; #define PG8_BAR __builtin_amdgcn_s_barrier()
; #define PG8_SCHED __builtin_amdgcn_sched_barrier(0)
; template <class Epi>
; __device__ __forceinline__ void gemm_phase(LAS unsigned char* lds, const Gemm g, const StaticOrder& S, const Epi& E, const int wid_s) {
;     ...
;             PG8_BAR; PG8_WAIT_L(0); PG8_MMA(1, 0, At, B0); PG8_BAR; PG8_SCHED;
;             PG8_STAGE(PG8_SB(1, 1), b3 + hstepB, voffB);
;             PG8_WAIT_V(6); PG8_BAR; PG8_MMA(1, 1, At, B1); PG8_BAR;
;     __device__ __forceinline__ void operator()(const f32x4 (&acc)[2][2][4][2], const Unit& u, int wr, int wc, int fr, int fq) const {
;         const int row0 = u.pm * BM + wr * 64 + fr, col0 = u.pn * BM + wc * 32 + 8 * fq;
;         const bool dg = u.pn < gelu_tiles, isba = (u.pn == ba_tile);
;         float rsv[2][4];
; #pragma unroll
;         for (int ai = 0; ai < 2; ++ai)
; #pragma unroll
;             for (int m = 0; m < 4; ++m) rsv[ai][m] = rowsq[row0 + ai * HALF + m * 16];
; #pragma unroll
;         for (int ai = 0; ai < 2; ++ai)
; #pragma unroll
;             for (int m = 0; m < 4; ++m) {
;                 const int r = row0 + ai * HALF + m * 16;
;                 const float rs = rsqrtf(rsv[ai][m] * (1.0f / 1024.0f) + EPS);
; #pragma unroll
;                 for (int bj = 0; bj < 2; ++bj) {
;                     f32x4 v0 = acc[ai][bj][m][0] * rs, v1 = acc[ai][bj][m][1] * rs;
;                     if (isba) {
;                         if (bj == 0 && wc == 0 && fq == 0) { *(f32x4*)(ba + (size_t)r * 8) = v0; *(f32x4*)(ba + (size_t)r * 8 + 4) = v1; }
;                     } else {
;                         if (dg) {
; #pragma unroll
;                             for (int j = 0; j < 4; ++j) { v0[j] = gelu_tanh(v0[j]); v1[j] = gelu_tanh(v1[j]); }
	s_waitcnt lgkmcnt(0)
	s_setprio 1
	s_waitcnt lgkmcnt(0)
	v_mfma_f32_16x16x32_f16 v[62:65], v[130:133], v[168:171], v[62:65]
	v_mfma_f32_16x16x32_f16 v[58:61], v[148:151], v[168:171], v[58:61]
	v_mfma_f32_16x16x32_f16 v[46:49], v[130:133], v[176:179], v[46:49]
	v_mfma_f32_16x16x32_f16 v[42:45], v[148:151], v[176:179], v[42:45]
	v_mfma_f32_16x16x32_f16 v[30:33], v[130:133], v[184:187], v[30:33]
	v_mfma_f32_16x16x32_f16 v[26:29], v[148:151], v[184:187], v[26:29]
	v_mfma_f32_16x16x32_f16 v[14:17], v[130:133], v[192:195], v[14:17]
	v_mfma_f32_16x16x32_f16 v[10:13], v[148:151], v[192:195], v[10:13]
	v_mfma_f32_16x16x32_f16 v[62:65], v[134:137], v[172:175], v[62:65]
	v_mfma_f32_16x16x32_f16 v[58:61], v[164:167], v[172:175], v[58:61]
	v_mfma_f32_16x16x32_f16 v[46:49], v[134:137], v[180:183], v[46:49]
	v_mfma_f32_16x16x32_f16 v[42:45], v[164:167], v[180:183], v[42:45]
	v_mfma_f32_16x16x32_f16 v[30:33], v[134:137], v[188:191], v[30:33]
	v_mfma_f32_16x16x32_f16 v[26:29], v[164:167], v[188:191], v[26:29]
	v_mfma_f32_16x16x32_f16 v[14:17], v[134:137], v[196:199], v[14:17]
	v_mfma_f32_16x16x32_f16 v[10:13], v[164:167], v[196:199], v[10:13]
	s_setprio 0
	s_barrier
	s_add_u32 s10, s10, 0x40080
	s_addc_u32 s11, s11, 0
	s_add_i32 s12, s12, s35
	v_lshl_add_u64 v[130:131], s[10:11], 0, v[0:1]
	s_mov_b32 m0, s12
	s_nop 0
	global_load_lds_dwordx4 v[130:131], off
	v_lshl_add_u64 v[130:131], s[10:11], 0, v[138:139]
	s_add_i32 m0, s12, 0x2000
	s_nop 0
	global_load_lds_dwordx4 v[130:131], off
	s_waitcnt vmcnt(6)
	s_barrier
	s_setprio 1
	v_mfma_f32_16x16x32_f16 v[54:57], v[200:203], v[168:171], v[54:57]
	v_mfma_f32_16x16x32_f16 v[50:53], v[208:211], v[168:171], v[50:53]
	v_mfma_f32_16x16x32_f16 v[38:41], v[200:203], v[176:179], v[38:41]
	v_mfma_f32_16x16x32_f16 v[34:37], v[208:211], v[176:179], v[34:37]
	v_mfma_f32_16x16x32_f16 v[22:25], v[200:203], v[184:187], v[22:25]
	v_mfma_f32_16x16x32_f16 v[18:21], v[208:211], v[184:187], v[18:21]
	v_mfma_f32_16x16x32_f16 v[6:9], v[200:203], v[192:195], v[6:9]
	v_mfma_f32_16x16x32_f16 v[2:5], v[208:211], v[192:195], v[2:5]
	v_mfma_f32_16x16x32_f16 v[54:57], v[204:207], v[172:175], v[54:57]
	v_mfma_f32_16x16x32_f16 v[50:53], v[212:215], v[172:175], v[50:53]
	v_mfma_f32_16x16x32_f16 v[38:41], v[204:207], v[180:183], v[38:41]
	v_mfma_f32_16x16x32_f16 v[34:37], v[212:215], v[180:183], v[34:37]
	v_mfma_f32_16x16x32_f16 v[22:25], v[204:207], v[188:191], v[22:25]
	v_mfma_f32_16x16x32_f16 v[18:21], v[212:215], v[188:191], v[18:21]
	v_mfma_f32_16x16x32_f16 v[6:9], v[204:207], v[196:199], v[6:9]
	v_mfma_f32_16x16x32_f16 v[2:5], v[212:215], v[196:199], v[2:5]
	s_setprio 0
	s_add_i32 s49, s49, 2
	s_add_u32 s4, s4, 0x100
	s_addc_u32 s5, s5, 0
	s_add_u32 s47, s47, 0x100
	s_addc_u32 s48, s48, 0
	s_cmp_gt_u32 s49, 13
	s_barrier
	s_cbranch_scc0 .LBB0_861
	s_cmpk_gt_u32 s28, 0xff
	s_cbranch_scc1 .Lalign_evin_a
	s_barrier
.Lalign_evin_a:
	v_lshl_add_u32 v150, s44, 8, v154
	v_ashrrev_i32_e32 v151, 31, v150
	v_lshl_add_u64 v[130:131], v[150:151], 2, s[16:17]
	global_load_dword v132, v[130:131], off
	global_load_dword v169, v[130:131], off offset:64
	global_load_dword v168, v[130:131], off offset:128
	global_load_dword v167, v[130:131], off offset:192
	global_load_dword v166, v[130:131], off offset:512
	global_load_dword v165, v[130:131], off offset:576
	global_load_dword v164, v[130:131], off offset:640
	global_load_dword v163, v[130:131], off offset:704
	s_cmp_lt_i32 s43, 4
	s_cselect_b64 s[10:11], -1, 0
	s_cmp_lg_u32 s43, 12
	v_lshl_or_b32 v148, s43, 8, v161
	s_cselect_b64 s[4:5], -1, 0
	v_ashrrev_i32_e32 v149, 31, v148
	s_mov_b64 s[12:13], -1
	s_waitcnt vmcnt(0)
	v_fmamk_f32 v130, v132, 0x3a800000, v216
	v_cmp_gt_f32_e32 vcc, s2, v130
	v_mul_f32_e32 v131, 0x4b800000, v130
	s_nop 0
	v_cndmask_b32_e32 v130, v130, v131, vcc
	v_rsq_f32_e32 v130, v130
	s_nop 0
	v_mul_f32_e32 v131, 0x45800000, v130
	v_cndmask_b32_e32 v152, v130, v131, vcc
	v_cndmask_b32_e64 v130, 0, 1, s[10:11]
	v_pk_mul_f32 v[128:129], v[128:129], v[152:153] op_sel_hi:[1,0]
	v_pk_mul_f32 v[126:127], v[126:127], v[152:153] op_sel_hi:[1,0]
	v_pk_mul_f32 v[124:125], v[124:125], v[152:153] op_sel_hi:[1,0]
	v_pk_mul_f32 v[122:123], v[122:123], v[152:153] op_sel_hi:[1,0]
	s_and_b64 vcc, exec, s[4:5]
	v_cmp_ne_u32_e64 s[10:11], 1, v130
	s_cbranch_vccz .LBB0_867
	v_mov_b64_e32 v[132:133], v[128:129]
	v_mov_b64_e32 v[136:137], v[124:125]
	s_and_b64 vcc, exec, s[10:11]
	v_mov_b64_e32 v[130:131], v[126:127]
	v_mov_b64_e32 v[134:135], v[122:123]
	s_cbranch_vccnz .LBB0_865
	v_mul_f32_e32 v131, 0x3d372713, v122
	v_mul_f32_e32 v131, v122, v131
	v_mul_f32_e32 v132, 0x3d372713, v127
	v_fma_f32 v131, v122, v131, v122
	v_mul_f32_e32 v132, v127, v132
	v_mov_b32_e32 v133, v127
	v_mul_f32_e32 v131, 0xbfcc422a, v131
	v_fmac_f32_e32 v133, v133, v132
	v_mul_f32_e32 v131, 0x3fb8aa3b, v131
	v_mul_f32_e32 v132, 0xbfcc422a, v133
	v_exp_f32_e32 v131, v131
	v_mul_f32_e32 v132, 0x3fb8aa3b, v132
	v_exp_f32_e32 v132, v132
	v_mov_b32_e32 v133, v123
	v_add_f32_e32 v131, 1.0, v131
	v_rcp_f32_e32 v134, v131
	v_add_f32_e32 v131, 1.0, v132
	v_mul_f32_e32 v132, 0x3d372713, v123
	v_mul_f32_e32 v132, v123, v132
	v_fmac_f32_e32 v133, v133, v132
	v_mul_f32_e32 v132, 0xbfcc422a, v133
	v_mul_f32_e32 v133, 0x3d372713, v128
	v_mul_f32_e32 v135, 0x3d372713, v124
	v_mul_f32_e32 v133, v128, v133
	v_mul_f32_e32 v135, v124, v135
	v_fma_f32 v133, v128, v133, v128
	v_fma_f32 v135, v124, v135, v124
	v_mul_f32_e32 v133, 0xbfcc422a, v133
	v_mul_f32_e32 v135, 0xbfcc422a, v135
	v_mul_f32_e32 v132, 0x3fb8aa3b, v132
	v_mul_f32_e32 v133, 0x3fb8aa3b, v133
	v_mul_f32_e32 v135, 0x3fb8aa3b, v135
	v_exp_f32_e32 v132, v132
	v_exp_f32_e32 v133, v133
	v_exp_f32_e32 v135, v135
	v_mul_f32_e32 v130, 0x3d372713, v126
	v_add_f32_e32 v153, 1.0, v132
	v_add_f32_e32 v132, 1.0, v133
	v_add_f32_e32 v133, 1.0, v135
	v_mul_f32_e32 v135, 0x3d372713, v129
	v_mul_f32_e32 v136, 0x3d372713, v125
	v_mul_f32_e32 v130, v126, v130
	v_mul_f32_e32 v135, v129, v135
	v_mul_f32_e32 v136, v125, v136
	v_fma_f32 v130, v126, v130, v126
	v_fma_f32 v135, v129, v135, v129
	v_fma_f32 v136, v125, v136, v125
	v_mul_f32_e32 v130, 0xbfcc422a, v130
	v_mul_f32_e32 v135, 0xbfcc422a, v135
	v_mul_f32_e32 v136, 0xbfcc422a, v136
	v_mul_f32_e32 v130, 0x3fb8aa3b, v130
	v_mul_f32_e32 v135, 0x3fb8aa3b, v135
	v_mul_f32_e32 v136, 0x3fb8aa3b, v136
	v_exp_f32_e32 v130, v130
	v_exp_f32_e32 v135, v135
	v_exp_f32_e32 v137, v136
	v_rcp_f32_e32 v136, v133
	v_add_f32_e32 v130, 1.0, v130
	v_add_f32_e32 v133, 1.0, v135
	v_add_f32_e32 v135, 1.0, v137
	v_rcp_f32_e32 v130, v130
	v_rcp_f32_e32 v131, v131
	v_rcp_f32_e32 v132, v132
	v_rcp_f32_e32 v133, v133
	v_rcp_f32_e32 v137, v135
	v_rcp_f32_e32 v135, v153
	v_pk_mul_f32 v[130:131], v[126:127], v[130:131]
	v_pk_mul_f32 v[132:133], v[128:129], v[132:133]
	v_pk_mul_f32 v[136:137], v[124:125], v[136:137]
	v_pk_mul_f32 v[134:135], v[122:123], v[134:135]

; template <class Epi>
; __device__ __forceinline__ void gemm_phase(LAS unsigned char* lds, const Gemm g, const StaticOrder& S, const Epi& E, const int wid_s) {
;     ...
;     for (;;) {
;         const bool has_next = S.next(ui + 1, nxt);
;         const char* nA = has_next ? (const char*)g.A + (size_t)nxt.pm * tstepA : cA; const char* nB = has_next ? (const char*)g.Bt + (size_t)nxt.pn * tstepB : cB;
.LBB0_1364:
	s_or_b64 exec, exec, s[4:5]
	s_and_b64 vcc, exec, s[8:9]
	s_mov_b32 s42, s14
	s_mov_b32 s43, s16
	s_mov_b64 s[22:23], s[20:21]
	s_mov_b64 s[4:5], s[18:19]
	s_cmpk_gt_u32 s27, 0xff
	s_cbranch_scc0 .Lalign_evout_b
	s_barrier

; #define PG8_STAGE(bufoff, gbase, voff) do { _Pragma("unroll") for (int _i = 0; _i < 2; ++_i) \
;         __builtin_amdgcn_global_load_lds((const unsigned*)((const char*)(gbase) + (voff)[_i]), (LAS unsigned*)(lds + (bufoff) + ldsw + _i * 8192), 16, 0, 0); } while (0)
; #define PG8_LDA(dst, b, h) do { _Pragma("unroll") for (int m = 0; m < 4; ++m) _Pragma("unroll") for (int k = 0; k < 2; ++k) dst[m][k] = *(const LAS h16x8*)(lds + PG8_SA(b, h) + aoff + m * 2048 + k * 1024); } while (0)
; #define PG8_LDB(dst, b, h) do { _Pragma("unroll") for (int n = 0; n < 2; ++n) _Pragma("unroll") for (int k = 0; k < 2; ++k) dst[n][k] = *(const LAS h16x8*)(lds + PG8_SB(b, h) + boff + n * 2048 + k * 1024); } while (0)
; #define PG8_MMA(ai, bj, At, Bt) do { __builtin_amdgcn_s_setprio(1); _Pragma("unroll") for (int m = 0; m < 4; ++m) _Pragma("unroll") for (int n = 0; n < 2; ++n) _Pragma("unroll") for (int k = 0; k < 2; ++k) \
;         acc[ai][bj][m][n] = __builtin_amdgcn_mfma_f32_16x16x32_f16(Bt[n][k], At[m][k], acc[ai][bj][m][n], 0, 0, 0); __builtin_amdgcn_s_setprio(0); } while (0)
; #define PG8_WAIT_V(n) asm volatile("s_waitcnt vmcnt(" #n ")" ::: "memory")
; #define PG8_WAIT_L(n) asm volatile("s_waitcnt lgkmcnt(" #n ")" ::: "memory")
; #define PG8_BAR __builtin_amdgcn_s_barrier()
; #define PG8_SCHED __builtin_amdgcn_sched_barrier(0)
; template <class Epi>
; __device__ __forceinline__ void gemm_phase(LAS unsigned char* lds, const Gemm g, const StaticOrder& S, const Epi& E, const int wid_s) {
;     ...
;             PG8_LDB(B0, 0, 0); PG8_SCHED; PG8_LDA(At, 0, 0); PG8_STAGE(PG8_SA(1, 1), a1 + hstepA, voffA);
;             PG8_WAIT_L(8); PG8_BAR; PG8_WAIT_L(0); PG8_MMA(0, 0, At, B0); PG8_BAR; PG8_SCHED;
;             PG8_LDB(B1, 0, 1); PG8_STAGE(PG8_SB(0, 0), b2, voffB);
;             PG8_BAR; PG8_WAIT_L(0); PG8_MMA(0, 1, At, B1); PG8_BAR;
;             PG8_LDA(At, 0, 1); PG8_STAGE(PG8_SA(0, 0), a2, voffA);
;             PG8_BAR; PG8_WAIT_L(0); PG8_MMA(1, 0, At, B0); PG8_BAR; PG8_SCHED;
;             PG8_STAGE(PG8_SB(0, 1), b2 + hstepB, voffB);
;             PG8_WAIT_V(6); PG8_BAR; PG8_MMA(1, 1, At, B1); PG8_BAR;
.LBB0_1372:
	s_add_u32 s22, s4, 0xfffc0080
	s_addc_u32 s23, s5, -1
	s_add_i32 s49, 0, 0x10000
	v_add_u32_e32 v148, s49, v155
	ds_read_b128 v[136:139], v148
	ds_read_b128 v[140:143], v148 offset:1024
	ds_read_b128 v[144:147], v148 offset:2048
	ds_read_b128 v[148:151], v148 offset:3072
	s_cmp_eq_u32 s48, 12
	s_cselect_b32 s25, s17, s23
	s_cselect_b32 s24, s44, s22
	s_cselect_b32 s23, s15, s47
	s_cselect_b32 s22, s45, s46
	v_lshl_add_u64 v[152:153], s[4:5], 0, v[132:133]
	s_add_i32 m0, s35, 0xc000
	ds_read_b128 v[166:169], v164
	ds_read_b128 v[170:173], v164 offset:1024
	ds_read_b128 v[174:177], v164 offset:2048
	ds_read_b128 v[178:181], v164 offset:3072
	ds_read_b128 v[182:185], v164 offset:4096
	ds_read_b128 v[186:189], v164 offset:5120
	ds_read_b128 v[190:193], v164 offset:6144
	ds_read_b128 v[194:197], v164 offset:7168
	global_load_lds_dwordx4 v[152:153], off
	v_lshl_add_u64 v[152:153], s[4:5], 0, v[134:135]
	s_add_i32 m0, s35, 0xe000
	s_nop 0
	global_load_lds_dwordx4 v[152:153], off
	s_waitcnt lgkmcnt(8)
	s_barrier
	s_waitcnt lgkmcnt(0)
	s_setprio 1
	s_waitcnt lgkmcnt(0)
	v_mfma_f32_16x16x32_f16 v[126:129], v[136:139], v[166:169], v[126:129]
	v_mfma_f32_16x16x32_f16 v[122:125], v[144:147], v[166:169], v[122:125]
	v_mfma_f32_16x16x32_f16 v[110:113], v[136:139], v[174:177], v[110:113]
	v_mfma_f32_16x16x32_f16 v[106:109], v[144:147], v[174:177], v[106:109]
	v_mfma_f32_16x16x32_f16 v[94:97], v[136:139], v[182:185], v[94:97]
	v_mfma_f32_16x16x32_f16 v[90:93], v[144:147], v[182:185], v[90:93]
	v_mfma_f32_16x16x32_f16 v[78:81], v[136:139], v[190:193], v[78:81]
	v_mfma_f32_16x16x32_f16 v[74:77], v[144:147], v[190:193], v[74:77]
	v_mfma_f32_16x16x32_f16 v[126:129], v[140:143], v[170:173], v[126:129]
	v_mfma_f32_16x16x32_f16 v[122:125], v[148:151], v[170:173], v[122:125]
	v_mfma_f32_16x16x32_f16 v[110:113], v[140:143], v[178:181], v[110:113]
	v_mfma_f32_16x16x32_f16 v[106:109], v[148:151], v[178:181], v[106:109]
	v_mfma_f32_16x16x32_f16 v[94:97], v[140:143], v[186:189], v[94:97]
	v_mfma_f32_16x16x32_f16 v[90:93], v[148:151], v[186:189], v[90:93]
	v_mfma_f32_16x16x32_f16 v[78:81], v[140:143], v[194:197], v[78:81]
	v_mfma_f32_16x16x32_f16 v[74:77], v[148:151], v[194:197], v[74:77]
	s_setprio 0
	s_barrier
	s_add_i32 s52, 0, 0x14000
	v_add_u32_e32 v152, s52, v155
	s_add_i32 s49, s49, s34
	ds_read_b128 v[198:201], v152
	ds_read_b128 v[202:205], v152 offset:1024
	ds_read_b128 v[206:209], v152 offset:2048
	ds_read_b128 v[210:213], v152 offset:3072
	v_lshl_add_u64 v[152:153], s[22:23], 0, v[0:1]
	s_mov_b32 m0, s49
	v_lshl_add_u64 v[214:215], s[22:23], 0, v[130:131]
	global_load_lds_dwordx4 v[152:153], off
	s_add_i32 m0, s49, 0x2000
	s_nop 0
	global_load_lds_dwordx4 v[214:215], off
	s_barrier
	s_waitcnt lgkmcnt(0)
	s_setprio 1
	s_waitcnt lgkmcnt(0)
	v_mfma_f32_16x16x32_f16 v[118:121], v[198:201], v[166:169], v[118:121]
	v_mfma_f32_16x16x32_f16 v[114:117], v[206:209], v[166:169], v[114:117]
	v_mfma_f32_16x16x32_f16 v[102:105], v[198:201], v[174:177], v[102:105]
	v_mfma_f32_16x16x32_f16 v[98:101], v[206:209], v[174:177], v[98:101]
	v_mfma_f32_16x16x32_f16 v[86:89], v[198:201], v[182:185], v[86:89]
	v_mfma_f32_16x16x32_f16 v[82:85], v[206:209], v[182:185], v[82:85]
	v_mfma_f32_16x16x32_f16 v[70:73], v[198:201], v[190:193], v[70:73]
	v_mfma_f32_16x16x32_f16 v[66:69], v[206:209], v[190:193], v[66:69]
	v_mfma_f32_16x16x32_f16 v[118:121], v[202:205], v[170:173], v[118:121]
	v_mfma_f32_16x16x32_f16 v[114:117], v[210:213], v[170:173], v[114:117]
	v_mfma_f32_16x16x32_f16 v[102:105], v[202:205], v[178:181], v[102:105]
	v_mfma_f32_16x16x32_f16 v[98:101], v[210:213], v[178:181], v[98:101]
	v_mfma_f32_16x16x32_f16 v[86:89], v[202:205], v[186:189], v[86:89]
	v_mfma_f32_16x16x32_f16 v[82:85], v[210:213], v[186:189], v[82:85]
	v_mfma_f32_16x16x32_f16 v[70:73], v[202:205], v[194:197], v[70:73]
	v_mfma_f32_16x16x32_f16 v[66:69], v[210:213], v[194:197], v[66:69]
	s_setprio 0
	s_mov_b32 m0, s35
	v_lshl_add_u64 v[228:229], s[24:25], 0, v[0:1]
	s_barrier
	ds_read_b128 v[166:169], v164 offset:16384
	ds_read_b128 v[170:173], v164 offset:17408
	ds_read_b128 v[174:177], v164 offset:18432
	ds_read_b128 v[178:181], v164 offset:19456
	ds_read_b128 v[182:185], v164 offset:20480
	ds_read_b128 v[186:189], v164 offset:21504
	ds_read_b128 v[190:193], v164 offset:22528
	ds_read_b128 v[194:197], v164 offset:23552
	global_load_lds_dwordx4 v[228:229], off
	v_lshl_add_u64 v[230:231], s[24:25], 0, v[130:131]
	s_mov_b32 m0, s36
	s_nop 0
	global_load_lds_dwordx4 v[230:231], off
	s_barrier
	s_waitcnt lgkmcnt(0)
	s_setprio 1
	s_waitcnt lgkmcnt(0)
	v_mfma_f32_16x16x32_f16 v[62:65], v[136:139], v[166:169], v[62:65]
	v_mfma_f32_16x16x32_f16 v[58:61], v[144:147], v[166:169], v[58:61]
	v_mfma_f32_16x16x32_f16 v[46:49], v[136:139], v[174:177], v[46:49]
	v_mfma_f32_16x16x32_f16 v[42:45], v[144:147], v[174:177], v[42:45]
	v_mfma_f32_16x16x32_f16 v[30:33], v[136:139], v[182:185], v[30:33]
	v_mfma_f32_16x16x32_f16 v[26:29], v[144:147], v[182:185], v[26:29]
	v_mfma_f32_16x16x32_f16 v[14:17], v[136:139], v[190:193], v[14:17]
	v_mfma_f32_16x16x32_f16 v[10:13], v[144:147], v[190:193], v[10:13]
	v_mfma_f32_16x16x32_f16 v[62:65], v[140:143], v[170:173], v[62:65]
	v_mfma_f32_16x16x32_f16 v[58:61], v[148:151], v[170:173], v[58:61]
	v_mfma_f32_16x16x32_f16 v[46:49], v[140:143], v[178:181], v[46:49]
	v_mfma_f32_16x16x32_f16 v[42:45], v[148:151], v[178:181], v[42:45]
	v_mfma_f32_16x16x32_f16 v[30:33], v[140:143], v[186:189], v[30:33]
	v_mfma_f32_16x16x32_f16 v[26:29], v[148:151], v[186:189], v[26:29]
	v_mfma_f32_16x16x32_f16 v[14:17], v[140:143], v[194:197], v[14:17]
	v_mfma_f32_16x16x32_f16 v[10:13], v[148:151], v[194:197], v[10:13]
	s_setprio 0
	s_barrier
; #define PG8_STAGE(bufoff, gbase, voff) do { _Pragma("unroll") for (int _i = 0; _i < 2; ++_i) \
;         __builtin_amdgcn_global_load_lds((const unsigned*)((const char*)(gbase) + (voff)[_i]), (LAS unsigned*)(lds + (bufoff) + ldsw + _i * 8192), 16, 0, 0); } while (0)
; #define PG8_LDA(dst, b, h) do { _Pragma("unroll") for (int m = 0; m < 4; ++m) _Pragma("unroll") for (int k = 0; k < 2; ++k) dst[m][k] = *(const LAS h16x8*)(lds + PG8_SA(b, h) + aoff + m * 2048 + k * 1024); } while (0)
; #define PG8_LDB(dst, b, h) do { _Pragma("unroll") for (int n = 0; n < 2; ++n) _Pragma("unroll") for (int k = 0; k < 2; ++k) dst[n][k] = *(const LAS h16x8*)(lds + PG8_SB(b, h) + boff + n * 2048 + k * 1024); } while (0)
; #define PG8_MMA(ai, bj, At, Bt) do { __builtin_amdgcn_s_setprio(1); _Pragma("unroll") for (int m = 0; m < 4; ++m) _Pragma("unroll") for (int n = 0; n < 2; ++n) _Pragma("unroll") for (int k = 0; k < 2; ++k) \
;         acc[ai][bj][m][n] = __builtin_amdgcn_mfma_f32_16x16x32_f16(Bt[n][k], At[m][k], acc[ai][bj][m][n], 0, 0, 0); __builtin_amdgcn_s_setprio(0); } while (0)
; #define PG8_WAIT_V(n) asm volatile("s_waitcnt vmcnt(" #n ")" ::: "memory")
; #define PG8_WAIT_L(n) asm volatile("s_waitcnt lgkmcnt(" #n ")" ::: "memory")
; #define PG8_BAR __builtin_amdgcn_s_barrier()
; #define PG8_SCHED __builtin_amdgcn_sched_barrier(0)
; template <class Epi>
; __device__ __forceinline__ void gemm_phase(LAS unsigned char* lds, const Gemm g, const StaticOrder& S, const Epi& E, const int wid_s) {
;     ...
;             PG8_WAIT_V(6); PG8_BAR; PG8_MMA(1, 1, At, B1); PG8_BAR;
;             PG8_LDB(B0, 1, 0); PG8_SCHED; PG8_LDA(At, 1, 0); PG8_STAGE(PG8_SA(0, 1), a2 + hstepA, voffA);
;             PG8_WAIT_L(8); PG8_BAR; PG8_WAIT_L(0); PG8_MMA(0, 0, At, B0); PG8_BAR; PG8_SCHED;
;             PG8_LDB(B1, 1, 1); PG8_STAGE(PG8_SB(1, 0), b3, voffB);
;             PG8_BAR; PG8_WAIT_L(0); PG8_MMA(0, 1, At, B1); PG8_BAR;
;             PG8_LDA(At, 1, 1); PG8_STAGE(PG8_SA(1, 0), a3, voffA);
;             PG8_BAR; PG8_WAIT_L(0); PG8_MMA(1, 0, At, B0); PG8_BAR; PG8_SCHED;
	s_add_u32 s50, s22, 0x40000
	s_addc_u32 s51, s23, 0
	s_add_i32 s49, s52, s34
	v_lshl_add_u64 v[136:137], s[50:51], 0, v[0:1]
	s_mov_b32 m0, s49
	s_nop 0
	global_load_lds_dwordx4 v[136:137], off
	v_lshl_add_u64 v[136:137], s[50:51], 0, v[130:131]
	s_add_i32 m0, s49, 0x2000
	s_nop 0
	global_load_lds_dwordx4 v[136:137], off
	s_waitcnt vmcnt(6)
	s_barrier
	s_setprio 1
	v_mfma_f32_16x16x32_f16 v[54:57], v[198:201], v[166:169], v[54:57]
	v_mfma_f32_16x16x32_f16 v[50:53], v[206:209], v[166:169], v[50:53]
	v_mfma_f32_16x16x32_f16 v[38:41], v[198:201], v[174:177], v[38:41]
	v_mfma_f32_16x16x32_f16 v[34:37], v[206:209], v[174:177], v[34:37]
	v_mfma_f32_16x16x32_f16 v[22:25], v[198:201], v[182:185], v[22:25]
	v_mfma_f32_16x16x32_f16 v[18:21], v[206:209], v[182:185], v[18:21]
	v_mfma_f32_16x16x32_f16 v[6:9], v[198:201], v[190:193], v[6:9]
	v_mfma_f32_16x16x32_f16 v[2:5], v[206:209], v[190:193], v[2:5]
	v_mfma_f32_16x16x32_f16 v[54:57], v[202:205], v[170:173], v[54:57]
	v_mfma_f32_16x16x32_f16 v[50:53], v[210:213], v[170:173], v[50:53]
	v_mfma_f32_16x16x32_f16 v[38:41], v[202:205], v[178:181], v[38:41]
	v_mfma_f32_16x16x32_f16 v[34:37], v[210:213], v[178:181], v[34:37]
	v_mfma_f32_16x16x32_f16 v[22:25], v[202:205], v[186:189], v[22:25]
	v_mfma_f32_16x16x32_f16 v[18:21], v[210:213], v[186:189], v[18:21]
	v_mfma_f32_16x16x32_f16 v[6:9], v[202:205], v[194:197], v[6:9]
	v_mfma_f32_16x16x32_f16 v[2:5], v[210:213], v[194:197], v[2:5]
	s_setprio 0
	s_add_i32 s49, 0, 0x18000
	v_add_u32_e32 v148, s49, v155
	s_barrier
	ds_read_b128 v[136:139], v148
	ds_read_b128 v[140:143], v148 offset:1024
	ds_read_b128 v[144:147], v148 offset:2048
	ds_read_b128 v[148:151], v148 offset:3072
	s_add_u32 s24, s24, 0x40000
	s_addc_u32 s25, s25, 0
	s_mov_b32 m0, s37
	v_lshl_add_u64 v[198:199], s[24:25], 0, v[0:1]
	ds_read_b128 v[166:169], v164 offset:32768
	ds_read_b128 v[170:173], v164 offset:33792
	ds_read_b128 v[174:177], v164 offset:34816
	ds_read_b128 v[178:181], v164 offset:35840
	ds_read_b128 v[182:185], v164 offset:36864
	ds_read_b128 v[186:189], v164 offset:37888
	ds_read_b128 v[190:193], v164 offset:38912
	ds_read_b128 v[194:197], v164 offset:39936
	global_load_lds_dwordx4 v[198:199], off
	v_lshl_add_u64 v[198:199], s[24:25], 0, v[130:131]
	s_mov_b32 m0, s38
	s_nop 0
	global_load_lds_dwordx4 v[198:199], off
	s_waitcnt lgkmcnt(8)
	s_barrier
	s_waitcnt lgkmcnt(0)
	s_setprio 1
	s_waitcnt lgkmcnt(0)
	v_mfma_f32_16x16x32_f16 v[126:129], v[136:139], v[166:169], v[126:129]
	v_mfma_f32_16x16x32_f16 v[122:125], v[144:147], v[166:169], v[122:125]
	v_mfma_f32_16x16x32_f16 v[110:113], v[136:139], v[174:177], v[110:113]
	v_mfma_f32_16x16x32_f16 v[106:109], v[144:147], v[174:177], v[106:109]
	v_mfma_f32_16x16x32_f16 v[94:97], v[136:139], v[182:185], v[94:97]
	v_mfma_f32_16x16x32_f16 v[90:93], v[144:147], v[182:185], v[90:93]
	v_mfma_f32_16x16x32_f16 v[78:81], v[136:139], v[190:193], v[78:81]
	v_mfma_f32_16x16x32_f16 v[74:77], v[144:147], v[190:193], v[74:77]
	v_mfma_f32_16x16x32_f16 v[126:129], v[140:143], v[170:173], v[126:129]
	v_mfma_f32_16x16x32_f16 v[122:125], v[148:151], v[170:173], v[122:125]
	v_mfma_f32_16x16x32_f16 v[110:113], v[140:143], v[178:181], v[110:113]
	v_mfma_f32_16x16x32_f16 v[106:109], v[148:151], v[178:181], v[106:109]
	v_mfma_f32_16x16x32_f16 v[94:97], v[140:143], v[186:189], v[94:97]
	v_mfma_f32_16x16x32_f16 v[90:93], v[148:151], v[186:189], v[90:93]
	v_mfma_f32_16x16x32_f16 v[78:81], v[140:143], v[194:197], v[78:81]
	v_mfma_f32_16x16x32_f16 v[74:77], v[148:151], v[194:197], v[74:77]
	s_setprio 0
	s_barrier
	s_add_i32 s24, 0, 0x1c000
	s_add_i32 s25, s49, s34
	v_add_u32_e32 v165, s24, v155
	v_lshl_add_u64 v[152:153], v[152:153], 0, s[74:75]
	s_mov_b32 m0, s25
	ds_read_b128 v[198:201], v165
	ds_read_b128 v[202:205], v165 offset:1024
	ds_read_b128 v[206:209], v165 offset:2048
	ds_read_b128 v[210:213], v165 offset:3072
	global_load_lds_dwordx4 v[152:153], off
	v_lshl_add_u64 v[152:153], v[214:215], 0, s[74:75]
	s_add_i32 m0, s25, 0x2000
	s_nop 0
	global_load_lds_dwordx4 v[152:153], off
	s_barrier
	s_waitcnt lgkmcnt(0)
	s_setprio 1
	s_waitcnt lgkmcnt(0)
	v_mfma_f32_16x16x32_f16 v[118:121], v[198:201], v[166:169], v[118:121]
	v_mfma_f32_16x16x32_f16 v[114:117], v[206:209], v[166:169], v[114:117]
	v_mfma_f32_16x16x32_f16 v[102:105], v[198:201], v[174:177], v[102:105]
	v_mfma_f32_16x16x32_f16 v[98:101], v[206:209], v[174:177], v[98:101]
	v_mfma_f32_16x16x32_f16 v[86:89], v[198:201], v[182:185], v[86:89]
	v_mfma_f32_16x16x32_f16 v[82:85], v[206:209], v[182:185], v[82:85]
	v_mfma_f32_16x16x32_f16 v[70:73], v[198:201], v[190:193], v[70:73]
	v_mfma_f32_16x16x32_f16 v[66:69], v[206:209], v[190:193], v[66:69]
	v_mfma_f32_16x16x32_f16 v[118:121], v[202:205], v[170:173], v[118:121]
	v_mfma_f32_16x16x32_f16 v[114:117], v[210:213], v[170:173], v[114:117]
	v_mfma_f32_16x16x32_f16 v[102:105], v[202:205], v[178:181], v[102:105]
	v_mfma_f32_16x16x32_f16 v[98:101], v[210:213], v[178:181], v[98:101]
	v_mfma_f32_16x16x32_f16 v[86:89], v[202:205], v[186:189], v[86:89]
	v_mfma_f32_16x16x32_f16 v[82:85], v[210:213], v[186:189], v[82:85]
	v_mfma_f32_16x16x32_f16 v[70:73], v[202:205], v[194:197], v[70:73]
	v_mfma_f32_16x16x32_f16 v[66:69], v[210:213], v[194:197], v[66:69]
	s_setprio 0
	s_mov_b32 m0, s39
	v_lshl_add_u64 v[152:153], v[228:229], 0, s[74:75]
	s_barrier
	ds_read_b128 v[166:169], v164 offset:49152
	ds_read_b128 v[170:173], v164 offset:50176
	ds_read_b128 v[174:177], v164 offset:51200
	ds_read_b128 v[178:181], v164 offset:52224
	ds_read_b128 v[182:185], v164 offset:53248
	ds_read_b128 v[186:189], v164 offset:54272
	ds_read_b128 v[190:193], v164 offset:55296
	ds_read_b128 v[194:197], v164 offset:56320
	global_load_lds_dwordx4 v[152:153], off
	v_lshl_add_u64 v[152:153], v[230:231], 0, s[74:75]
	s_mov_b32 m0, s40
	s_nop 0
	global_load_lds_dwordx4 v[152:153], off
	s_barrier
; #define PG8_WAIT_V(n) asm volatile("s_waitcnt vmcnt(" #n ")" ::: "memory")
; #define PG8_WAIT_L(n) asm volatile("s_waitcnt lgkmcnt(" #n ")" ::: "memory")
; #define PG8_BAR __builtin_amdgcn_s_barrier()
; template <class Epi>
; __device__ __forceinline__ void gemm_phase(LAS unsigned char* lds, const Gemm g, const StaticOrder& S, const Epi& E, const int wid_s) {
;     ...
;             PG8_BAR; PG8_WAIT_L(0); PG8_MMA(1, 0, At, B0); PG8_BAR; PG8_SCHED;
;             PG8_STAGE(PG8_SB(1, 1), b3 + hstepB, voffB);
;             PG8_WAIT_V(6); PG8_BAR; PG8_MMA(1, 1, At, B1); PG8_BAR;
;     __device__ __forceinline__ void operator()(const f32x4 (&acc)[2][2][4][2], const Unit& u, int wr, int wc, int fr, int fq) const {
;         const int row0 = u.pm * BM + wr * 64 + fr, col0 = u.pn * BM + wc * 32 + 4 * fq;
;         h16x4 hin[2][2], hnx[2][2];
; #pragma unroll
;         for (int bj = 0; bj < 2; ++bj)
; #pragma unroll
;             for (int n = 0; n < 2; ++n) hin[bj][n] = *(const h16x4*)(HB + (size_t)row0 * D + col0 + bj * HALF + n * 16);
; #pragma unroll
;         for (int g = 0; g < 8; ++g) {
;             const int ai = g >> 2, m = g & 3;
;             const int r = row0 + ai * HALF + m * 16; float ss = 0.f;
;             if (g < 7) { const int rn = row0 + ((g + 1) >> 2) * HALF + ((g + 1) & 3) * 16;
; #pragma unroll
;                 for (int bj = 0; bj < 2; ++bj)
; #pragma unroll
;                     for (int n = 0; n < 2; ++n) hnx[bj][n] = *(const h16x4*)(HB + (size_t)rn * D + col0 + bj * HALF + n * 16); }
; #pragma unroll
;             for (int bj = 0; bj < 2; ++bj)
; #pragma unroll
;                 for (int n = 0; n < 2; ++n) {
;                     const size_t o = (size_t)r * D + col0 + bj * HALF + n * 16;
;                     f32x4 hv; hv[0] = (float)hin[bj][n][0]; hv[1] = (float)hin[bj][n][1]; hv[2] = (float)hin[bj][n][2]; hv[3] = (float)hin[bj][n][3];
;                     hv += acc[ai][bj][m][n];
;                     ss += hv[0] * hv[0] + hv[1] * hv[1] + hv[2] * hv[2] + hv[3] * hv[3];
;                     if (OUT != nullptr) *(f32x4*)(OUT + o) = hv;
;                     else { h16x4 hh; hh[0] = (h16)hv[0]; hh[1] = (h16)hv[1]; hh[2] = (h16)hv[2]; hh[3] = (h16)hv[3]; *(h16x4*)(HB + o) = hh; }
;                 }
;             ss += __shfl_xor(ss, 16); ss += __shfl_xor(ss, 32);
;             if (fq == 0) atomicAdd(rsq_next + r, ss);
	s_waitcnt lgkmcnt(0)
	s_setprio 1
	s_waitcnt lgkmcnt(0)
	v_mfma_f32_16x16x32_f16 v[62:65], v[136:139], v[166:169], v[62:65]
	v_mfma_f32_16x16x32_f16 v[58:61], v[144:147], v[166:169], v[58:61]
	v_mfma_f32_16x16x32_f16 v[46:49], v[136:139], v[174:177], v[46:49]
	v_mfma_f32_16x16x32_f16 v[42:45], v[144:147], v[174:177], v[42:45]
	v_mfma_f32_16x16x32_f16 v[30:33], v[136:139], v[182:185], v[30:33]
	v_mfma_f32_16x16x32_f16 v[26:29], v[144:147], v[182:185], v[26:29]
	v_mfma_f32_16x16x32_f16 v[14:17], v[136:139], v[190:193], v[14:17]
	v_mfma_f32_16x16x32_f16 v[10:13], v[144:147], v[190:193], v[10:13]
	v_mfma_f32_16x16x32_f16 v[62:65], v[140:143], v[170:173], v[62:65]
	v_mfma_f32_16x16x32_f16 v[58:61], v[148:151], v[170:173], v[58:61]
	v_mfma_f32_16x16x32_f16 v[46:49], v[140:143], v[178:181], v[46:49]
	v_mfma_f32_16x16x32_f16 v[42:45], v[148:151], v[178:181], v[42:45]
	v_mfma_f32_16x16x32_f16 v[30:33], v[140:143], v[186:189], v[30:33]
	v_mfma_f32_16x16x32_f16 v[26:29], v[148:151], v[186:189], v[26:29]
	v_mfma_f32_16x16x32_f16 v[14:17], v[140:143], v[194:197], v[14:17]
	v_mfma_f32_16x16x32_f16 v[10:13], v[148:151], v[194:197], v[10:13]
	s_setprio 0
	s_barrier
	s_add_u32 s22, s22, 0x40080
	s_addc_u32 s23, s23, 0
	s_add_i32 s24, s24, s34
	v_lshl_add_u64 v[136:137], s[22:23], 0, v[0:1]
	s_mov_b32 m0, s24
	s_nop 0
	global_load_lds_dwordx4 v[136:137], off
	v_lshl_add_u64 v[136:137], s[22:23], 0, v[130:131]
	s_add_i32 m0, s24, 0x2000
	s_nop 0
	global_load_lds_dwordx4 v[136:137], off
	s_waitcnt vmcnt(6)
	s_barrier
	s_setprio 1
	v_mfma_f32_16x16x32_f16 v[54:57], v[198:201], v[166:169], v[54:57]
	v_mfma_f32_16x16x32_f16 v[50:53], v[206:209], v[166:169], v[50:53]
	v_mfma_f32_16x16x32_f16 v[38:41], v[198:201], v[174:177], v[38:41]
	v_mfma_f32_16x16x32_f16 v[34:37], v[206:209], v[174:177], v[34:37]
	v_mfma_f32_16x16x32_f16 v[22:25], v[198:201], v[182:185], v[22:25]
	v_mfma_f32_16x16x32_f16 v[18:21], v[206:209], v[182:185], v[18:21]
	v_mfma_f32_16x16x32_f16 v[6:9], v[198:201], v[190:193], v[6:9]
	v_mfma_f32_16x16x32_f16 v[2:5], v[206:209], v[190:193], v[2:5]
	v_mfma_f32_16x16x32_f16 v[54:57], v[202:205], v[170:173], v[54:57]
	v_mfma_f32_16x16x32_f16 v[50:53], v[210:213], v[170:173], v[50:53]
	v_mfma_f32_16x16x32_f16 v[38:41], v[202:205], v[178:181], v[38:41]
	v_mfma_f32_16x16x32_f16 v[34:37], v[210:213], v[178:181], v[34:37]
	v_mfma_f32_16x16x32_f16 v[22:25], v[202:205], v[186:189], v[22:25]
	v_mfma_f32_16x16x32_f16 v[18:21], v[210:213], v[186:189], v[18:21]
	v_mfma_f32_16x16x32_f16 v[6:9], v[202:205], v[194:197], v[6:9]
	v_mfma_f32_16x16x32_f16 v[2:5], v[210:213], v[194:197], v[2:5]
	s_setprio 0
	s_add_i32 s48, s48, 2
	s_add_u32 s4, s4, 0x100
	s_addc_u32 s5, s5, 0
	s_add_u32 s46, s46, 0x100
	s_addc_u32 s47, s47, 0
	s_cmp_gt_u32 s48, 13
	s_barrier
	s_cbranch_scc0 .LBB0_1372
	s_cmpk_gt_u32 s27, 0xff
	s_cbranch_scc1 .Lalign_evout_a
	s_barrier
.Lalign_evout_a:
	v_lshl_add_u32 v138, s43, 8, v154
	v_lshl_or_b32 v136, s42, 8, v163
	v_ashrrev_i32_e32 v139, 31, v138
	v_lshlrev_b64 v[140:141], 11, v[138:139]
	v_ashrrev_i32_e32 v137, 31, v136
	v_lshl_add_u64 v[140:141], s[10:11], 0, v[140:141]
	v_lshlrev_b64 v[142:143], 1, v[136:137]
	v_lshl_add_u64 v[152:153], v[140:141], 0, v[142:143]
	global_load_dwordx2 v[166:167], v[152:153], off
	global_load_dwordx2 v[168:169], v[152:153], off offset:32
	global_load_dwordx2 v[170:171], v[152:153], off offset:256
	global_load_dwordx2 v[172:173], v[152:153], off offset:288
	v_or_b32_e32 v140, 16, v138
	v_ashrrev_i32_e32 v141, 31, v140
	v_lshlrev_b64 v[144:145], 11, v[140:141]
	v_lshl_add_u64 v[144:145], s[10:11], 0, v[144:145]
	v_lshl_add_u64 v[142:143], v[144:145], 0, v[142:143]
	global_load_dwordx2 v[150:151], v[142:143], off
	global_load_dwordx2 v[148:149], v[142:143], off offset:32
	global_load_dwordx2 v[146:147], v[142:143], off offset:256
	global_load_dwordx2 v[144:145], v[142:143], off offset:288
	s_waitcnt vmcnt(0)
	v_cvt_f32_f16_e32 v174, v166
	v_cvt_f32_f16_sdwa v175, v166 dst_sel:DWORD dst_unused:UNUSED_PAD src0_sel:WORD_1
	v_cvt_f32_f16_e32 v166, v167
	v_cvt_f32_f16_sdwa v167, v167 dst_sel:DWORD dst_unused:UNUSED_PAD src0_sel:WORD_1
	v_pk_add_f32 v[126:127], v[126:127], v[174:175]
	s_nop 0
	v_mul_f32_e32 v165, v127, v127
	v_pk_add_f32 v[128:129], v[128:129], v[166:167]
	v_fmac_f32_e32 v165, v126, v126
	v_fmac_f32_e32 v165, v128, v128
	v_fmac_f32_e32 v165, v129, v129
	v_cvt_pk_f16_f32 v129, v128, v129
	v_cvt_pk_f16_f32 v128, v126, v127
	v_cvt_f32_f16_e32 v126, v168
	v_cvt_f32_f16_sdwa v127, v168 dst_sel:DWORD dst_unused:UNUSED_PAD src0_sel:WORD_1
	global_store_dwordx2 v[152:153], v[128:129], off
	v_cvt_f32_f16_e32 v128, v169
	v_cvt_f32_f16_sdwa v129, v169 dst_sel:DWORD dst_unused:UNUSED_PAD src0_sel:WORD_1
	v_pk_add_f32 v[122:123], v[122:123], v[126:127]
	v_pk_add_f32 v[124:125], v[124:125], v[128:129]
	v_mul_f32_e32 v126, v123, v123
	v_fmac_f32_e32 v126, v122, v122
	v_fmac_f32_e32 v126, v124, v124
	v_fmac_f32_e32 v126, v125, v125
	v_cvt_pk_f16_f32 v125, v124, v125
	v_cvt_pk_f16_f32 v124, v122, v123
	v_cvt_f32_f16_e32 v122, v170
	v_cvt_f32_f16_sdwa v123, v170 dst_sel:DWORD dst_unused:UNUSED_PAD src0_sel:WORD_1
	global_store_dwordx2 v[152:153], v[124:125], off offset:32
	v_cvt_f32_f16_e32 v124, v171
	v_cvt_f32_f16_sdwa v125, v171 dst_sel:DWORD dst_unused:UNUSED_PAD src0_sel:WORD_1
	v_pk_add_f32 v[118:119], v[118:119], v[122:123]
	v_add_f32_e32 v126, v165, v126
	v_mul_f32_e32 v122, v119, v119
	v_pk_add_f32 v[120:121], v[120:121], v[124:125]
	v_fmac_f32_e32 v122, v118, v118
	v_fmac_f32_e32 v122, v120, v120
	v_fmac_f32_e32 v122, v121, v121
	v_cvt_pk_f16_f32 v121, v120, v121
	v_cvt_pk_f16_f32 v120, v118, v119
	v_cvt_f32_f16_e32 v118, v172
	v_cvt_f32_f16_sdwa v119, v172 dst_sel:DWORD dst_unused:UNUSED_PAD src0_sel:WORD_1
	global_store_dwordx2 v[152:153], v[120:121], off offset:256
	v_cvt_f32_f16_e32 v120, v173
	v_cvt_f32_f16_sdwa v121, v173 dst_sel:DWORD dst_unused:UNUSED_PAD src0_sel:WORD_1
	v_pk_add_f32 v[114:115], v[114:115], v[118:119]
	v_add_f32_e32 v122, v126, v122
	v_mul_f32_e32 v118, v115, v115
	v_pk_add_f32 v[116:117], v[116:117], v[120:121]
	v_fmac_f32_e32 v118, v114, v114
	v_fmac_f32_e32 v118, v116, v116
	v_fmac_f32_e32 v118, v117, v117
	v_add_f32_e32 v118, v122, v118
	v_cvt_pk_f16_f32 v117, v116, v117
	v_cvt_pk_f16_f32 v116, v114, v115
	ds_bpermute_b32 v114, v161, v118
	global_store_dwordx2 v[152:153], v[116:117], off offset:288
	s_waitcnt lgkmcnt(0)
	v_add_f32_e32 v114, v118, v114
	ds_bpermute_b32 v115, v162, v114
	s_and_saveexec_b64 s[4:5], s[6:7]
	s_cbranch_execz .LBB0_1375
	v_lshl_add_u64 v[116:117], v[138:139], 2, s[12:13]
	s_waitcnt lgkmcnt(0)
	v_add_f32_e32 v114, v114, v115
	global_atomic_add_f32 v[116:117], v114, off

; #define LAS __attribute__((address_space(3)))
; __device__ __forceinline__ float silu_f(float x) { return x * __builtin_amdgcn_rcpf(1.f + __expf(-x)); }
;     __device__ __forceinline__ void operator()(const f32x4 (&acc_c)[2][2][4][2], const Unit& u, int wr, int wc, int fr, int fq) const {
;     ...
;             for (int ai = 0; ai < 2; ++ai) {
;                 f32x4 xpg = {0.f, 0.f, 0.f, 0.f}, xpv = {0.f, 0.f, 0.f, 0.f};
;                 const bool top = (ai == 0 && wr == 0);
;                 if (!top && fr >= 14) { const int ps = (wr == 1) ? ((ai * 2) * 4 + wc) : (((ai - 1) * 2 + 1) * 4 + wc);
;                     xpg = *(const LAS f32x4*)(xch + ps * 128 + (fr - 14) * 64 + 8 * fq + 4 * n); xpv = *(const LAS f32x4*)(xch + ps * 128 + (fr - 14) * 64 + 32 + 8 * fq + 4 * n); }
; #pragma unroll
;                 for (int m = 0; m < 4; ++m) {
;                     const f32x4 cg = acc[ai][0][m][n], cv = acc[ai][1][m][n];
;                     const f32x4 pg = m ? acc[ai][0][m - 1][n] : xpg, pv = m ? acc[ai][1][m - 1][n] : xpv;
;                     h16x4 o;
; #pragma unroll
;                     for (int e = 0; e < 4; ++e) {
;                         const float g1 = dppmov<0x111>(dppmov<0x121>(0.f, pg[e]), cg[e]), g2 = dppmov<0x112>(dppmov<0x122>(0.f, pg[e]), cg[e]);
;                         const float v1 = dppmov<0x111>(dppmov<0x121>(0.f, pv[e]), cv[e]), v2 = dppmov<0x112>(dppmov<0x122>(0.f, pv[e]), cv[e]);
;                         const float gate = wg[0][e] * g2 + wg[1][e] * g1 + wg[2][e] * cg[e] + bg[e];
;                         const float val = wv[0][e] * v2 + wv[1][e] * v1 + wv[2][e] * cv[e] + bv[e];
;                         o[e] = (h16)(silu_f(gate) * val);
;                     }
;                     *(h16x4*)(act + (size_t)(row0 + ai * HALF + m * 16) * FF + ch0 + 4 * n) = o;
.LBB0_1431:
	s_or_b64 exec, exec, s[4:5]
	v_mov_b32_e32 v139, v138
	v_mov_b32_e32 v38, v138
	v_mov_b32_e32 v39, v138
	v_mov_b32_e32 v141, v140
	v_pk_mul_f32 v[24:25], v[24:25], v[38:39]
	v_pk_mul_f32 v[40:41], v[22:23], v[138:139]
	v_pk_mul_f32 v[22:23], v[12:13], v[38:39]
	v_pk_mul_f32 v[38:39], v[10:11], v[138:139]
	v_mov_b32_e32 v10, v140
	v_mov_b32_e32 v11, v140
	v_mov_b32_e32 v42, v142
	v_mov_b32_e32 v43, v142
	v_mov_b32_e32 v143, v142
	v_pk_mul_f32 v[12:13], v[20:21], v[10:11]
	v_pk_mul_f32 v[20:21], v[18:19], v[140:141]
	v_pk_mul_f32 v[18:19], v[6:7], v[140:141]
	v_pk_mul_f32 v[6:7], v[16:17], v[42:43]
	v_mov_b32_e32 v16, v1
	v_mov_b32_e32 v17, v1
	v_pk_mul_f32 v[10:11], v[8:9], v[10:11]
	v_pk_mul_f32 v[8:9], v[14:15], v[142:143]
	v_mov_b32_e32 v14, v1
	s_waitcnt lgkmcnt(1)
	v_mov_b32_dpp v16, v90 row_ror:2 row_mask:0xf bank_mask:0xf
	v_mov_b32_e32 v15, v1
	v_mov_b32_dpp v17, v91 row_ror:2 row_mask:0xf bank_mask:0xf
	v_mov_b32_dpp v14, v90 row_ror:1 row_mask:0xf bank_mask:0xf
	v_mov_b32_dpp v16, v40 row_shr:2 row_mask:0xf bank_mask:0xf
	v_mov_b32_dpp v15, v91 row_ror:1 row_mask:0xf bank_mask:0xf
	v_mov_b32_dpp v17, v41 row_shr:2 row_mask:0xf bank_mask:0xf
	v_mov_b32_dpp v14, v40 row_shr:1 row_mask:0xf bank_mask:0xf
	v_mov_b32_dpp v15, v41 row_shr:1 row_mask:0xf bank_mask:0xf
	v_pk_mul_f32 v[16:17], v[58:59], v[16:17]
	v_mov_b32_e32 v44, v1
	v_pk_fma_f32 v[14:15], v[66:67], v[14:15], v[16:17]
	v_mov_b32_e32 v45, v1
	v_pk_fma_f32 v[14:15], v[40:41], v[74:75], v[14:15]
	v_pk_mul_f32 v[4:5], v[4:5], v[42:43]
	v_pk_add_f32 v[14:15], v[82:83], v[14:15]
	v_mov_b32_e32 v42, v1
	v_mul_f32_e32 v0, 0xbfb8aa3b, v14
	v_exp_f32_e32 v0, v0
	s_waitcnt lgkmcnt(0)
	v_mov_b32_dpp v44, v34 row_ror:2 row_mask:0xf bank_mask:0xf
	v_mov_b32_e32 v43, v1
	v_mov_b32_dpp v45, v35 row_ror:2 row_mask:0xf bank_mask:0xf
	v_add_f32_e32 v0, 1.0, v0
	v_rcp_f32_e32 v16, v0
	v_mul_f32_e32 v0, 0xbfb8aa3b, v15
	v_exp_f32_e32 v0, v0
	v_mov_b32_dpp v42, v34 row_ror:1 row_mask:0xf bank_mask:0xf
	v_mov_b32_dpp v44, v38 row_shr:2 row_mask:0xf bank_mask:0xf
	v_mov_b32_dpp v43, v35 row_ror:1 row_mask:0xf bank_mask:0xf
	v_add_f32_e32 v0, 1.0, v0
	v_mov_b32_dpp v45, v39 row_shr:2 row_mask:0xf bank_mask:0xf
	v_rcp_f32_e32 v17, v0
	v_mov_b32_dpp v42, v38 row_shr:1 row_mask:0xf bank_mask:0xf
	v_mov_b32_dpp v43, v39 row_shr:1 row_mask:0xf bank_mask:0xf
	v_pk_mul_f32 v[34:35], v[62:63], v[44:45]
	v_pk_mul_f32 v[14:15], v[14:15], v[16:17]
	v_pk_fma_f32 v[34:35], v[70:71], v[42:43], v[34:35]
	v_mov_b32_e32 v16, v1
	v_pk_fma_f32 v[34:35], v[38:39], v[78:79], v[34:35]
	v_mov_b32_e32 v17, v1
	v_pk_add_f32 v[34:35], v[86:87], v[34:35]
	v_mov_b32_dpp v16, v92 row_ror:1 row_mask:0xf bank_mask:0xf
	v_pk_mul_f32 v[14:15], v[34:35], v[14:15]
	v_mov_b32_e32 v34, v1
	v_mov_b32_e32 v35, v1
	v_mov_b32_dpp v17, v93 row_ror:1 row_mask:0xf bank_mask:0xf
	v_mov_b32_dpp v34, v92 row_ror:2 row_mask:0xf bank_mask:0xf
	v_mov_b32_dpp v35, v93 row_ror:2 row_mask:0xf bank_mask:0xf
	v_mov_b32_dpp v16, v24 row_shr:1 row_mask:0xf bank_mask:0xf
	v_mov_b32_dpp v34, v24 row_shr:2 row_mask:0xf bank_mask:0xf
	v_mov_b32_dpp v35, v25 row_shr:2 row_mask:0xf bank_mask:0xf
	v_mov_b32_dpp v17, v25 row_shr:1 row_mask:0xf bank_mask:0xf
	v_pk_mul_f32 v[34:35], v[60:61], v[34:35]
	v_mov_b32_e32 v44, v1
	v_pk_fma_f32 v[16:17], v[68:69], v[16:17], v[34:35]
	v_mov_b32_e32 v45, v1
	v_pk_fma_f32 v[16:17], v[24:25], v[76:77], v[16:17]
	v_mov_b32_e32 v42, v1
	v_pk_add_f32 v[16:17], v[84:85], v[16:17]
	v_mov_b32_dpp v44, v36 row_ror:2 row_mask:0xf bank_mask:0xf
	v_mul_f32_e32 v0, 0xbfb8aa3b, v16
	v_exp_f32_e32 v0, v0
	v_mov_b32_e32 v43, v1
	v_mov_b32_dpp v45, v37 row_ror:2 row_mask:0xf bank_mask:0xf
	v_mov_b32_dpp v42, v36 row_ror:1 row_mask:0xf bank_mask:0xf
	v_add_f32_e32 v0, 1.0, v0
	v_rcp_f32_e32 v34, v0
	v_mul_f32_e32 v0, 0xbfb8aa3b, v17
	v_exp_f32_e32 v0, v0
	v_mov_b32_dpp v44, v22 row_shr:2 row_mask:0xf bank_mask:0xf
	v_mov_b32_dpp v43, v37 row_ror:1 row_mask:0xf bank_mask:0xf
	v_mov_b32_dpp v45, v23 row_shr:2 row_mask:0xf bank_mask:0xf
	v_add_f32_e32 v0, 1.0, v0
	v_rcp_f32_e32 v35, v0
	v_mov_b32_dpp v42, v22 row_shr:1 row_mask:0xf bank_mask:0xf
	v_mov_b32_dpp v43, v23 row_shr:1 row_mask:0xf bank_mask:0xf
	v_pk_mul_f32 v[36:37], v[64:65], v[44:45]
	v_pk_mul_f32 v[16:17], v[16:17], v[34:35]
	v_pk_fma_f32 v[36:37], v[72:73], v[42:43], v[36:37]
	v_cvt_pk_f16_f32 v14, v14, v15
	v_pk_fma_f32 v[36:37], v[22:23], v[80:81], v[36:37]
	v_mov_b32_e32 v34, v1
	v_pk_add_f32 v[36:37], v[88:89], v[36:37]
	v_mov_b32_e32 v35, v1
	v_pk_mul_f32 v[16:17], v[36:37], v[16:17]
	v_mov_b32_e32 v36, v1
	v_cvt_pk_f16_f32 v15, v16, v17
	v_mov_b32_e32 v16, v1
	v_mov_b32_e32 v17, v1
	global_store_dwordx2 v[126:127], v[14:15], off offset:8
	v_mov_b32_e32 v14, v1
	v_mov_b32_dpp v16, v40 row_ror:2 row_mask:0xf bank_mask:0xf
	v_mov_b32_e32 v15, v1
	v_mov_b32_dpp v17, v41 row_ror:2 row_mask:0xf bank_mask:0xf
	v_mov_b32_dpp v14, v40 row_ror:1 row_mask:0xf bank_mask:0xf
	v_mov_b32_dpp v16, v20 row_shr:2 row_mask:0xf bank_mask:0xf
	v_mov_b32_dpp v15, v41 row_ror:1 row_mask:0xf bank_mask:0xf
	v_mov_b32_dpp v17, v21 row_shr:2 row_mask:0xf bank_mask:0xf
	v_mov_b32_dpp v14, v20 row_shr:1 row_mask:0xf bank_mask:0xf
	v_mov_b32_dpp v15, v21 row_shr:1 row_mask:0xf bank_mask:0xf
	v_pk_mul_f32 v[16:17], v[58:59], v[16:17]
	v_mov_b32_e32 v37, v1
	v_pk_fma_f32 v[14:15], v[66:67], v[14:15], v[16:17]
	v_mov_b32_dpp v36, v38 row_ror:2 row_mask:0xf bank_mask:0xf
	v_pk_fma_f32 v[14:15], v[20:21], v[74:75], v[14:15]
	v_mov_b32_dpp v37, v39 row_ror:2 row_mask:0xf bank_mask:0xf
	v_pk_add_f32 v[14:15], v[82:83], v[14:15]
	v_mov_b32_dpp v34, v38 row_ror:1 row_mask:0xf bank_mask:0xf
; #define LAS __attribute__((address_space(3)))
; __device__ __forceinline__ float silu_f(float x) { return x * __builtin_amdgcn_rcpf(1.f + __expf(-x)); }
;     __device__ __forceinline__ void operator()(const f32x4 (&acc_c)[2][2][4][2], const Unit& u, int wr, int wc, int fr, int fq) const {
;     ...
;             for (int ai = 0; ai < 2; ++ai) {
;                 f32x4 xpg = {0.f, 0.f, 0.f, 0.f}, xpv = {0.f, 0.f, 0.f, 0.f};
;                 const bool top = (ai == 0 && wr == 0);
;                 if (!top && fr >= 14) { const int ps = (wr == 1) ? ((ai * 2) * 4 + wc) : (((ai - 1) * 2 + 1) * 4 + wc);
;                     xpg = *(const LAS f32x4*)(xch + ps * 128 + (fr - 14) * 64 + 8 * fq + 4 * n); xpv = *(const LAS f32x4*)(xch + ps * 128 + (fr - 14) * 64 + 32 + 8 * fq + 4 * n); }
; #pragma unroll
;                 for (int m = 0; m < 4; ++m) {
;                     const f32x4 cg = acc[ai][0][m][n], cv = acc[ai][1][m][n];
;                     const f32x4 pg = m ? acc[ai][0][m - 1][n] : xpg, pv = m ? acc[ai][1][m - 1][n] : xpv;
;                     h16x4 o;
; #pragma unroll
;                     for (int e = 0; e < 4; ++e) {
;                         const float g1 = dppmov<0x111>(dppmov<0x121>(0.f, pg[e]), cg[e]), g2 = dppmov<0x112>(dppmov<0x122>(0.f, pg[e]), cg[e]);
;                         const float v1 = dppmov<0x111>(dppmov<0x121>(0.f, pv[e]), cv[e]), v2 = dppmov<0x112>(dppmov<0x122>(0.f, pv[e]), cv[e]);
;                         const float gate = wg[0][e] * g2 + wg[1][e] * g1 + wg[2][e] * cg[e] + bg[e];
;                         const float val = wv[0][e] * v2 + wv[1][e] * v1 + wv[2][e] * cv[e] + bv[e];
;                         o[e] = (h16)(silu_f(gate) * val);
;                     }
;                     *(h16x4*)(act + (size_t)(row0 + ai * HALF + m * 16) * FF + ch0 + 4 * n) = o;
	v_mul_f32_e32 v0, 0xbfb8aa3b, v14
	v_exp_f32_e32 v0, v0
	v_mov_b32_dpp v36, v18 row_shr:2 row_mask:0xf bank_mask:0xf
	v_mov_b32_dpp v35, v39 row_ror:1 row_mask:0xf bank_mask:0xf
	v_mov_b32_dpp v37, v19 row_shr:2 row_mask:0xf bank_mask:0xf
	v_add_f32_e32 v0, 1.0, v0
	v_rcp_f32_e32 v16, v0
	v_mul_f32_e32 v0, 0xbfb8aa3b, v15
	v_exp_f32_e32 v0, v0
	v_mov_b32_dpp v34, v18 row_shr:1 row_mask:0xf bank_mask:0xf
	v_mov_b32_dpp v35, v19 row_shr:1 row_mask:0xf bank_mask:0xf
	v_pk_mul_f32 v[36:37], v[62:63], v[36:37]
	v_add_f32_e32 v0, 1.0, v0
	v_rcp_f32_e32 v17, v0
	v_pk_fma_f32 v[34:35], v[70:71], v[34:35], v[36:37]
	v_mov_b32_e32 v36, v1
	v_pk_fma_f32 v[34:35], v[18:19], v[78:79], v[34:35]
	v_pk_mul_f32 v[14:15], v[14:15], v[16:17]
	v_pk_add_f32 v[34:35], v[86:87], v[34:35]
	v_mov_b32_e32 v16, v1
	v_pk_mul_f32 v[14:15], v[34:35], v[14:15]
	v_mov_b32_e32 v34, v1
	v_mov_b32_e32 v35, v1
	v_mov_b32_e32 v17, v1
	v_mov_b32_dpp v34, v24 row_ror:2 row_mask:0xf bank_mask:0xf
	v_mov_b32_dpp v35, v25 row_ror:2 row_mask:0xf bank_mask:0xf
	v_mov_b32_dpp v16, v24 row_ror:1 row_mask:0xf bank_mask:0xf
	v_mov_b32_dpp v34, v12 row_shr:2 row_mask:0xf bank_mask:0xf
	v_mov_b32_e32 v24, v1
	v_mov_b32_dpp v17, v25 row_ror:1 row_mask:0xf bank_mask:0xf
	v_mov_b32_dpp v35, v13 row_shr:2 row_mask:0xf bank_mask:0xf
	v_mov_b32_e32 v25, v1
	v_mov_b32_e32 v37, v1
	v_mov_b32_dpp v16, v12 row_shr:1 row_mask:0xf bank_mask:0xf
	v_mov_b32_dpp v24, v22 row_ror:1 row_mask:0xf bank_mask:0xf
	v_mov_b32_dpp v36, v22 row_ror:2 row_mask:0xf bank_mask:0xf
	v_mov_b32_dpp v17, v13 row_shr:1 row_mask:0xf bank_mask:0xf
	v_mov_b32_dpp v25, v23 row_ror:1 row_mask:0xf bank_mask:0xf
	v_mov_b32_dpp v37, v23 row_ror:2 row_mask:0xf bank_mask:0xf
	v_pk_mul_f32 v[22:23], v[60:61], v[34:35]
	v_mov_b32_dpp v36, v10 row_shr:2 row_mask:0xf bank_mask:0xf
	v_pk_fma_f32 v[16:17], v[68:69], v[16:17], v[22:23]
	v_mov_b32_dpp v37, v11 row_shr:2 row_mask:0xf bank_mask:0xf
	v_pk_fma_f32 v[16:17], v[12:13], v[76:77], v[16:17]
	v_mov_b32_dpp v24, v10 row_shr:1 row_mask:0xf bank_mask:0xf
	v_pk_add_f32 v[16:17], v[84:85], v[16:17]
	v_mov_b32_dpp v25, v11 row_shr:1 row_mask:0xf bank_mask:0xf
	v_mul_f32_e32 v0, 0xbfb8aa3b, v16
	v_exp_f32_e32 v0, v0
	v_pk_mul_f32 v[34:35], v[64:65], v[36:37]
	v_cvt_pk_f16_f32 v14, v14, v15
	v_pk_fma_f32 v[24:25], v[72:73], v[24:25], v[34:35]
	v_add_f32_e32 v0, 1.0, v0
	v_rcp_f32_e32 v22, v0
	v_mul_f32_e32 v0, 0xbfb8aa3b, v17
	v_exp_f32_e32 v0, v0
	v_pk_fma_f32 v[24:25], v[10:11], v[80:81], v[24:25]
	v_pk_mul_f32 v[2:3], v[2:3], v[142:143]
	v_pk_add_f32 v[24:25], v[88:89], v[24:25]
	v_add_f32_e32 v0, 1.0, v0
	v_rcp_f32_e32 v23, v0
	s_and_b64 vcc, exec, s[10:11]
	s_mov_b32 s72, s40
	s_mov_b32 s4, s42
	v_pk_mul_f32 v[16:17], v[16:17], v[22:23]
	v_mov_b32_e32 v22, v1
	v_pk_mul_f32 v[16:17], v[24:25], v[16:17]
	v_mov_b32_e32 v23, v1
	v_cvt_pk_f16_f32 v15, v16, v17
	v_mov_b32_e32 v16, v1
	v_mov_b32_e32 v17, v1
	global_store_dwordx2 v[124:125], v[14:15], off offset:8
	v_mov_b32_e32 v14, v1
	v_mov_b32_dpp v16, v20 row_ror:2 row_mask:0xf bank_mask:0xf
	v_mov_b32_e32 v15, v1
	v_mov_b32_dpp v17, v21 row_ror:2 row_mask:0xf bank_mask:0xf
	v_mov_b32_dpp v14, v20 row_ror:1 row_mask:0xf bank_mask:0xf
	v_mov_b32_dpp v16, v8 row_shr:2 row_mask:0xf bank_mask:0xf
	v_mov_b32_dpp v15, v21 row_ror:1 row_mask:0xf bank_mask:0xf
	v_mov_b32_dpp v17, v9 row_shr:2 row_mask:0xf bank_mask:0xf
	v_mov_b32_dpp v14, v8 row_shr:1 row_mask:0xf bank_mask:0xf
	v_mov_b32_dpp v15, v9 row_shr:1 row_mask:0xf bank_mask:0xf
	v_pk_mul_f32 v[16:17], v[58:59], v[16:17]
	v_mov_b32_e32 v20, v1
	v_pk_fma_f32 v[14:15], v[66:67], v[14:15], v[16:17]
	v_mov_b32_dpp v22, v18 row_ror:2 row_mask:0xf bank_mask:0xf
	v_pk_fma_f32 v[14:15], v[8:9], v[74:75], v[14:15]
	v_mov_b32_e32 v21, v1
	v_pk_add_f32 v[14:15], v[82:83], v[14:15]
	v_mov_b32_dpp v23, v19 row_ror:2 row_mask:0xf bank_mask:0xf
	v_mul_f32_e32 v0, 0xbfb8aa3b, v14
	v_exp_f32_e32 v0, v0
	v_mov_b32_dpp v20, v18 row_ror:1 row_mask:0xf bank_mask:0xf
	v_mov_b32_dpp v22, v2 row_shr:2 row_mask:0xf bank_mask:0xf
	v_mov_b32_dpp v21, v19 row_ror:1 row_mask:0xf bank_mask:0xf
	v_add_f32_e32 v0, 1.0, v0
	v_rcp_f32_e32 v16, v0
	v_mul_f32_e32 v0, 0xbfb8aa3b, v15
	v_exp_f32_e32 v0, v0
	v_mov_b32_dpp v23, v3 row_shr:2 row_mask:0xf bank_mask:0xf
	v_mov_b32_dpp v20, v2 row_shr:1 row_mask:0xf bank_mask:0xf
	v_mov_b32_dpp v21, v3 row_shr:1 row_mask:0xf bank_mask:0xf
	v_add_f32_e32 v0, 1.0, v0
	v_rcp_f32_e32 v17, v0
	v_pk_mul_f32 v[18:19], v[62:63], v[22:23]
	s_mov_b64 s[50:51], s[46:47]
	v_pk_fma_f32 v[18:19], v[70:71], v[20:21], v[18:19]
	v_pk_mul_f32 v[14:15], v[14:15], v[16:17]
	v_pk_fma_f32 v[18:19], v[2:3], v[78:79], v[18:19]
	v_mov_b32_e32 v16, v1
	v_pk_add_f32 v[18:19], v[86:87], v[18:19]
	v_mov_b32_e32 v17, v1
	v_pk_mul_f32 v[14:15], v[18:19], v[14:15]
	v_mov_b32_e32 v18, v1
	v_mov_b32_e32 v19, v1
	v_mov_b32_dpp v16, v12 row_ror:1 row_mask:0xf bank_mask:0xf
	v_mov_b32_dpp v18, v12 row_ror:2 row_mask:0xf bank_mask:0xf
	v_mov_b32_dpp v19, v13 row_ror:2 row_mask:0xf bank_mask:0xf
	v_mov_b32_e32 v12, v1
	v_mov_b32_dpp v18, v6 row_shr:2 row_mask:0xf bank_mask:0xf
	v_mov_b32_e32 v20, v1
	v_mov_b32_dpp v17, v13 row_ror:1 row_mask:0xf bank_mask:0xf
	v_mov_b32_dpp v19, v7 row_shr:2 row_mask:0xf bank_mask:0xf
	v_mov_b32_e32 v13, v1
; #define LAS __attribute__((address_space(3)))
; __device__ __forceinline__ float silu_f(float x) { return x * __builtin_amdgcn_rcpf(1.f + __expf(-x)); }
;     __device__ __forceinline__ void operator()(const f32x4 (&acc_c)[2][2][4][2], const Unit& u, int wr, int wc, int fr, int fq) const {
;     ...
;             for (int ai = 0; ai < 2; ++ai) {
;                 f32x4 xpg = {0.f, 0.f, 0.f, 0.f}, xpv = {0.f, 0.f, 0.f, 0.f};
;                 const bool top = (ai == 0 && wr == 0);
;                 if (!top && fr >= 14) { const int ps = (wr == 1) ? ((ai * 2) * 4 + wc) : (((ai - 1) * 2 + 1) * 4 + wc);
;                     xpg = *(const LAS f32x4*)(xch + ps * 128 + (fr - 14) * 64 + 8 * fq + 4 * n); xpv = *(const LAS f32x4*)(xch + ps * 128 + (fr - 14) * 64 + 32 + 8 * fq + 4 * n); }
; #pragma unroll
;                 for (int m = 0; m < 4; ++m) {
;                     const f32x4 cg = acc[ai][0][m][n], cv = acc[ai][1][m][n];
;                     const f32x4 pg = m ? acc[ai][0][m - 1][n] : xpg, pv = m ? acc[ai][1][m - 1][n] : xpv;
;                     h16x4 o;
; #pragma unroll
;                     for (int e = 0; e < 4; ++e) {
;                         const float g1 = dppmov<0x111>(dppmov<0x121>(0.f, pg[e]), cg[e]), g2 = dppmov<0x112>(dppmov<0x122>(0.f, pg[e]), cg[e]);
;                         const float v1 = dppmov<0x111>(dppmov<0x121>(0.f, pv[e]), cv[e]), v2 = dppmov<0x112>(dppmov<0x122>(0.f, pv[e]), cv[e]);
;                         const float gate = wg[0][e] * g2 + wg[1][e] * g1 + wg[2][e] * cg[e] + bg[e];
;                         const float val = wv[0][e] * v2 + wv[1][e] * v1 + wv[2][e] * cv[e] + bv[e];
;                         o[e] = (h16)(silu_f(gate) * val);
;                     }
;                     *(h16x4*)(act + (size_t)(row0 + ai * HALF + m * 16) * FF + ch0 + 4 * n) = o;
;                 }
;             }
	v_mov_b32_e32 v21, v1
	v_mov_b32_dpp v16, v6 row_shr:1 row_mask:0xf bank_mask:0xf
	v_mov_b32_dpp v12, v10 row_ror:1 row_mask:0xf bank_mask:0xf
	v_mov_b32_dpp v20, v10 row_ror:2 row_mask:0xf bank_mask:0xf
	v_mov_b32_dpp v17, v7 row_shr:1 row_mask:0xf bank_mask:0xf
	v_mov_b32_dpp v13, v11 row_ror:1 row_mask:0xf bank_mask:0xf
	v_mov_b32_dpp v21, v11 row_ror:2 row_mask:0xf bank_mask:0xf
	v_pk_mul_f32 v[10:11], v[60:61], v[18:19]
	v_mov_b32_dpp v20, v4 row_shr:2 row_mask:0xf bank_mask:0xf
	v_pk_fma_f32 v[10:11], v[68:69], v[16:17], v[10:11]
	v_mov_b32_dpp v21, v5 row_shr:2 row_mask:0xf bank_mask:0xf
	v_pk_fma_f32 v[10:11], v[6:7], v[76:77], v[10:11]
	v_mov_b32_dpp v12, v4 row_shr:1 row_mask:0xf bank_mask:0xf
	v_pk_add_f32 v[10:11], v[84:85], v[10:11]
	v_mov_b32_dpp v13, v5 row_shr:1 row_mask:0xf bank_mask:0xf
	v_mul_f32_e32 v0, 0xbfb8aa3b, v10
	v_exp_f32_e32 v0, v0
	v_pk_mul_f32 v[18:19], v[64:65], v[20:21]
	v_cvt_pk_f16_f32 v14, v14, v15
	v_pk_fma_f32 v[12:13], v[72:73], v[12:13], v[18:19]
	v_add_f32_e32 v0, 1.0, v0
	v_rcp_f32_e32 v16, v0
	v_mul_f32_e32 v0, 0xbfb8aa3b, v11
	v_exp_f32_e32 v0, v0
	v_pk_fma_f32 v[12:13], v[4:5], v[80:81], v[12:13]
	s_mov_b64 s[48:49], s[44:45]
	v_pk_add_f32 v[12:13], v[88:89], v[12:13]
	v_add_f32_e32 v0, 1.0, v0
	v_rcp_f32_e32 v17, v0
	s_nop 0
	v_pk_mul_f32 v[10:11], v[10:11], v[16:17]
	s_nop 0
	v_pk_mul_f32 v[10:11], v[12:13], v[10:11]
	v_mov_b32_e32 v12, v1
	v_mov_b32_e32 v13, v1
	v_cvt_pk_f16_f32 v15, v10, v11
	v_mov_b32_e32 v10, v1
	v_mov_b32_dpp v12, v8 row_ror:2 row_mask:0xf bank_mask:0xf
	v_mov_b32_e32 v11, v1
	v_mov_b32_dpp v13, v9 row_ror:2 row_mask:0xf bank_mask:0xf
	global_store_dwordx2 v[122:123], v[14:15], off offset:8
	v_mov_b32_dpp v10, v8 row_ror:1 row_mask:0xf bank_mask:0xf
	v_mov_b32_dpp v12, v26 row_shr:2 row_mask:0xf bank_mask:0xf
	v_mov_b32_e32 v8, v1
	v_mov_b32_e32 v14, v1
	v_mov_b32_dpp v11, v9 row_ror:1 row_mask:0xf bank_mask:0xf
	v_mov_b32_dpp v13, v27 row_shr:2 row_mask:0xf bank_mask:0xf
	v_mov_b32_e32 v9, v1
	v_mov_b32_e32 v15, v1
	v_mov_b32_dpp v10, v26 row_shr:1 row_mask:0xf bank_mask:0xf
	v_mov_b32_dpp v8, v2 row_ror:1 row_mask:0xf bank_mask:0xf
	v_mov_b32_dpp v14, v2 row_ror:2 row_mask:0xf bank_mask:0xf
	v_mov_b32_dpp v11, v27 row_shr:1 row_mask:0xf bank_mask:0xf
	v_mov_b32_dpp v9, v3 row_ror:1 row_mask:0xf bank_mask:0xf
	v_mov_b32_dpp v15, v3 row_ror:2 row_mask:0xf bank_mask:0xf
	v_pk_mul_f32 v[2:3], v[58:59], v[12:13]
	v_mov_b32_dpp v14, v30 row_shr:2 row_mask:0xf bank_mask:0xf
	v_pk_fma_f32 v[2:3], v[66:67], v[10:11], v[2:3]
	v_mov_b32_dpp v15, v31 row_shr:2 row_mask:0xf bank_mask:0xf
	v_pk_fma_f32 v[2:3], v[26:27], v[74:75], v[2:3]
	v_mov_b32_dpp v8, v30 row_shr:1 row_mask:0xf bank_mask:0xf
	v_pk_add_f32 v[2:3], v[82:83], v[2:3]
	v_mov_b32_dpp v9, v31 row_shr:1 row_mask:0xf bank_mask:0xf
	v_mul_f32_e32 v0, 0xbfb8aa3b, v2
	v_exp_f32_e32 v0, v0
	v_pk_mul_f32 v[12:13], v[62:63], v[14:15]
	v_add_f32_e32 v0, 1.0, v0
	v_rcp_f32_e32 v10, v0
	v_mul_f32_e32 v0, 0xbfb8aa3b, v3
	v_exp_f32_e32 v0, v0
	v_pk_fma_f32 v[8:9], v[70:71], v[8:9], v[12:13]
	v_mov_b32_e32 v12, v1
	v_pk_fma_f32 v[8:9], v[30:31], v[78:79], v[8:9]
	v_add_f32_e32 v0, 1.0, v0
	v_rcp_f32_e32 v11, v0
	v_pk_add_f32 v[8:9], v[86:87], v[8:9]
	v_mov_b32_e32 v13, v1
	v_mov_b32_dpp v12, v4 row_ror:2 row_mask:0xf bank_mask:0xf
	v_pk_mul_f32 v[2:3], v[2:3], v[10:11]
	v_mov_b32_e32 v10, v1
	v_mov_b32_e32 v11, v1
	v_pk_mul_f32 v[2:3], v[8:9], v[2:3]
	v_mov_b32_e32 v8, v1
	v_mov_b32_dpp v10, v6 row_ror:2 row_mask:0xf bank_mask:0xf
	v_mov_b32_e32 v9, v1
	v_mov_b32_dpp v11, v7 row_ror:2 row_mask:0xf bank_mask:0xf
	v_mov_b32_dpp v8, v6 row_ror:1 row_mask:0xf bank_mask:0xf
	v_mov_b32_dpp v10, v28 row_shr:2 row_mask:0xf bank_mask:0xf
	v_mov_b32_e32 v6, v1
	v_mov_b32_dpp v9, v7 row_ror:1 row_mask:0xf bank_mask:0xf
	v_mov_b32_dpp v11, v29 row_shr:2 row_mask:0xf bank_mask:0xf
	v_mov_b32_e32 v7, v1
	v_mov_b32_dpp v8, v28 row_shr:1 row_mask:0xf bank_mask:0xf
	v_mov_b32_dpp v6, v4 row_ror:1 row_mask:0xf bank_mask:0xf
	v_mov_b32_dpp v9, v29 row_shr:1 row_mask:0xf bank_mask:0xf
	v_mov_b32_dpp v7, v5 row_ror:1 row_mask:0xf bank_mask:0xf
	v_mov_b32_dpp v13, v5 row_ror:2 row_mask:0xf bank_mask:0xf
	v_pk_mul_f32 v[4:5], v[60:61], v[10:11]
	v_mov_b32_dpp v12, v32 row_shr:2 row_mask:0xf bank_mask:0xf
	v_pk_fma_f32 v[4:5], v[68:69], v[8:9], v[4:5]
	v_mov_b32_dpp v13, v33 row_shr:2 row_mask:0xf bank_mask:0xf
	v_pk_fma_f32 v[4:5], v[28:29], v[76:77], v[4:5]
	v_mov_b32_dpp v6, v32 row_shr:1 row_mask:0xf bank_mask:0xf
	v_pk_add_f32 v[4:5], v[84:85], v[4:5]
	v_mov_b32_dpp v7, v33 row_shr:1 row_mask:0xf bank_mask:0xf
	v_mul_f32_e32 v0, 0xbfb8aa3b, v4
	v_exp_f32_e32 v0, v0
	v_pk_mul_f32 v[10:11], v[64:65], v[12:13]
	v_cvt_pk_f16_f32 v2, v2, v3
	v_pk_fma_f32 v[6:7], v[72:73], v[6:7], v[10:11]
	v_add_f32_e32 v0, 1.0, v0
	v_rcp_f32_e32 v8, v0
	v_mul_f32_e32 v0, 0xbfb8aa3b, v5
	v_exp_f32_e32 v0, v0
	v_pk_fma_f32 v[6:7], v[32:33], v[80:81], v[6:7]
	v_add_f32_e32 v0, 1.0, v0
	v_rcp_f32_e32 v9, v0
	v_pk_add_f32 v[6:7], v[88:89], v[6:7]
	v_pk_mul_f32 v[4:5], v[4:5], v[8:9]
	s_nop 0
	v_pk_mul_f32 v[4:5], v[6:7], v[4:5]
	s_nop 0
	v_cvt_pk_f16_f32 v3, v4, v5
	global_store_dwordx2 v[100:101], v[2:3], off offset:8
	s_cmp_eq_u64 s[8:9], 0
	s_cbranch_scc0 .Lalign_up_b
	s_barrier

; #define PG8_STAGE(bufoff, gbase, voff) do { _Pragma("unroll") for (int _i = 0; _i < 2; ++_i) \
;         __builtin_amdgcn_global_load_lds((const unsigned*)((const char*)(gbase) + (voff)[_i]), (LAS unsigned*)(lds + (bufoff) + ldsw + _i * 8192), 16, 0, 0); } while (0)
; #define PG8_LDA(dst, b, h) do { _Pragma("unroll") for (int m = 0; m < 4; ++m) _Pragma("unroll") for (int k = 0; k < 2; ++k) dst[m][k] = *(const LAS h16x8*)(lds + PG8_SA(b, h) + aoff + m * 2048 + k * 1024); } while (0)
; #define PG8_LDB(dst, b, h) do { _Pragma("unroll") for (int n = 0; n < 2; ++n) _Pragma("unroll") for (int k = 0; k < 2; ++k) dst[n][k] = *(const LAS h16x8*)(lds + PG8_SB(b, h) + boff + n * 2048 + k * 1024); } while (0)
; #define PG8_WAIT_V(n) asm volatile("s_waitcnt vmcnt(" #n ")" ::: "memory")
; #define PG8_WAIT_L(n) asm volatile("s_waitcnt lgkmcnt(" #n ")" ::: "memory")
; #define PG8_BAR __builtin_amdgcn_s_barrier()
; #define PG8_SCHED __builtin_amdgcn_sched_barrier(0)
; template <class Epi>
; __device__ __forceinline__ void gemm_phase(LAS unsigned char* lds, const Gemm g, const StaticOrder& S, const Epi& E, const int wid_s) {
;     ...
;             PG8_LDB(B0, 0, 0); PG8_SCHED; PG8_LDA(At, 0, 0); PG8_STAGE(PG8_SA(1, 1), a1 + hstepA, voffA);
;             PG8_WAIT_L(8); PG8_BAR; PG8_WAIT_L(0); PG8_MMA(0, 0, At, B0); PG8_BAR; PG8_SCHED;
;             PG8_LDB(B1, 0, 1); PG8_STAGE(PG8_SB(0, 0), b2, voffB);
;             PG8_BAR; PG8_WAIT_L(0); PG8_MMA(0, 1, At, B1); PG8_BAR;
;             PG8_LDA(At, 0, 1); PG8_STAGE(PG8_SA(0, 0), a2, voffA);
;             PG8_BAR; PG8_WAIT_L(0); PG8_MMA(1, 0, At, B0); PG8_BAR; PG8_SCHED;
;             PG8_STAGE(PG8_SB(0, 1), b2 + hstepB, voffB);
;             PG8_WAIT_V(6); PG8_BAR; PG8_MMA(1, 1, At, B1); PG8_BAR;
;             PG8_LDB(B0, 1, 0); PG8_SCHED; PG8_LDA(At, 1, 0); PG8_STAGE(PG8_SA(0, 1), a2 + hstepA, voffA);
;             PG8_WAIT_L(8); PG8_BAR; PG8_WAIT_L(0); PG8_MMA(0, 0, At, B0); PG8_BAR; PG8_SCHED;
;             PG8_LDB(B1, 1, 1); PG8_STAGE(PG8_SB(1, 0), b3, voffB);
;             PG8_BAR; PG8_WAIT_L(0); PG8_MMA(0, 1, At, B1); PG8_BAR;
;             PG8_LDA(At, 1, 1); PG8_STAGE(PG8_SA(1, 0), a3, voffA);
;             PG8_BAR; PG8_WAIT_L(0); PG8_MMA(1, 0, At, B0); PG8_BAR; PG8_SCHED;
;             PG8_STAGE(PG8_SB(1, 1), b3 + hstepB, voffB);
;             PG8_WAIT_V(6); PG8_BAR; PG8_MMA(1, 1, At, B1); PG8_BAR;
.LBB0_1435:
	s_add_u32 s50, s48, 0xfffc0080
	s_addc_u32 s51, s49, -1
	s_add_i32 s83, 0, 0x10000
	v_add_u32_e32 v0, s83, v171
	ds_read_b128 v[114:117], v0
	ds_read_b128 v[118:121], v0 offset:1024
	ds_read_b128 v[138:141], v0 offset:2048
	ds_read_b128 v[142:145], v0 offset:3072
	s_cmp_eq_u32 s82, 12
	s_cselect_b32 s53, s5, s51
	s_cselect_b32 s52, s43, s50
	s_cselect_b32 s51, s41, s77
	s_cselect_b32 s50, s73, s76
	v_lshl_add_u64 v[154:155], s[48:49], 0, v[174:175]
	s_add_i32 m0, s64, 0xc000
	ds_read_b128 v[146:149], v240
	ds_read_b128 v[150:153], v240 offset:1024
	ds_read_b128 v[178:181], v240 offset:2048
	ds_read_b128 v[182:185], v240 offset:3072
	ds_read_b128 v[186:189], v240 offset:4096
	ds_read_b128 v[190:193], v240 offset:5120
	ds_read_b128 v[194:197], v240 offset:6144
	ds_read_b128 v[198:201], v240 offset:7168
	global_load_lds_dwordx4 v[154:155], off
	v_lshl_add_u64 v[154:155], s[48:49], 0, v[176:177]
	s_add_i32 m0, s64, 0xe000
	s_nop 0
	global_load_lds_dwordx4 v[154:155], off
	s_waitcnt lgkmcnt(8)
	s_barrier
	s_waitcnt lgkmcnt(0)
	s_setprio 1
	s_waitcnt lgkmcnt(0)
	v_mfma_f32_16x16x32_f16 v[102:105], v[114:117], v[146:149], v[102:105]
	v_mfma_f32_16x16x32_f16 v[98:101], v[138:141], v[146:149], v[98:101]
	v_mfma_f32_16x16x32_f16 v[134:137], v[114:117], v[178:181], v[134:137]
	v_mfma_f32_16x16x32_f16 v[46:49], v[138:141], v[178:181], v[46:49]
	v_mfma_f32_16x16x32_f16 v[130:133], v[114:117], v[186:189], v[130:133]
	v_mfma_f32_16x16x32_f16 v[42:45], v[138:141], v[186:189], v[42:45]
	v_mfma_f32_16x16x32_f16 v[110:113], v[114:117], v[194:197], v[110:113]
	v_mfma_f32_16x16x32_f16 v[54:57], v[138:141], v[194:197], v[54:57]
	v_mfma_f32_16x16x32_f16 v[102:105], v[118:121], v[150:153], v[102:105]
	v_mfma_f32_16x16x32_f16 v[98:101], v[142:145], v[150:153], v[98:101]
	v_mfma_f32_16x16x32_f16 v[134:137], v[118:121], v[182:185], v[134:137]
	v_mfma_f32_16x16x32_f16 v[46:49], v[142:145], v[182:185], v[46:49]
	v_mfma_f32_16x16x32_f16 v[130:133], v[118:121], v[190:193], v[130:133]
	v_mfma_f32_16x16x32_f16 v[42:45], v[142:145], v[190:193], v[42:45]
	v_mfma_f32_16x16x32_f16 v[110:113], v[118:121], v[198:201], v[110:113]
	v_mfma_f32_16x16x32_f16 v[54:57], v[142:145], v[198:201], v[54:57]
	s_setprio 0
	s_barrier
	s_add_i32 s86, 0, 0x14000
	s_add_i32 s83, s83, s63
	v_add_u32_e32 v0, s86, v171
	v_lshl_add_u64 v[154:155], s[50:51], 0, v[166:167]
	s_mov_b32 m0, s83
	ds_read_b128 v[202:205], v0
	ds_read_b128 v[206:209], v0 offset:1024
	ds_read_b128 v[210:213], v0 offset:2048
	ds_read_b128 v[242:245], v0 offset:3072
	global_load_lds_dwordx4 v[154:155], off
	v_lshl_add_u64 v[214:215], s[50:51], 0, v[162:163]
	s_add_i32 m0, s83, 0x2000
	s_nop 0
	global_load_lds_dwordx4 v[214:215], off
	s_barrier
	s_waitcnt lgkmcnt(0)
	s_setprio 1
	s_waitcnt lgkmcnt(0)
	v_mfma_f32_16x16x32_f16 v[94:97], v[202:205], v[146:149], v[94:97]
	v_mfma_f32_16x16x32_f16 v[90:93], v[210:213], v[146:149], v[90:93]
	v_mfma_f32_16x16x32_f16 v[126:129], v[202:205], v[178:181], v[126:129]
	v_mfma_f32_16x16x32_f16 v[38:41], v[210:213], v[178:181], v[38:41]
	v_mfma_f32_16x16x32_f16 v[122:125], v[202:205], v[186:189], v[122:125]
	v_mfma_f32_16x16x32_f16 v[34:37], v[210:213], v[186:189], v[34:37]
	v_mfma_f32_16x16x32_f16 v[106:109], v[202:205], v[194:197], v[106:109]
	v_mfma_f32_16x16x32_f16 v[50:53], v[210:213], v[194:197], v[50:53]
	v_mfma_f32_16x16x32_f16 v[94:97], v[206:209], v[150:153], v[94:97]
	v_mfma_f32_16x16x32_f16 v[90:93], v[242:245], v[150:153], v[90:93]
	v_mfma_f32_16x16x32_f16 v[126:129], v[206:209], v[182:185], v[126:129]
	v_mfma_f32_16x16x32_f16 v[38:41], v[242:245], v[182:185], v[38:41]
	v_mfma_f32_16x16x32_f16 v[122:125], v[206:209], v[190:193], v[122:125]
	v_mfma_f32_16x16x32_f16 v[34:37], v[242:245], v[190:193], v[34:37]
	v_mfma_f32_16x16x32_f16 v[106:109], v[206:209], v[198:201], v[106:109]
	v_mfma_f32_16x16x32_f16 v[50:53], v[242:245], v[198:201], v[50:53]
	s_setprio 0
	s_mov_b32 m0, s64
	v_lshl_add_u64 v[246:247], s[52:53], 0, v[168:169]
	s_barrier
	ds_read_b128 v[146:149], v240 offset:16384
	ds_read_b128 v[150:153], v240 offset:17408
	ds_read_b128 v[178:181], v240 offset:18432
	ds_read_b128 v[182:185], v240 offset:19456
	ds_read_b128 v[186:189], v240 offset:20480
	ds_read_b128 v[190:193], v240 offset:21504
	ds_read_b128 v[194:197], v240 offset:22528
	ds_read_b128 v[198:201], v240 offset:23552
	global_load_lds_dwordx4 v[246:247], off
	v_lshl_add_u64 v[248:249], s[52:53], 0, v[164:165]
	s_mov_b32 m0, s65
	s_nop 0
	global_load_lds_dwordx4 v[248:249], off
	s_barrier
	s_waitcnt lgkmcnt(0)
	s_setprio 1
	s_waitcnt lgkmcnt(0)
	v_mfma_f32_16x16x32_f16 v[78:81], v[114:117], v[146:149], v[78:81]
	v_mfma_f32_16x16x32_f16 v[22:25], v[138:141], v[146:149], v[22:25]
	v_mfma_f32_16x16x32_f16 v[74:77], v[114:117], v[178:181], v[74:77]
	v_mfma_f32_16x16x32_f16 v[18:21], v[138:141], v[178:181], v[18:21]
	v_mfma_f32_16x16x32_f16 v[66:69], v[114:117], v[186:189], v[66:69]
	v_mfma_f32_16x16x32_f16 v[14:17], v[138:141], v[186:189], v[14:17]
	v_mfma_f32_16x16x32_f16 v[86:89], v[114:117], v[194:197], v[86:89]
	v_mfma_f32_16x16x32_f16 v[26:29], v[138:141], v[194:197], v[26:29]
	v_mfma_f32_16x16x32_f16 v[78:81], v[118:121], v[150:153], v[78:81]
	v_mfma_f32_16x16x32_f16 v[22:25], v[142:145], v[150:153], v[22:25]
	v_mfma_f32_16x16x32_f16 v[74:77], v[118:121], v[182:185], v[74:77]
	v_mfma_f32_16x16x32_f16 v[18:21], v[142:145], v[182:185], v[18:21]
	v_mfma_f32_16x16x32_f16 v[66:69], v[118:121], v[190:193], v[66:69]
	v_mfma_f32_16x16x32_f16 v[14:17], v[142:145], v[190:193], v[14:17]
	v_mfma_f32_16x16x32_f16 v[86:89], v[118:121], v[198:201], v[86:89]
	v_mfma_f32_16x16x32_f16 v[26:29], v[142:145], v[198:201], v[26:29]
	s_setprio 0
	s_barrier
; #define PG8_STAGE(bufoff, gbase, voff) do { _Pragma("unroll") for (int _i = 0; _i < 2; ++_i) \
;         __builtin_amdgcn_global_load_lds((const unsigned*)((const char*)(gbase) + (voff)[_i]), (LAS unsigned*)(lds + (bufoff) + ldsw + _i * 8192), 16, 0, 0); } while (0)
; #define PG8_LDA(dst, b, h) do { _Pragma("unroll") for (int m = 0; m < 4; ++m) _Pragma("unroll") for (int k = 0; k < 2; ++k) dst[m][k] = *(const LAS h16x8*)(lds + PG8_SA(b, h) + aoff + m * 2048 + k * 1024); } while (0)
; #define PG8_LDB(dst, b, h) do { _Pragma("unroll") for (int n = 0; n < 2; ++n) _Pragma("unroll") for (int k = 0; k < 2; ++k) dst[n][k] = *(const LAS h16x8*)(lds + PG8_SB(b, h) + boff + n * 2048 + k * 1024); } while (0)
; #define PG8_MMA(ai, bj, At, Bt) do { __builtin_amdgcn_s_setprio(1); _Pragma("unroll") for (int m = 0; m < 4; ++m) _Pragma("unroll") for (int n = 0; n < 2; ++n) _Pragma("unroll") for (int k = 0; k < 2; ++k) \
;         acc[ai][bj][m][n] = __builtin_amdgcn_mfma_f32_16x16x32_f16(Bt[n][k], At[m][k], acc[ai][bj][m][n], 0, 0, 0); __builtin_amdgcn_s_setprio(0); } while (0)
; #define PG8_WAIT_V(n) asm volatile("s_waitcnt vmcnt(" #n ")" ::: "memory")
; #define PG8_WAIT_L(n) asm volatile("s_waitcnt lgkmcnt(" #n ")" ::: "memory")
; #define PG8_BAR __builtin_amdgcn_s_barrier()
; #define PG8_SCHED __builtin_amdgcn_sched_barrier(0)
; template <class Epi>
; __device__ __forceinline__ void gemm_phase(LAS unsigned char* lds, const Gemm g, const StaticOrder& S, const Epi& E, const int wid_s) {
;     ...
;             PG8_BAR; PG8_WAIT_L(0); PG8_MMA(1, 0, At, B0); PG8_BAR; PG8_SCHED;
;             PG8_STAGE(PG8_SB(0, 1), b2 + hstepB, voffB);
;             PG8_WAIT_V(6); PG8_BAR; PG8_MMA(1, 1, At, B1); PG8_BAR;
;             PG8_LDB(B0, 1, 0); PG8_SCHED; PG8_LDA(At, 1, 0); PG8_STAGE(PG8_SA(0, 1), a2 + hstepA, voffA);
;             PG8_WAIT_L(8); PG8_BAR; PG8_WAIT_L(0); PG8_MMA(0, 0, At, B0); PG8_BAR; PG8_SCHED;
;             PG8_LDB(B1, 1, 1); PG8_STAGE(PG8_SB(1, 0), b3, voffB);
;             PG8_BAR; PG8_WAIT_L(0); PG8_MMA(0, 1, At, B1); PG8_BAR;
;             PG8_LDA(At, 1, 1); PG8_STAGE(PG8_SA(1, 0), a3, voffA);
;             PG8_BAR; PG8_WAIT_L(0); PG8_MMA(1, 0, At, B0); PG8_BAR; PG8_SCHED;
	s_add_u32 s84, s50, 0x40000
	s_addc_u32 s85, s51, 0
	s_add_i32 s83, s86, s63
	v_lshl_add_u64 v[114:115], s[84:85], 0, v[166:167]
	s_mov_b32 m0, s83
	s_nop 0
	global_load_lds_dwordx4 v[114:115], off
	v_lshl_add_u64 v[114:115], s[84:85], 0, v[162:163]
	s_add_i32 m0, s83, 0x2000
	s_nop 0
	global_load_lds_dwordx4 v[114:115], off
	s_waitcnt vmcnt(6)
	s_barrier
	s_setprio 1
	v_mfma_f32_16x16x32_f16 v[70:73], v[202:205], v[146:149], v[70:73]
	v_mfma_f32_16x16x32_f16 v[10:13], v[210:213], v[146:149], v[10:13]
	v_mfma_f32_16x16x32_f16 v[62:65], v[202:205], v[178:181], v[62:65]
	v_mfma_f32_16x16x32_f16 v[6:9], v[210:213], v[178:181], v[6:9]
	v_mfma_f32_16x16x32_f16 v[58:61], v[202:205], v[186:189], v[58:61]
	v_mfma_f32_16x16x32_f16 v[2:5], v[210:213], v[186:189], v[2:5]
	v_mfma_f32_16x16x32_f16 v[82:85], v[202:205], v[194:197], v[82:85]
	v_mfma_f32_16x16x32_f16 v[30:33], v[210:213], v[194:197], v[30:33]
	v_mfma_f32_16x16x32_f16 v[70:73], v[206:209], v[150:153], v[70:73]
	v_mfma_f32_16x16x32_f16 v[10:13], v[242:245], v[150:153], v[10:13]
	v_mfma_f32_16x16x32_f16 v[62:65], v[206:209], v[182:185], v[62:65]
	v_mfma_f32_16x16x32_f16 v[6:9], v[242:245], v[182:185], v[6:9]
	v_mfma_f32_16x16x32_f16 v[58:61], v[206:209], v[190:193], v[58:61]
	v_mfma_f32_16x16x32_f16 v[2:5], v[242:245], v[190:193], v[2:5]
	v_mfma_f32_16x16x32_f16 v[82:85], v[206:209], v[198:201], v[82:85]
	v_mfma_f32_16x16x32_f16 v[30:33], v[242:245], v[198:201], v[30:33]
	s_setprio 0
	s_add_i32 s83, 0, 0x18000
	v_add_u32_e32 v0, s83, v171
	s_barrier
	ds_read_b128 v[114:117], v0
	ds_read_b128 v[118:121], v0 offset:1024
	ds_read_b128 v[138:141], v0 offset:2048
	ds_read_b128 v[142:145], v0 offset:3072
	s_add_u32 s52, s52, 0x40000
	s_addc_u32 s53, s53, 0
	s_mov_b32 m0, s66
	v_lshl_add_u64 v[202:203], s[52:53], 0, v[168:169]
	ds_read_b128 v[146:149], v240 offset:32768
	ds_read_b128 v[150:153], v240 offset:33792
	ds_read_b128 v[178:181], v240 offset:34816
	ds_read_b128 v[182:185], v240 offset:35840
	ds_read_b128 v[186:189], v240 offset:36864
	ds_read_b128 v[190:193], v240 offset:37888
	ds_read_b128 v[194:197], v240 offset:38912
	ds_read_b128 v[198:201], v240 offset:39936
	global_load_lds_dwordx4 v[202:203], off
	v_lshl_add_u64 v[202:203], s[52:53], 0, v[164:165]
	s_mov_b32 m0, s67
	s_nop 0
	global_load_lds_dwordx4 v[202:203], off
	s_waitcnt lgkmcnt(8)
	s_barrier
	s_waitcnt lgkmcnt(0)
	s_setprio 1
	s_waitcnt lgkmcnt(0)
	v_mfma_f32_16x16x32_f16 v[102:105], v[114:117], v[146:149], v[102:105]
	v_mfma_f32_16x16x32_f16 v[98:101], v[138:141], v[146:149], v[98:101]
	v_mfma_f32_16x16x32_f16 v[134:137], v[114:117], v[178:181], v[134:137]
	v_mfma_f32_16x16x32_f16 v[46:49], v[138:141], v[178:181], v[46:49]
	v_mfma_f32_16x16x32_f16 v[130:133], v[114:117], v[186:189], v[130:133]
	v_mfma_f32_16x16x32_f16 v[42:45], v[138:141], v[186:189], v[42:45]
	v_mfma_f32_16x16x32_f16 v[110:113], v[114:117], v[194:197], v[110:113]
	v_mfma_f32_16x16x32_f16 v[54:57], v[138:141], v[194:197], v[54:57]
	v_mfma_f32_16x16x32_f16 v[102:105], v[118:121], v[150:153], v[102:105]
	v_mfma_f32_16x16x32_f16 v[98:101], v[142:145], v[150:153], v[98:101]
	v_mfma_f32_16x16x32_f16 v[134:137], v[118:121], v[182:185], v[134:137]
	v_mfma_f32_16x16x32_f16 v[46:49], v[142:145], v[182:185], v[46:49]
	v_mfma_f32_16x16x32_f16 v[130:133], v[118:121], v[190:193], v[130:133]
	v_mfma_f32_16x16x32_f16 v[42:45], v[142:145], v[190:193], v[42:45]
	v_mfma_f32_16x16x32_f16 v[110:113], v[118:121], v[198:201], v[110:113]
	v_mfma_f32_16x16x32_f16 v[54:57], v[142:145], v[198:201], v[54:57]
	s_setprio 0
	s_barrier
	s_add_i32 s52, 0, 0x1c000
	s_add_i32 s53, s83, s63
	v_add_u32_e32 v0, s52, v171
	v_lshl_add_u64 v[154:155], v[154:155], 0, s[74:75]
	s_mov_b32 m0, s53
	ds_read_b128 v[202:205], v0
	ds_read_b128 v[206:209], v0 offset:1024
	ds_read_b128 v[210:213], v0 offset:2048
	ds_read_b128 v[242:245], v0 offset:3072
	global_load_lds_dwordx4 v[154:155], off
	v_lshl_add_u64 v[154:155], v[214:215], 0, s[74:75]
	s_add_i32 m0, s53, 0x2000
	s_nop 0
	global_load_lds_dwordx4 v[154:155], off
	s_barrier
	s_waitcnt lgkmcnt(0)
	s_setprio 1
	s_waitcnt lgkmcnt(0)
	v_mfma_f32_16x16x32_f16 v[94:97], v[202:205], v[146:149], v[94:97]
	v_mfma_f32_16x16x32_f16 v[90:93], v[210:213], v[146:149], v[90:93]
	v_mfma_f32_16x16x32_f16 v[126:129], v[202:205], v[178:181], v[126:129]
	v_mfma_f32_16x16x32_f16 v[38:41], v[210:213], v[178:181], v[38:41]
	v_mfma_f32_16x16x32_f16 v[122:125], v[202:205], v[186:189], v[122:125]
	v_mfma_f32_16x16x32_f16 v[34:37], v[210:213], v[186:189], v[34:37]
	v_mfma_f32_16x16x32_f16 v[106:109], v[202:205], v[194:197], v[106:109]
	v_mfma_f32_16x16x32_f16 v[50:53], v[210:213], v[194:197], v[50:53]
	v_mfma_f32_16x16x32_f16 v[94:97], v[206:209], v[150:153], v[94:97]
	v_mfma_f32_16x16x32_f16 v[90:93], v[242:245], v[150:153], v[90:93]
	v_mfma_f32_16x16x32_f16 v[126:129], v[206:209], v[182:185], v[126:129]
	v_mfma_f32_16x16x32_f16 v[38:41], v[242:245], v[182:185], v[38:41]
	v_mfma_f32_16x16x32_f16 v[122:125], v[206:209], v[190:193], v[122:125]
	v_mfma_f32_16x16x32_f16 v[34:37], v[242:245], v[190:193], v[34:37]
	v_mfma_f32_16x16x32_f16 v[106:109], v[206:209], v[198:201], v[106:109]
	v_mfma_f32_16x16x32_f16 v[50:53], v[242:245], v[198:201], v[50:53]
	s_setprio 0
	s_mov_b32 m0, s58
	v_lshl_add_u64 v[154:155], v[246:247], 0, s[74:75]
	s_barrier
	ds_read_b128 v[146:149], v240 offset:49152
	ds_read_b128 v[150:153], v240 offset:50176
	ds_read_b128 v[178:181], v240 offset:51200
	ds_read_b128 v[182:185], v240 offset:52224
	ds_read_b128 v[186:189], v240 offset:53248
	ds_read_b128 v[190:193], v240 offset:54272
	ds_read_b128 v[194:197], v240 offset:55296
	ds_read_b128 v[198:201], v240 offset:56320
	global_load_lds_dwordx4 v[154:155], off
	v_lshl_add_u64 v[154:155], v[248:249], 0, s[74:75]
	s_mov_b32 m0, s70
	s_nop 0
	global_load_lds_dwordx4 v[154:155], off
	s_barrier
; #define LAS __attribute__((address_space(3)))
; #define PG8_STAGE(bufoff, gbase, voff) do { _Pragma("unroll") for (int _i = 0; _i < 2; ++_i) \
;         __builtin_amdgcn_global_load_lds((const unsigned*)((const char*)(gbase) + (voff)[_i]), (LAS unsigned*)(lds + (bufoff) + ldsw + _i * 8192), 16, 0, 0); } while (0)
; #define PG8_MMA(ai, bj, At, Bt) do { __builtin_amdgcn_s_setprio(1); _Pragma("unroll") for (int m = 0; m < 4; ++m) _Pragma("unroll") for (int n = 0; n < 2; ++n) _Pragma("unroll") for (int k = 0; k < 2; ++k) \
;         acc[ai][bj][m][n] = __builtin_amdgcn_mfma_f32_16x16x32_f16(Bt[n][k], At[m][k], acc[ai][bj][m][n], 0, 0, 0); __builtin_amdgcn_s_setprio(0); } while (0)
; #define PG8_WAIT_V(n) asm volatile("s_waitcnt vmcnt(" #n ")" ::: "memory")
; #define PG8_WAIT_L(n) asm volatile("s_waitcnt lgkmcnt(" #n ")" ::: "memory")
; #define PG8_BAR __builtin_amdgcn_s_barrier()
; #define PG8_SCHED __builtin_amdgcn_sched_barrier(0)
; template <class Epi>
; __device__ __forceinline__ void gemm_phase(LAS unsigned char* lds, const Gemm g, const StaticOrder& S, const Epi& E, const int wid_s) {
;     ...
;             PG8_BAR; PG8_WAIT_L(0); PG8_MMA(1, 0, At, B0); PG8_BAR; PG8_SCHED;
;             PG8_STAGE(PG8_SB(1, 1), b3 + hstepB, voffB);
;             PG8_WAIT_V(6); PG8_BAR; PG8_MMA(1, 1, At, B1); PG8_BAR;
;         }
;     __device__ __forceinline__ void operator()(const f32x4 (&acc_c)[2][2][4][2], const Unit& u, int wr, int wc, int fr, int fq) const {
;     ...
;         float rsv[2][4];
; #pragma unroll
;         for (int ai = 0; ai < 2; ++ai)
; #pragma unroll
;             for (int m = 0; m < 4; ++m) rsv[ai][m] = rowsq[row0 + ai * HALF + m * 16];
; #pragma unroll
;         for (int ai = 0; ai < 2; ++ai)
; #pragma unroll
;             for (int m = 0; m < 4; ++m) { const float rs = rsqrtf(rsv[ai][m] * (1.0f / 1024.0f) + EPS);
; #pragma unroll
;                 for (int bj = 0; bj < 2; ++bj)
; #pragma unroll
;                     for (int n = 0; n < 2; ++n) acc[ai][bj][m][n] *= rs; }
;         if (fr >= 14) {
; #pragma unroll
;             for (int ai = 0; ai < 2; ++ai)
; #pragma unroll
;                 for (int bj = 0; bj < 2; ++bj)
; #pragma unroll
;                     for (int n = 0; n < 2; ++n) *(LAS f32x4*)(xch + ((ai * 2 + wr) * 4 + wc) * 128 + (fr - 14) * 64 + bj * 32 + 8 * fq + 4 * n) = acc[ai][bj][3][n];
;         }
	s_waitcnt lgkmcnt(0)
	s_setprio 1
	s_waitcnt lgkmcnt(0)
	v_mfma_f32_16x16x32_f16 v[78:81], v[114:117], v[146:149], v[78:81]
	v_mfma_f32_16x16x32_f16 v[22:25], v[138:141], v[146:149], v[22:25]
	v_mfma_f32_16x16x32_f16 v[74:77], v[114:117], v[178:181], v[74:77]
	v_mfma_f32_16x16x32_f16 v[18:21], v[138:141], v[178:181], v[18:21]
	v_mfma_f32_16x16x32_f16 v[66:69], v[114:117], v[186:189], v[66:69]
	v_mfma_f32_16x16x32_f16 v[14:17], v[138:141], v[186:189], v[14:17]
	v_mfma_f32_16x16x32_f16 v[86:89], v[114:117], v[194:197], v[86:89]
	v_mfma_f32_16x16x32_f16 v[26:29], v[138:141], v[194:197], v[26:29]
	v_mfma_f32_16x16x32_f16 v[78:81], v[118:121], v[150:153], v[78:81]
	v_mfma_f32_16x16x32_f16 v[22:25], v[142:145], v[150:153], v[22:25]
	v_mfma_f32_16x16x32_f16 v[74:77], v[118:121], v[182:185], v[74:77]
	v_mfma_f32_16x16x32_f16 v[18:21], v[142:145], v[182:185], v[18:21]
	v_mfma_f32_16x16x32_f16 v[66:69], v[118:121], v[190:193], v[66:69]
	v_mfma_f32_16x16x32_f16 v[14:17], v[142:145], v[190:193], v[14:17]
	v_mfma_f32_16x16x32_f16 v[86:89], v[118:121], v[198:201], v[86:89]
	v_mfma_f32_16x16x32_f16 v[26:29], v[142:145], v[198:201], v[26:29]
	s_setprio 0
	s_barrier
	s_add_u32 s50, s50, 0x40080
	s_addc_u32 s51, s51, 0
	s_add_i32 s52, s52, s63
	v_lshl_add_u64 v[114:115], s[50:51], 0, v[166:167]
	s_mov_b32 m0, s52
	s_nop 0
	global_load_lds_dwordx4 v[114:115], off
	v_lshl_add_u64 v[114:115], s[50:51], 0, v[162:163]
	s_add_i32 m0, s52, 0x2000
	s_nop 0
	global_load_lds_dwordx4 v[114:115], off
	s_waitcnt vmcnt(6)
	s_barrier
	s_setprio 1
	v_mfma_f32_16x16x32_f16 v[70:73], v[202:205], v[146:149], v[70:73]
	v_mfma_f32_16x16x32_f16 v[10:13], v[210:213], v[146:149], v[10:13]
	v_mfma_f32_16x16x32_f16 v[62:65], v[202:205], v[178:181], v[62:65]
	v_mfma_f32_16x16x32_f16 v[6:9], v[210:213], v[178:181], v[6:9]
	v_mfma_f32_16x16x32_f16 v[58:61], v[202:205], v[186:189], v[58:61]
	v_mfma_f32_16x16x32_f16 v[2:5], v[210:213], v[186:189], v[2:5]
	v_mfma_f32_16x16x32_f16 v[82:85], v[202:205], v[194:197], v[82:85]
	v_mfma_f32_16x16x32_f16 v[30:33], v[210:213], v[194:197], v[30:33]
	v_mfma_f32_16x16x32_f16 v[70:73], v[206:209], v[150:153], v[70:73]
	v_mfma_f32_16x16x32_f16 v[10:13], v[242:245], v[150:153], v[10:13]
	v_mfma_f32_16x16x32_f16 v[62:65], v[206:209], v[182:185], v[62:65]
	v_mfma_f32_16x16x32_f16 v[6:9], v[242:245], v[182:185], v[6:9]
	v_mfma_f32_16x16x32_f16 v[58:61], v[206:209], v[190:193], v[58:61]
	v_mfma_f32_16x16x32_f16 v[2:5], v[242:245], v[190:193], v[2:5]
	v_mfma_f32_16x16x32_f16 v[82:85], v[206:209], v[198:201], v[82:85]
	v_mfma_f32_16x16x32_f16 v[30:33], v[242:245], v[198:201], v[30:33]
	s_setprio 0
	s_add_i32 s82, s82, 2
	s_add_u32 s48, s48, 0x100
	s_addc_u32 s49, s49, 0
	s_add_u32 s76, s76, 0x100
	s_addc_u32 s77, s77, 0
	s_cmp_gt_u32 s82, 13
	s_barrier
	s_cbranch_scc0 .LBB0_1435
	s_cmp_lg_u64 s[8:9], 0
	s_cbranch_scc0 .Lalign_up_a
	s_barrier
.Lalign_up_a:
	v_lshl_add_u32 v192, s4, 8, v161
	v_or_b32_e32 v198, 16, v192
	v_ashrrev_i32_e32 v193, 31, v192
	v_ashrrev_i32_e32 v199, 31, v198
	v_or_b32_e32 v196, 32, v192
	v_lshl_add_u64 v[114:115], v[192:193], 2, s[14:15]
	v_lshl_add_u64 v[116:117], v[198:199], 2, s[14:15]
	v_ashrrev_i32_e32 v197, 31, v196
	v_or_b32_e32 v194, 48, v192
	global_load_dword v0, v[114:115], off
	global_load_dword v190, v[116:117], off
	v_lshl_add_u64 v[116:117], v[196:197], 2, s[14:15]
	v_ashrrev_i32_e32 v195, 31, v194
	global_load_dword v147, v[116:117], off
	v_lshl_add_u64 v[116:117], v[194:195], 2, s[14:15]
	global_load_dword v116, v[116:117], off
	s_nop 0
	global_load_dword v195, v[114:115], off offset:512
	global_load_dword v193, v[114:115], off offset:576
	global_load_dword v191, v[114:115], off offset:640
	s_nop 0
	global_load_dword v115, v[114:115], off offset:704
	s_waitcnt vmcnt(0)
	v_fmamk_f32 v114, v116, 0x3a800000, v216
	v_cmp_gt_f32_e32 vcc, s2, v114
	v_mul_f32_e32 v116, 0x4b800000, v114
	s_nop 0
	v_cndmask_b32_e32 v114, v114, v116, vcc
	v_rsq_f32_e32 v114, v114
	s_nop 0
	v_mul_f32_e32 v116, 0x45800000, v114
	v_cndmask_b32_e32 v114, v114, v116, vcc
	v_pk_mul_f32 v[138:139], v[106:107], v[114:115] op_sel_hi:[1,0]
	v_fmamk_f32 v106, v115, 0x3a800000, v216
	v_cmp_gt_f32_e32 vcc, s2, v106
	v_mul_f32_e32 v107, 0x4b800000, v106
	v_pk_mul_f32 v[144:145], v[112:113], v[114:115] op_sel_hi:[1,0]
	v_cndmask_b32_e32 v106, v106, v107, vcc
	v_rsq_f32_e32 v106, v106
	v_pk_mul_f32 v[142:143], v[110:111], v[114:115] op_sel_hi:[1,0]
	v_pk_mul_f32 v[56:57], v[56:57], v[114:115] op_sel_hi:[1,0]
	v_pk_mul_f32 v[54:55], v[54:55], v[114:115] op_sel_hi:[1,0]
	v_mul_f32_e32 v107, 0x45800000, v106
	v_cndmask_b32_e32 v106, v106, v107, vcc
	v_pk_mul_f32 v[140:141], v[108:109], v[114:115] op_sel_hi:[1,0]
	v_pk_mul_f32 v[52:53], v[52:53], v[114:115] op_sel_hi:[1,0]
	v_pk_mul_f32 v[50:51], v[50:51], v[114:115] op_sel_hi:[1,0]
	v_pk_mul_f32 v[88:89], v[88:89], v[106:107] op_sel_hi:[1,0]
	v_pk_mul_f32 v[86:87], v[86:87], v[106:107] op_sel_hi:[1,0]
	v_pk_mul_f32 v[28:29], v[28:29], v[106:107] op_sel_hi:[1,0]
	v_pk_mul_f32 v[26:27], v[26:27], v[106:107] op_sel_hi:[1,0]
	v_pk_mul_f32 v[84:85], v[84:85], v[106:107] op_sel_hi:[1,0]
	v_pk_mul_f32 v[82:83], v[82:83], v[106:107] op_sel_hi:[1,0]
	v_pk_mul_f32 v[32:33], v[32:33], v[106:107] op_sel_hi:[1,0]
	v_pk_mul_f32 v[30:31], v[30:31], v[106:107] op_sel_hi:[1,0]
	s_and_saveexec_b64 s[48:49], s[6:7]
	s_cbranch_execz .LBB0_1438
	ds_write_b128 v228, v[142:145]
	ds_write_b128 v229, v[54:57]
	ds_write_b128 v230, v[138:141]
	ds_write_b128 v231, v[50:53]
	ds_write_b128 v227, v[86:89] offset:512
	ds_write_b128 v227, v[26:29] offset:528
	ds_write_b128 v227, v[82:85] offset:640
	ds_write_b128 v227, v[30:33] offset:656

; template <class Epi>
; __device__ __forceinline__ void gemm_phase(LAS unsigned char* lds, const Gemm g, const StaticOrder& S, const Epi& E, const int wid_s) {
;     ...
;         E(acc, cur, wr, wc, fr, fq);
;         if (!has_next) break;
; #pragma unroll
;         for (int a = 0; a < 2; ++a)
; #pragma unroll
;             for (int b = 0; b < 2; ++b)
; #pragma unroll
;                 for (int m = 0; m < 4; ++m)
; #pragma unroll
;                     for (int n = 0; n < 2; ++n) acc[a][b][m][n] = (f32x4){0.f, 0.f, 0.f, 0.f};
;         cur = nxt; cA = nA; cB = nB; ++ui;
;     }
.LBB0_1532:
	s_or_b64 exec, exec, s[4:5]
	s_and_b64 vcc, exec, s[8:9]
	s_mov_b32 s46, s44
	s_mov_b32 s47, s45
	s_mov_b64 s[24:25], s[12:13]
	s_mov_b64 s[4:5], s[22:23]
	s_cmpk_gt_u32 s29, 0xff
	s_cbranch_scc0 .Lalign_down_b
	s_barrier

; #define PG8_STAGE(bufoff, gbase, voff) do { _Pragma("unroll") for (int _i = 0; _i < 2; ++_i) \
;         __builtin_amdgcn_global_load_lds((const unsigned*)((const char*)(gbase) + (voff)[_i]), (LAS unsigned*)(lds + (bufoff) + ldsw + _i * 8192), 16, 0, 0); } while (0)
; #define PG8_LDA(dst, b, h) do { _Pragma("unroll") for (int m = 0; m < 4; ++m) _Pragma("unroll") for (int k = 0; k < 2; ++k) dst[m][k] = *(const LAS h16x8*)(lds + PG8_SA(b, h) + aoff + m * 2048 + k * 1024); } while (0)
; #define PG8_LDB(dst, b, h) do { _Pragma("unroll") for (int n = 0; n < 2; ++n) _Pragma("unroll") for (int k = 0; k < 2; ++k) dst[n][k] = *(const LAS h16x8*)(lds + PG8_SB(b, h) + boff + n * 2048 + k * 1024); } while (0)
; #define PG8_MMA(ai, bj, At, Bt) do { __builtin_amdgcn_s_setprio(1); _Pragma("unroll") for (int m = 0; m < 4; ++m) _Pragma("unroll") for (int n = 0; n < 2; ++n) _Pragma("unroll") for (int k = 0; k < 2; ++k) \
;         acc[ai][bj][m][n] = __builtin_amdgcn_mfma_f32_16x16x32_f16(Bt[n][k], At[m][k], acc[ai][bj][m][n], 0, 0, 0); __builtin_amdgcn_s_setprio(0); } while (0)
; #define PG8_WAIT_V(n) asm volatile("s_waitcnt vmcnt(" #n ")" ::: "memory")
; #define PG8_WAIT_L(n) asm volatile("s_waitcnt lgkmcnt(" #n ")" ::: "memory")
; #define PG8_BAR __builtin_amdgcn_s_barrier()
; #define PG8_SCHED __builtin_amdgcn_sched_barrier(0)
; template <class Epi>
; __device__ __forceinline__ void gemm_phase(LAS unsigned char* lds, const Gemm g, const StaticOrder& S, const Epi& E, const int wid_s) {
;     ...
;             PG8_LDB(B0, 0, 0); PG8_SCHED; PG8_LDA(At, 0, 0); PG8_STAGE(PG8_SA(1, 1), a1 + hstepA, voffA);
;             PG8_WAIT_L(8); PG8_BAR; PG8_WAIT_L(0); PG8_MMA(0, 0, At, B0); PG8_BAR; PG8_SCHED;
;             PG8_LDB(B1, 0, 1); PG8_STAGE(PG8_SB(0, 0), b2, voffB);
;             PG8_BAR; PG8_WAIT_L(0); PG8_MMA(0, 1, At, B1); PG8_BAR;
;             PG8_LDA(At, 0, 1); PG8_STAGE(PG8_SA(0, 0), a2, voffA);
;             PG8_BAR; PG8_WAIT_L(0); PG8_MMA(1, 0, At, B0); PG8_BAR; PG8_SCHED;
;             PG8_STAGE(PG8_SB(0, 1), b2 + hstepB, voffB);
;             PG8_WAIT_V(6); PG8_BAR; PG8_MMA(1, 1, At, B1); PG8_BAR;
.LBB0_1544:
	s_add_u32 s10, s4, 0x100
	s_addc_u32 s11, s5, 0
	s_add_i32 s51, 0, 0x10000
	v_add_u32_e32 v148, s51, v170
	ds_read_b128 v[136:139], v148
	ds_read_b128 v[140:143], v148 offset:1024
	ds_read_b128 v[144:147], v148 offset:2048
	ds_read_b128 v[148:151], v148 offset:3072
	s_cmp_eq_u32 s50, 40
	s_cselect_b32 s27, s23, s11
	s_cselect_b32 s26, s22, s10
	s_cselect_b32 s25, s13, s49
	s_cselect_b32 s24, s12, s48
	v_lshl_add_u64 v[196:197], s[4:5], 0, v[132:133]
	s_add_i32 m0, s37, 0xc000
	ds_read_b128 v[152:155], v174
	ds_read_b128 v[162:165], v174 offset:1024
	ds_read_b128 v[166:169], v174 offset:2048
	ds_read_b128 v[176:179], v174 offset:3072
	ds_read_b128 v[180:183], v174 offset:4096
	ds_read_b128 v[184:187], v174 offset:5120
	ds_read_b128 v[188:191], v174 offset:6144
	ds_read_b128 v[192:195], v174 offset:7168
	global_load_lds_dwordx4 v[196:197], off
	v_lshl_add_u64 v[196:197], s[4:5], 0, v[134:135]
	s_add_i32 m0, s37, 0xe000
	s_nop 0
	global_load_lds_dwordx4 v[196:197], off
	s_waitcnt lgkmcnt(8)
	s_barrier
	s_waitcnt lgkmcnt(0)
	s_setprio 1
	s_waitcnt lgkmcnt(0)
	v_mfma_f32_16x16x32_f16 v[126:129], v[136:139], v[152:155], v[126:129]
	v_mfma_f32_16x16x32_f16 v[122:125], v[144:147], v[152:155], v[122:125]
	v_mfma_f32_16x16x32_f16 v[110:113], v[136:139], v[166:169], v[110:113]
	v_mfma_f32_16x16x32_f16 v[106:109], v[144:147], v[166:169], v[106:109]
	v_mfma_f32_16x16x32_f16 v[94:97], v[136:139], v[180:183], v[94:97]
	v_mfma_f32_16x16x32_f16 v[90:93], v[144:147], v[180:183], v[90:93]
	v_mfma_f32_16x16x32_f16 v[78:81], v[136:139], v[188:191], v[78:81]
	v_mfma_f32_16x16x32_f16 v[74:77], v[144:147], v[188:191], v[74:77]
	v_mfma_f32_16x16x32_f16 v[126:129], v[140:143], v[162:165], v[126:129]
	v_mfma_f32_16x16x32_f16 v[122:125], v[148:151], v[162:165], v[122:125]
	v_mfma_f32_16x16x32_f16 v[110:113], v[140:143], v[176:179], v[110:113]
	v_mfma_f32_16x16x32_f16 v[106:109], v[148:151], v[176:179], v[106:109]
	v_mfma_f32_16x16x32_f16 v[94:97], v[140:143], v[184:187], v[94:97]
	v_mfma_f32_16x16x32_f16 v[90:93], v[148:151], v[184:187], v[90:93]
	v_mfma_f32_16x16x32_f16 v[78:81], v[140:143], v[192:195], v[78:81]
	v_mfma_f32_16x16x32_f16 v[74:77], v[148:151], v[192:195], v[74:77]
	s_setprio 0
	s_barrier
	s_add_i32 s52, 0, 0x14000
	s_add_i32 s4, s51, s30
	v_add_u32_e32 v175, s52, v170
	v_lshl_add_u64 v[212:213], s[24:25], 0, v[0:1]
	s_mov_b32 m0, s4
	ds_read_b128 v[196:199], v175
	ds_read_b128 v[200:203], v175 offset:1024
	ds_read_b128 v[204:207], v175 offset:2048
	ds_read_b128 v[208:211], v175 offset:3072
	global_load_lds_dwordx4 v[212:213], off
	v_lshl_add_u64 v[214:215], s[24:25], 0, v[130:131]
	s_add_i32 m0, s4, 0x2000
	s_nop 0
	global_load_lds_dwordx4 v[214:215], off
	s_barrier
	s_waitcnt lgkmcnt(0)
	s_setprio 1
	s_waitcnt lgkmcnt(0)
	v_mfma_f32_16x16x32_f16 v[118:121], v[196:199], v[152:155], v[118:121]
	v_mfma_f32_16x16x32_f16 v[114:117], v[204:207], v[152:155], v[114:117]
	v_mfma_f32_16x16x32_f16 v[102:105], v[196:199], v[166:169], v[102:105]
	v_mfma_f32_16x16x32_f16 v[98:101], v[204:207], v[166:169], v[98:101]
	v_mfma_f32_16x16x32_f16 v[86:89], v[196:199], v[180:183], v[86:89]
	v_mfma_f32_16x16x32_f16 v[82:85], v[204:207], v[180:183], v[82:85]
	v_mfma_f32_16x16x32_f16 v[70:73], v[196:199], v[188:191], v[70:73]
	v_mfma_f32_16x16x32_f16 v[66:69], v[204:207], v[188:191], v[66:69]
	v_mfma_f32_16x16x32_f16 v[118:121], v[200:203], v[162:165], v[118:121]
	v_mfma_f32_16x16x32_f16 v[114:117], v[208:211], v[162:165], v[114:117]
	v_mfma_f32_16x16x32_f16 v[102:105], v[200:203], v[176:179], v[102:105]
	v_mfma_f32_16x16x32_f16 v[98:101], v[208:211], v[176:179], v[98:101]
	v_mfma_f32_16x16x32_f16 v[86:89], v[200:203], v[184:187], v[86:89]
	v_mfma_f32_16x16x32_f16 v[82:85], v[208:211], v[184:187], v[82:85]
	v_mfma_f32_16x16x32_f16 v[70:73], v[200:203], v[192:195], v[70:73]
	v_mfma_f32_16x16x32_f16 v[66:69], v[208:211], v[192:195], v[66:69]
	s_setprio 0
	s_mov_b32 m0, s37
	v_lshl_add_u64 v[228:229], s[26:27], 0, v[0:1]
	s_barrier
	ds_read_b128 v[152:155], v174 offset:16384
	ds_read_b128 v[162:165], v174 offset:17408
	ds_read_b128 v[166:169], v174 offset:18432
	ds_read_b128 v[176:179], v174 offset:19456
	ds_read_b128 v[180:183], v174 offset:20480
	ds_read_b128 v[184:187], v174 offset:21504
	ds_read_b128 v[188:191], v174 offset:22528
	ds_read_b128 v[192:195], v174 offset:23552
	global_load_lds_dwordx4 v[228:229], off
	v_lshl_add_u64 v[230:231], s[26:27], 0, v[130:131]
	s_mov_b32 m0, s38
	s_nop 0
	global_load_lds_dwordx4 v[230:231], off
	s_barrier
	s_waitcnt lgkmcnt(0)
	s_setprio 1
	s_waitcnt lgkmcnt(0)
	v_mfma_f32_16x16x32_f16 v[62:65], v[136:139], v[152:155], v[62:65]
	v_mfma_f32_16x16x32_f16 v[58:61], v[144:147], v[152:155], v[58:61]
	v_mfma_f32_16x16x32_f16 v[46:49], v[136:139], v[166:169], v[46:49]
	v_mfma_f32_16x16x32_f16 v[42:45], v[144:147], v[166:169], v[42:45]
	v_mfma_f32_16x16x32_f16 v[30:33], v[136:139], v[180:183], v[30:33]
	v_mfma_f32_16x16x32_f16 v[26:29], v[144:147], v[180:183], v[26:29]
	v_mfma_f32_16x16x32_f16 v[14:17], v[136:139], v[188:191], v[14:17]
	v_mfma_f32_16x16x32_f16 v[10:13], v[144:147], v[188:191], v[10:13]
	v_mfma_f32_16x16x32_f16 v[62:65], v[140:143], v[162:165], v[62:65]
	v_mfma_f32_16x16x32_f16 v[58:61], v[148:151], v[162:165], v[58:61]
	v_mfma_f32_16x16x32_f16 v[46:49], v[140:143], v[176:179], v[46:49]
	v_mfma_f32_16x16x32_f16 v[42:45], v[148:151], v[176:179], v[42:45]
	v_mfma_f32_16x16x32_f16 v[30:33], v[140:143], v[184:187], v[30:33]
	v_mfma_f32_16x16x32_f16 v[26:29], v[148:151], v[184:187], v[26:29]
	v_mfma_f32_16x16x32_f16 v[14:17], v[140:143], v[192:195], v[14:17]
	v_mfma_f32_16x16x32_f16 v[10:13], v[148:151], v[192:195], v[10:13]
	s_setprio 0
	s_barrier
; #define PG8_STAGE(bufoff, gbase, voff) do { _Pragma("unroll") for (int _i = 0; _i < 2; ++_i) \
;         __builtin_amdgcn_global_load_lds((const unsigned*)((const char*)(gbase) + (voff)[_i]), (LAS unsigned*)(lds + (bufoff) + ldsw + _i * 8192), 16, 0, 0); } while (0)
; #define PG8_LDA(dst, b, h) do { _Pragma("unroll") for (int m = 0; m < 4; ++m) _Pragma("unroll") for (int k = 0; k < 2; ++k) dst[m][k] = *(const LAS h16x8*)(lds + PG8_SA(b, h) + aoff + m * 2048 + k * 1024); } while (0)
; #define PG8_LDB(dst, b, h) do { _Pragma("unroll") for (int n = 0; n < 2; ++n) _Pragma("unroll") for (int k = 0; k < 2; ++k) dst[n][k] = *(const LAS h16x8*)(lds + PG8_SB(b, h) + boff + n * 2048 + k * 1024); } while (0)
; #define PG8_MMA(ai, bj, At, Bt) do { __builtin_amdgcn_s_setprio(1); _Pragma("unroll") for (int m = 0; m < 4; ++m) _Pragma("unroll") for (int n = 0; n < 2; ++n) _Pragma("unroll") for (int k = 0; k < 2; ++k) \
;         acc[ai][bj][m][n] = __builtin_amdgcn_mfma_f32_16x16x32_f16(Bt[n][k], At[m][k], acc[ai][bj][m][n], 0, 0, 0); __builtin_amdgcn_s_setprio(0); } while (0)
; #define PG8_WAIT_V(n) asm volatile("s_waitcnt vmcnt(" #n ")" ::: "memory")
; #define PG8_WAIT_L(n) asm volatile("s_waitcnt lgkmcnt(" #n ")" ::: "memory")
; #define PG8_BAR __builtin_amdgcn_s_barrier()
; #define PG8_SCHED __builtin_amdgcn_sched_barrier(0)
; template <class Epi>
; __device__ __forceinline__ void gemm_phase(LAS unsigned char* lds, const Gemm g, const StaticOrder& S, const Epi& E, const int wid_s) {
;     ...
;             PG8_BAR; PG8_WAIT_L(0); PG8_MMA(1, 0, At, B0); PG8_BAR; PG8_SCHED;
;             PG8_STAGE(PG8_SB(0, 1), b2 + hstepB, voffB);
;             PG8_WAIT_V(6); PG8_BAR; PG8_MMA(1, 1, At, B1); PG8_BAR;
;             PG8_LDB(B0, 1, 0); PG8_SCHED; PG8_LDA(At, 1, 0); PG8_STAGE(PG8_SA(0, 1), a2 + hstepA, voffA);
;             PG8_WAIT_L(8); PG8_BAR; PG8_WAIT_L(0); PG8_MMA(0, 0, At, B0); PG8_BAR; PG8_SCHED;
;             PG8_LDB(B1, 1, 1); PG8_STAGE(PG8_SB(1, 0), b3, voffB);
;             PG8_BAR; PG8_WAIT_L(0); PG8_MMA(0, 1, At, B1); PG8_BAR;
;             PG8_LDA(At, 1, 1); PG8_STAGE(PG8_SA(1, 0), a3, voffA);
;             PG8_BAR; PG8_WAIT_L(0); PG8_MMA(1, 0, At, B0); PG8_BAR; PG8_SCHED;
	s_add_u32 s4, s24, 0xb0000
	s_addc_u32 s5, s25, 0
	s_add_i32 s51, s52, s30
	v_lshl_add_u64 v[136:137], s[4:5], 0, v[0:1]
	s_mov_b32 m0, s51
	s_nop 0
	global_load_lds_dwordx4 v[136:137], off
	v_lshl_add_u64 v[136:137], s[4:5], 0, v[130:131]
	s_add_i32 m0, s51, 0x2000
	s_nop 0
	global_load_lds_dwordx4 v[136:137], off
	s_waitcnt vmcnt(6)
	s_barrier
	s_setprio 1
	v_mfma_f32_16x16x32_f16 v[54:57], v[196:199], v[152:155], v[54:57]
	v_mfma_f32_16x16x32_f16 v[50:53], v[204:207], v[152:155], v[50:53]
	v_mfma_f32_16x16x32_f16 v[38:41], v[196:199], v[166:169], v[38:41]
	v_mfma_f32_16x16x32_f16 v[34:37], v[204:207], v[166:169], v[34:37]
	v_mfma_f32_16x16x32_f16 v[22:25], v[196:199], v[180:183], v[22:25]
	v_mfma_f32_16x16x32_f16 v[18:21], v[204:207], v[180:183], v[18:21]
	v_mfma_f32_16x16x32_f16 v[6:9], v[196:199], v[188:191], v[6:9]
	v_mfma_f32_16x16x32_f16 v[2:5], v[204:207], v[188:191], v[2:5]
	v_mfma_f32_16x16x32_f16 v[54:57], v[200:203], v[162:165], v[54:57]
	v_mfma_f32_16x16x32_f16 v[50:53], v[208:211], v[162:165], v[50:53]
	v_mfma_f32_16x16x32_f16 v[38:41], v[200:203], v[176:179], v[38:41]
	v_mfma_f32_16x16x32_f16 v[34:37], v[208:211], v[176:179], v[34:37]
	v_mfma_f32_16x16x32_f16 v[22:25], v[200:203], v[184:187], v[22:25]
	v_mfma_f32_16x16x32_f16 v[18:21], v[208:211], v[184:187], v[18:21]
	v_mfma_f32_16x16x32_f16 v[6:9], v[200:203], v[192:195], v[6:9]
	v_mfma_f32_16x16x32_f16 v[2:5], v[208:211], v[192:195], v[2:5]
	s_setprio 0
	s_add_i32 s51, 0, 0x18000
	v_add_u32_e32 v148, s51, v170
	s_barrier
	ds_read_b128 v[136:139], v148
	ds_read_b128 v[140:143], v148 offset:1024
	ds_read_b128 v[144:147], v148 offset:2048
	ds_read_b128 v[148:151], v148 offset:3072
	s_add_u32 s4, s26, 0xb0000
	s_addc_u32 s5, s27, 0
	s_mov_b32 m0, s39
	v_lshl_add_u64 v[196:197], s[4:5], 0, v[0:1]
	ds_read_b128 v[152:155], v174 offset:32768
	ds_read_b128 v[162:165], v174 offset:33792
	ds_read_b128 v[166:169], v174 offset:34816
	ds_read_b128 v[176:179], v174 offset:35840
	ds_read_b128 v[180:183], v174 offset:36864
	ds_read_b128 v[184:187], v174 offset:37888
	ds_read_b128 v[188:191], v174 offset:38912
	ds_read_b128 v[192:195], v174 offset:39936
	global_load_lds_dwordx4 v[196:197], off
	v_lshl_add_u64 v[196:197], s[4:5], 0, v[130:131]
	s_mov_b32 m0, s40
	s_nop 0
	global_load_lds_dwordx4 v[196:197], off
	s_waitcnt lgkmcnt(8)
	s_barrier
	s_waitcnt lgkmcnt(0)
	s_setprio 1
	s_waitcnt lgkmcnt(0)
	v_mfma_f32_16x16x32_f16 v[126:129], v[136:139], v[152:155], v[126:129]
	v_mfma_f32_16x16x32_f16 v[122:125], v[144:147], v[152:155], v[122:125]
	v_mfma_f32_16x16x32_f16 v[110:113], v[136:139], v[166:169], v[110:113]
	v_mfma_f32_16x16x32_f16 v[106:109], v[144:147], v[166:169], v[106:109]
	v_mfma_f32_16x16x32_f16 v[94:97], v[136:139], v[180:183], v[94:97]
	v_mfma_f32_16x16x32_f16 v[90:93], v[144:147], v[180:183], v[90:93]
	v_mfma_f32_16x16x32_f16 v[78:81], v[136:139], v[188:191], v[78:81]
	v_mfma_f32_16x16x32_f16 v[74:77], v[144:147], v[188:191], v[74:77]
	v_mfma_f32_16x16x32_f16 v[126:129], v[140:143], v[162:165], v[126:129]
	v_mfma_f32_16x16x32_f16 v[122:125], v[148:151], v[162:165], v[122:125]
	v_mfma_f32_16x16x32_f16 v[110:113], v[140:143], v[176:179], v[110:113]
	v_mfma_f32_16x16x32_f16 v[106:109], v[148:151], v[176:179], v[106:109]
	v_mfma_f32_16x16x32_f16 v[94:97], v[140:143], v[184:187], v[94:97]
	v_mfma_f32_16x16x32_f16 v[90:93], v[148:151], v[184:187], v[90:93]
	v_mfma_f32_16x16x32_f16 v[78:81], v[140:143], v[192:195], v[78:81]
	v_mfma_f32_16x16x32_f16 v[74:77], v[148:151], v[192:195], v[74:77]
	s_setprio 0
	s_barrier
	s_add_i32 s26, 0, 0x1c000
	s_add_i32 s4, s51, s30
	v_add_u32_e32 v175, s26, v170
	v_lshl_add_u64 v[212:213], v[212:213], 0, s[74:75]
	s_mov_b32 m0, s4
	ds_read_b128 v[196:199], v175
	ds_read_b128 v[200:203], v175 offset:1024
	ds_read_b128 v[204:207], v175 offset:2048
	ds_read_b128 v[208:211], v175 offset:3072
	global_load_lds_dwordx4 v[212:213], off
	v_lshl_add_u64 v[212:213], v[214:215], 0, s[74:75]
	s_add_i32 m0, s4, 0x2000
	s_nop 0
	global_load_lds_dwordx4 v[212:213], off
	s_barrier
	s_waitcnt lgkmcnt(0)
	s_setprio 1
	s_waitcnt lgkmcnt(0)
	v_mfma_f32_16x16x32_f16 v[118:121], v[196:199], v[152:155], v[118:121]
	v_mfma_f32_16x16x32_f16 v[114:117], v[204:207], v[152:155], v[114:117]
	v_mfma_f32_16x16x32_f16 v[102:105], v[196:199], v[166:169], v[102:105]
	v_mfma_f32_16x16x32_f16 v[98:101], v[204:207], v[166:169], v[98:101]
	v_mfma_f32_16x16x32_f16 v[86:89], v[196:199], v[180:183], v[86:89]
	v_mfma_f32_16x16x32_f16 v[82:85], v[204:207], v[180:183], v[82:85]
	v_mfma_f32_16x16x32_f16 v[70:73], v[196:199], v[188:191], v[70:73]
	v_mfma_f32_16x16x32_f16 v[66:69], v[204:207], v[188:191], v[66:69]
	v_mfma_f32_16x16x32_f16 v[118:121], v[200:203], v[162:165], v[118:121]
	v_mfma_f32_16x16x32_f16 v[114:117], v[208:211], v[162:165], v[114:117]
	v_mfma_f32_16x16x32_f16 v[102:105], v[200:203], v[176:179], v[102:105]
	v_mfma_f32_16x16x32_f16 v[98:101], v[208:211], v[176:179], v[98:101]
	v_mfma_f32_16x16x32_f16 v[86:89], v[200:203], v[184:187], v[86:89]
	v_mfma_f32_16x16x32_f16 v[82:85], v[208:211], v[184:187], v[82:85]
	v_mfma_f32_16x16x32_f16 v[70:73], v[200:203], v[192:195], v[70:73]
	v_mfma_f32_16x16x32_f16 v[66:69], v[208:211], v[192:195], v[66:69]
	s_setprio 0
	s_mov_b32 m0, s41
	v_lshl_add_u64 v[212:213], v[228:229], 0, s[74:75]
	s_barrier
; #define PG8_STAGE(bufoff, gbase, voff) do { _Pragma("unroll") for (int _i = 0; _i < 2; ++_i) \
;         __builtin_amdgcn_global_load_lds((const unsigned*)((const char*)(gbase) + (voff)[_i]), (LAS unsigned*)(lds + (bufoff) + ldsw + _i * 8192), 16, 0, 0); } while (0)
; #define PG8_WAIT_V(n) asm volatile("s_waitcnt vmcnt(" #n ")" ::: "memory")
; #define PG8_WAIT_L(n) asm volatile("s_waitcnt lgkmcnt(" #n ")" ::: "memory")
; #define PG8_BAR __builtin_amdgcn_s_barrier()
; template <class Epi>
; __device__ __forceinline__ void gemm_phase(LAS unsigned char* lds, const Gemm g, const StaticOrder& S, const Epi& E, const int wid_s) {
;     ...
;             PG8_BAR; PG8_WAIT_L(0); PG8_MMA(1, 0, At, B0); PG8_BAR; PG8_SCHED;
;             PG8_STAGE(PG8_SB(1, 1), b3 + hstepB, voffB);
;             PG8_WAIT_V(6); PG8_BAR; PG8_MMA(1, 1, At, B1); PG8_BAR;
;         }
;     __device__ __forceinline__ void operator()(const f32x4 (&acc)[2][2][4][2], const Unit& u, int wr, int wc, int fr, int fq) const {
;         const int row0 = u.pm * BM + wr * 64 + fr, col0 = u.pn * BM + wc * 32 + 4 * fq;
;         h16x4 hin[2][2], hnx[2][2];
; #pragma unroll
;         for (int bj = 0; bj < 2; ++bj)
; #pragma unroll
;             for (int n = 0; n < 2; ++n) hin[bj][n] = *(const h16x4*)(HB + (size_t)row0 * D + col0 + bj * HALF + n * 16);
; #pragma unroll
;         for (int g = 0; g < 8; ++g) {
;             const int ai = g >> 2, m = g & 3;
;             const int r = row0 + ai * HALF + m * 16; float ss = 0.f;
;             if (g < 7) { const int rn = row0 + ((g + 1) >> 2) * HALF + ((g + 1) & 3) * 16;
; #pragma unroll
;                 for (int bj = 0; bj < 2; ++bj)
; #pragma unroll
;                     for (int n = 0; n < 2; ++n) hnx[bj][n] = *(const h16x4*)(HB + (size_t)rn * D + col0 + bj * HALF + n * 16); }
; #pragma unroll
;             for (int bj = 0; bj < 2; ++bj)
; #pragma unroll
;                 for (int n = 0; n < 2; ++n) {
;                     const size_t o = (size_t)r * D + col0 + bj * HALF + n * 16;
;                     f32x4 hv; hv[0] = (float)hin[bj][n][0]; hv[1] = (float)hin[bj][n][1]; hv[2] = (float)hin[bj][n][2]; hv[3] = (float)hin[bj][n][3];
;                     hv += acc[ai][bj][m][n];
;                     ss += hv[0] * hv[0] + hv[1] * hv[1] + hv[2] * hv[2] + hv[3] * hv[3];
;                     if (OUT != nullptr) *(f32x4*)(OUT + o) = hv;
	ds_read_b128 v[152:155], v174 offset:49152
	ds_read_b128 v[162:165], v174 offset:50176
	ds_read_b128 v[166:169], v174 offset:51200
	ds_read_b128 v[176:179], v174 offset:52224
	ds_read_b128 v[180:183], v174 offset:53248
	ds_read_b128 v[184:187], v174 offset:54272
	ds_read_b128 v[188:191], v174 offset:55296
	ds_read_b128 v[192:195], v174 offset:56320
	global_load_lds_dwordx4 v[212:213], off
	v_lshl_add_u64 v[212:213], v[230:231], 0, s[74:75]
	s_mov_b32 m0, s42
	s_nop 0
	global_load_lds_dwordx4 v[212:213], off
	s_barrier
	s_waitcnt lgkmcnt(0)
	s_setprio 1
	s_waitcnt lgkmcnt(0)
	v_mfma_f32_16x16x32_f16 v[62:65], v[136:139], v[152:155], v[62:65]
	v_mfma_f32_16x16x32_f16 v[58:61], v[144:147], v[152:155], v[58:61]
	v_mfma_f32_16x16x32_f16 v[46:49], v[136:139], v[166:169], v[46:49]
	v_mfma_f32_16x16x32_f16 v[42:45], v[144:147], v[166:169], v[42:45]
	v_mfma_f32_16x16x32_f16 v[30:33], v[136:139], v[180:183], v[30:33]
	v_mfma_f32_16x16x32_f16 v[26:29], v[144:147], v[180:183], v[26:29]
	v_mfma_f32_16x16x32_f16 v[14:17], v[136:139], v[188:191], v[14:17]
	v_mfma_f32_16x16x32_f16 v[10:13], v[144:147], v[188:191], v[10:13]
	v_mfma_f32_16x16x32_f16 v[62:65], v[140:143], v[162:165], v[62:65]
	v_mfma_f32_16x16x32_f16 v[58:61], v[148:151], v[162:165], v[58:61]
	v_mfma_f32_16x16x32_f16 v[46:49], v[140:143], v[176:179], v[46:49]
	v_mfma_f32_16x16x32_f16 v[42:45], v[148:151], v[176:179], v[42:45]
	v_mfma_f32_16x16x32_f16 v[30:33], v[140:143], v[184:187], v[30:33]
	v_mfma_f32_16x16x32_f16 v[26:29], v[148:151], v[184:187], v[26:29]
	v_mfma_f32_16x16x32_f16 v[14:17], v[140:143], v[192:195], v[14:17]
	v_mfma_f32_16x16x32_f16 v[10:13], v[148:151], v[192:195], v[10:13]
	s_setprio 0
	s_barrier
	s_add_u32 s4, s24, 0xb0080
	s_addc_u32 s5, s25, 0
	s_add_i32 s24, s26, s30
	v_lshl_add_u64 v[136:137], s[4:5], 0, v[0:1]
	s_mov_b32 m0, s24
	s_nop 0
	global_load_lds_dwordx4 v[136:137], off
	v_lshl_add_u64 v[136:137], s[4:5], 0, v[130:131]
	s_add_i32 m0, s24, 0x2000
	s_nop 0
	global_load_lds_dwordx4 v[136:137], off
	s_waitcnt vmcnt(6)
	s_barrier
	s_setprio 1
	v_mfma_f32_16x16x32_f16 v[54:57], v[196:199], v[152:155], v[54:57]
	v_mfma_f32_16x16x32_f16 v[50:53], v[204:207], v[152:155], v[50:53]
	v_mfma_f32_16x16x32_f16 v[38:41], v[196:199], v[166:169], v[38:41]
	v_mfma_f32_16x16x32_f16 v[34:37], v[204:207], v[166:169], v[34:37]
	v_mfma_f32_16x16x32_f16 v[22:25], v[196:199], v[180:183], v[22:25]
	v_mfma_f32_16x16x32_f16 v[18:21], v[204:207], v[180:183], v[18:21]
	v_mfma_f32_16x16x32_f16 v[6:9], v[196:199], v[188:191], v[6:9]
	v_mfma_f32_16x16x32_f16 v[2:5], v[204:207], v[188:191], v[2:5]
	v_mfma_f32_16x16x32_f16 v[54:57], v[200:203], v[162:165], v[54:57]
	v_mfma_f32_16x16x32_f16 v[50:53], v[208:211], v[162:165], v[50:53]
	v_mfma_f32_16x16x32_f16 v[38:41], v[200:203], v[176:179], v[38:41]
	v_mfma_f32_16x16x32_f16 v[34:37], v[208:211], v[176:179], v[34:37]
	v_mfma_f32_16x16x32_f16 v[22:25], v[200:203], v[184:187], v[22:25]
	v_mfma_f32_16x16x32_f16 v[18:21], v[208:211], v[184:187], v[18:21]
	v_mfma_f32_16x16x32_f16 v[6:9], v[200:203], v[192:195], v[6:9]
	v_mfma_f32_16x16x32_f16 v[2:5], v[208:211], v[192:195], v[2:5]
	s_setprio 0
	s_add_i32 s50, s50, 2
	s_add_u32 s48, s48, 0x100
	s_addc_u32 s49, s49, 0
	s_cmp_gt_u32 s50, 41
	s_mov_b64 s[4:5], s[10:11]
	s_barrier
	s_cbranch_scc0 .LBB0_1544
	s_cmpk_gt_u32 s29, 0xff
	s_cbranch_scc1 .Lalign_down_a
	s_barrier
.Lalign_down_a:
	v_lshl_add_u32 v138, s47, 8, v161
	v_lshl_or_b32 v136, s46, 8, v173
	v_ashrrev_i32_e32 v139, 31, v138
	v_lshlrev_b64 v[140:141], 11, v[138:139]
	v_ashrrev_i32_e32 v137, 31, v136
	v_lshl_add_u64 v[140:141], s[16:17], 0, v[140:141]
	v_lshlrev_b64 v[142:143], 1, v[136:137]
	v_lshl_add_u64 v[166:167], v[140:141], 0, v[142:143]
	v_or_b32_e32 v140, 16, v138
	v_ashrrev_i32_e32 v141, 31, v140
	v_lshlrev_b64 v[144:145], 11, v[140:141]
	v_lshl_add_u64 v[144:145], s[16:17], 0, v[144:145]
	v_lshl_add_u64 v[148:149], v[144:145], 0, v[142:143]
	global_load_dwordx2 v[154:155], v[166:167], off
	global_load_dwordx2 v[164:165], v[166:167], off offset:32
	global_load_dwordx2 v[162:163], v[166:167], off offset:256
	global_load_dwordx2 v[152:153], v[166:167], off offset:288
	global_load_dwordx2 v[150:151], v[148:149], off
	global_load_dwordx2 v[146:147], v[148:149], off offset:32
	global_load_dwordx2 v[144:145], v[148:149], off offset:256
	global_load_dwordx2 v[142:143], v[148:149], off offset:288
	v_cndmask_b32_e64 v168, 0, 1, s[20:21]
	v_cmp_ne_u32_e64 s[10:11], 1, v168
	v_lshlrev_b64 v[168:169], 10, v[138:139]
	v_lshl_add_u64 v[168:169], v[168:169], 0, v[136:137]
	s_andn2_b64 vcc, exec, s[20:21]
	s_waitcnt vmcnt(0)
	v_cvt_f32_f16_e32 v176, v154
	v_cvt_f32_f16_e32 v178, v155
	v_cvt_f32_f16_sdwa v179, v155 dst_sel:DWORD dst_unused:UNUSED_PAD src0_sel:WORD_1
	v_cvt_f32_f16_sdwa v177, v154 dst_sel:DWORD dst_unused:UNUSED_PAD src0_sel:WORD_1
	v_lshl_add_u64 v[154:155], v[168:169], 2, s[14:15]
	v_pk_add_f32 v[128:129], v[128:129], v[178:179]
	v_pk_add_f32 v[126:127], v[126:127], v[176:177]
	s_cbranch_vccnz .LBB0_1657
	global_store_dwordx4 v[154:155], v[126:129], off
	s_cbranch_execnz .LBB0_1548
